# v8 + per-tile realign barrier of waves 4-7 deferred until after their next-tile index math and accumulator zeroing (they used to do that work after the barrier, while waves 0-3 were already in their f
# baseline (speedup 1.0000x reference)
; #define LAS __attribute__((address_space(3)))
; __global__ void __launch_bounds__(NTHREADS, 2) fwd_kernel(Args args) {
;     extern __shared__ __attribute__((aligned(16))) unsigned char lds[];
;     LAS unsigned char* L = (LAS unsigned char*)lds;
;     volatile LAS unsigned* MISC = (volatile LAS unsigned*)(L + MISC_OFF);
;     const int wave = __builtin_amdgcn_readfirstlane(threadIdx.x >> 6);
;     const int G = gridDim.x, bx = blockIdx.x;
;     ...
;     const int vcu = (G % 8 == 0) ? (bx % 8) * (G / 8) + bx / 8 : bx;
_Z10fwd_kernel4Args:
	s_mov_b32 s100, 0
	s_load_dword s33, s[0:1], 0xd0
	s_add_u32 s4, s0, 0xd0
	s_addc_u32 s5, s1, 0
	v_readfirstlane_b32 s6, v0
	v_writelane_b32 v255, s4, 0
	s_waitcnt lgkmcnt(0)
	s_and_b32 s3, s33, 7
	s_cmp_lg_u32 s3, 0
	v_writelane_b32 v255, s5, 1
	s_mov_b32 s91, s2
	s_cbranch_scc1 .LBB0_2
	s_ashr_i32 s4, s2, 31
	s_lshr_b32 s4, s4, 29
	s_add_i32 s4, s2, s4
	s_and_b32 s5, s4, -8
	s_ashr_i32 s3, s33, 3
	s_sub_i32 s5, s2, s5
	s_mul_i32 s3, s3, s5
	s_ashr_i32 s4, s4, 3
	s_add_i32 s91, s3, s4

; #define PG8_BAR __builtin_amdgcn_s_barrier()
;     __device__ __forceinline__ bool next(int i, Unit& u) const {
;         const bool hm = c < nmini, mini = hm && i == 0;
;         int j = i - (hm ? 1 : 0); j = j < 0 ? 0 : j;
;         const int ip = j >> pair;
;         const bool sk = skew > 0 && ip >= nfull;
;         const long L = sk ? (long)nfull * G + (long)(ip - nfull) * (G - skew) + (c - skew) : (long)ip * G + c; const bool ok = L < nwg && (!sk || c >= skew);
;         int wgid = ok ? (int)L : 0; { const int q = nwg / NXCD, r = nwg % NXCD, xcd = wgid % NXCD, off = wgid / NXCD; wgid = (xcd < r ? xcd * (q + 1) : r * (q + 1) + (xcd - r) * q) + off; }
;         const int nig = WGM * nN, gid = wgid / nig, fm = gid * WGM, gsz = (nM - fm) < WGM ? (nM - fm) : WGM;
;         const int fpm = fm + ((wgid % nig) % gsz), fpn = (wgid % nig) / gsz;
;         const int ns = nsplit > 0 ? nsplit : 1, t = c / ns, ks = c - t * ns, mpm = mini_pm0 + t / nN, mpn = t % nN;
;         u.pm = __builtin_amdgcn_readfirstlane(mini ? mpm : fpm); u.pn = __builtin_amdgcn_readfirstlane(mini ? mpn : fpn);
;         const int kh = mini_pair ? ns / 2 : ns, msub = mini_pair ? ks / kh : 0, mk = ks - msub * kh;
;         u.sub = __builtin_amdgcn_readfirstlane(mini ? msub : (j & ((1 << pair) - 1))); u.kt0 = __builtin_amdgcn_readfirstlane(mini ? mk * mini_nkt : 0); u.nkt = mini ? mini_nkt : nkt_full; u.part = mini ? 1 + ks : 0;
; template <class Epi, bool ALIGN_EPI = true, bool FP8 = false>
; __device__ __forceinline__ void gemm_phase(LAS unsigned char* lds, const Gemm g, const StaticOrder& S, const Epi& E, const int wid) {
;     ...
; #pragma unroll
;         for (int a = 0; a < 2; ++a)
; #pragma unroll
;             for (int b = 0; b < 2; ++b)
; #pragma unroll
;                 for (int m = 0; m < 4; ++m) {
;                     if (!keep) { acc[a][b][m][0] = (f32x4){0.f, 0.f, 0.f, 0.f}; acc[a][b][m][1] = (f32x4){0.f, 0.f, 0.f, 0.f}; }
;                     if constexpr (FP8) acc8[a][b][m] = __builtin_shufflevector(acc[a][b][m][0], acc[a][b][m][1], 0, 1, 2, 3, 4, 5, 6, 7); }
;         cur = nxt; cA = nA; cB = nB; ++ui;
;         if constexpr (ALIGN_EPI) { if (wr == 1) PG8_BAR; }
.LBB0_504:
	s_add_i32 s90, s90, 1
	s_add_i32 s3, s90, s49
	s_mul_i32 s6, s3, s50
	s_mul_hi_u32 s7, s3, s33
	s_add_i32 s7, s7, s6
	s_mul_i32 s3, s3, s33
	s_add_u32 s22, s3, s2
	s_addc_u32 s23, s7, s49
	v_cmp_lt_i64_e64 s[6:7], s[22:23], v[144:145]
	s_and_b64 s[24:25], s[6:7], exec
	s_cselect_b32 s3, s22, 0
	s_ashr_i32 s22, s3, 31
	s_lshr_b32 s22, s22, 29
	s_add_i32 s22, s3, s22
	s_ashr_i32 s23, s22, 3
	s_and_b32 s22, s22, -8
	s_sub_i32 s3, s3, s22
	s_cmp_lt_i32 s3, 0
	s_cselect_b32 s22, s85, 0x104
	s_mul_i32 s3, s3, s22
	s_add_i32 s3, s3, s23
	s_ashr_i32 s22, s3, 31
	s_lshr_b32 s22, s22, 26
	s_add_i32 s22, s3, s22
	s_ashr_i32 s23, s22, 6
	s_lshl_b32 s23, s23, 2
	s_sub_i32 s24, 0x82, s23
	s_min_i32 s24, s24, 4
	s_abs_i32 s25, s24
	v_cvt_f32_u32_e32 v0, s25
	s_sub_i32 s27, 0, s25
	s_andn2_b32 s22, s22, 63
	s_sub_i32 s3, s3, s22
	v_rcp_iflag_f32_e32 v0, v0
	s_abs_i32 s22, s3
	s_xor_b32 s26, s3, s24
	s_ashr_i32 s26, s26, 31
	v_mul_f32_e32 v0, 0x4f7ffffe, v0
	v_cvt_u32_f32_e32 v0, v0
	s_nop 0
	v_readfirstlane_b32 s28, v0
	s_mul_i32 s27, s27, s28
	s_mul_hi_u32 s27, s28, s27
	s_add_i32 s28, s28, s27
	s_mul_hi_u32 s27, s22, s28
	s_mul_i32 s28, s27, s25
	s_sub_i32 s22, s22, s28
	s_add_i32 s28, s27, 1
	s_sub_i32 s29, s22, s25
	s_cmp_ge_u32 s22, s25
	s_cselect_b32 s27, s28, s27
	s_cselect_b32 s22, s29, s22
	s_add_i32 s28, s27, 1
	s_cmp_ge_u32 s22, s25
	s_cselect_b32 s22, s28, s27
	s_xor_b32 s22, s22, s26
	s_sub_i32 s25, s22, s26
	s_mul_i32 s22, s25, s24
	s_sub_i32 s3, s3, s22
	s_add_i32 s22, s23, s3
	s_cmp_gt_i32 s25, 7
	s_cselect_b32 s3, 4, 0
	s_add_i32 s3, s25, s3
	s_ashr_i32 s23, s22, 31
	s_add_i32 s24, s3, 4
	s_lshl_b64 s[26:27], s[22:23], 20
	s_add_u32 s26, s56, s26
	s_addc_u32 s27, s57, s27
	s_ashr_i32 s25, s24, 31
	s_lshl_b64 s[28:29], s[24:25], 20
	s_add_u32 s28, s53, s28
	s_addc_u32 s29, s55, s29
	s_cmp_eq_u32 s9, 0
	s_cbranch_scc1 .LBB0_558
	s_and_b64 s[36:37], s[6:7], exec
	s_cselect_b32 s3, s27, s31
	s_cselect_b32 s23, s26, s30
	s_cselect_b32 s25, s29, s35
	s_cselect_b32 s38, s28, s34
	s_add_i32 s39, s9, -2
	s_add_u32 s30, s30, 0x80080
	s_addc_u32 s31, s31, 0
	s_add_u32 s42, s34, 0x100
	v_mov_b32_e32 v0, 0
	s_addc_u32 s43, s35, 0
	s_mov_b32 s34, 0
	v_mov_b32_e32 v1, v0
	v_mov_b32_e32 v2, v0
	v_mov_b32_e32 v3, v0
	v_mov_b32_e32 v4, v0
	v_mov_b32_e32 v5, v0
	v_mov_b32_e32 v6, v0
	v_mov_b32_e32 v7, v0
	v_mov_b32_e32 v16, v0
	v_mov_b32_e32 v17, v0
	v_mov_b32_e32 v18, v0
	v_mov_b32_e32 v19, v0
	v_mov_b32_e32 v20, v0
	v_mov_b32_e32 v21, v0
	v_mov_b32_e32 v22, v0
	v_mov_b32_e32 v23, v0
	v_mov_b32_e32 v32, v0
	s_waitcnt lgkmcnt(0)
	v_mov_b32_e32 v33, v0
	v_mov_b32_e32 v34, v0
	v_mov_b32_e32 v35, v0
	v_mov_b32_e32 v36, v0
	v_mov_b32_e32 v37, v0
	v_mov_b32_e32 v38, v0
	v_mov_b32_e32 v39, v0
	v_mov_b32_e32 v48, v0
	v_mov_b32_e32 v49, v0
	v_mov_b32_e32 v50, v0
	v_mov_b32_e32 v51, v0
	v_mov_b32_e32 v52, v0
	v_mov_b32_e32 v53, v0
	v_mov_b32_e32 v54, v0
	v_mov_b32_e32 v55, v0
	v_mov_b32_e32 v8, v0
	v_mov_b32_e32 v9, v0
	v_mov_b32_e32 v10, v0
	v_mov_b32_e32 v11, v0
	v_mov_b32_e32 v12, v0
	v_mov_b32_e32 v13, v0
	v_mov_b32_e32 v14, v0
	v_mov_b32_e32 v15, v0
	v_mov_b32_e32 v24, v0
	v_mov_b32_e32 v25, v0
	v_mov_b32_e32 v26, v0
	v_mov_b32_e32 v27, v0
	v_mov_b32_e32 v28, v0
	v_mov_b32_e32 v29, v0
	v_mov_b32_e32 v30, v0
	v_mov_b32_e32 v31, v0
	v_mov_b32_e32 v40, v0
	v_mov_b32_e32 v41, v0
	v_mov_b32_e32 v42, v0
	v_mov_b32_e32 v43, v0
	v_mov_b32_e32 v44, v0
	v_mov_b32_e32 v45, v0
	v_mov_b32_e32 v46, v0
	v_mov_b32_e32 v47, v0
	v_mov_b32_e32 v56, v0
	v_mov_b32_e32 v57, v0
	v_mov_b32_e32 v58, v0
	v_mov_b32_e32 v59, v0
	v_mov_b32_e32 v60, v0
	v_mov_b32_e32 v61, v0
	v_mov_b32_e32 v62, v0
	v_mov_b32_e32 v63, v0
	v_mov_b32_e32 v64, v0
	v_mov_b32_e32 v65, v0
	v_mov_b32_e32 v66, v0
	v_mov_b32_e32 v67, v0
	v_mov_b32_e32 v68, v0
	v_mov_b32_e32 v69, v0
	v_mov_b32_e32 v70, v0
	v_mov_b32_e32 v71, v0
	v_mov_b32_e32 v80, v0
	v_mov_b32_e32 v81, v0
	v_mov_b32_e32 v82, v0
	v_mov_b32_e32 v83, v0
	v_mov_b32_e32 v84, v0
	v_mov_b32_e32 v85, v0
	v_mov_b32_e32 v86, v0
	v_mov_b32_e32 v87, v0
	v_mov_b32_e32 v96, v0
	v_mov_b32_e32 v97, v0
	v_mov_b32_e32 v98, v0
	v_mov_b32_e32 v99, v0
	v_mov_b32_e32 v100, v0
	v_mov_b32_e32 v101, v0
	v_mov_b32_e32 v102, v0
	v_mov_b32_e32 v103, v0
	v_mov_b32_e32 v112, v0
	v_mov_b32_e32 v113, v0
	v_mov_b32_e32 v114, v0
	v_mov_b32_e32 v115, v0
	v_mov_b32_e32 v116, v0
	v_mov_b32_e32 v117, v0
	v_mov_b32_e32 v118, v0
	v_mov_b32_e32 v119, v0
	v_mov_b32_e32 v72, v0
	v_mov_b32_e32 v73, v0
	v_mov_b32_e32 v74, v0
	v_mov_b32_e32 v75, v0
	v_mov_b32_e32 v76, v0
	v_mov_b32_e32 v77, v0
	v_mov_b32_e32 v78, v0
	v_mov_b32_e32 v79, v0
	v_mov_b32_e32 v88, v0
	v_mov_b32_e32 v89, v0
	v_mov_b32_e32 v90, v0
	v_mov_b32_e32 v91, v0
	v_mov_b32_e32 v92, v0
	v_mov_b32_e32 v93, v0
	v_mov_b32_e32 v94, v0
	v_mov_b32_e32 v95, v0
	v_mov_b32_e32 v104, v0
	v_mov_b32_e32 v105, v0
	v_mov_b32_e32 v106, v0
	v_mov_b32_e32 v107, v0
	v_mov_b32_e32 v108, v0
	v_mov_b32_e32 v109, v0
	v_mov_b32_e32 v110, v0
	v_mov_b32_e32 v111, v0
	v_mov_b32_e32 v120, v0
	v_mov_b32_e32 v121, v0
	v_mov_b32_e32 v122, v0
	v_mov_b32_e32 v123, v0
	v_mov_b32_e32 v124, v0
	v_mov_b32_e32 v125, v0
	v_mov_b32_e32 v126, v0
	v_mov_b32_e32 v127, v0
	s_cmp_eq_u32 s100, 0
	s_cbranch_scc1 .Ldefbar_skip_1
	s_mov_b32 s100, 0
	s_barrier
; #define PG8_STAGE(bufoff, gbase, voff) do { _Pragma("unroll") for (int _i = 0; _i < 2; ++_i) \
;         __builtin_amdgcn_global_load_lds((const unsigned*)((const char*)(gbase) + (voff)[_i]), (LAS unsigned*)(lds + (bufoff) + ldsw + _i * 8192), 16, 0, 0); } while (0)
; #define PG8_LDA(dst, b, h) do { _Pragma("unroll") for (int m = 0; m < 4; ++m) _Pragma("unroll") for (int k = 0; k < 2; ++k) dst[m][k] = *(const LAS bf16x8*)(lds + PG8_SA(b, h) + aoff + m * 2048 + k * KOFF); } while (0)
; #define PG8_LDB(dst, b, h) do { _Pragma("unroll") for (int n = 0; n < 2; ++n) _Pragma("unroll") for (int k = 0; k < 2; ++k) dst[n][k] = *(const LAS bf16x8*)(lds + PG8_SB(b, h) + boff + n * 2048 + k * KOFF); } while (0)
; #define PG8_WAIT_V(n) asm volatile("s_waitcnt vmcnt(" #n ")" ::: "memory")
; #define PG8_WAIT_L(n) asm volatile("s_waitcnt lgkmcnt(" #n ")" ::: "memory")
; #define PG8_BAR __builtin_amdgcn_s_barrier()
; #define PG8_SCHED __builtin_amdgcn_sched_barrier(0)
; template <class Epi, bool ALIGN_EPI = true, bool FP8 = false>
; __device__ __forceinline__ void gemm_phase(LAS unsigned char* lds, const Gemm g, const StaticOrder& S, const Epi& E, const int wid) {
;     ...
;             const char* a1 = cA + (size_t)(t + 1) * kstep;
;             const char* a2 = last ? nA : cA + (size_t)(t + 2) * kstep; const char* b2 = last ? nB : cB + (size_t)(t + 2) * kstep;
;             const char* a3 = a2 + kstep; const char* b3 = b2 + kstep;
;             PG8_LDB(B0, 0, 0); PG8_LDB(B1, 0, 1); PG8_SCHED; PG8_LDA(At, 0, 0); PG8_STAGE(PG8_SA(1, 1), a1 + hstep, voffA);
;             PG8_WAIT_V(8); PG8_WAIT_L(0); PG8_BAR; PG8_MMA(0, 0, At, B0); PG8_MMA(0, 1, At, B1); PG8_BAR; PG8_SCHED;
;             PG8_LDA(At, 0, 1); PG8_STAGE(PG8_SB(0, 0), b2, voffB); PG8_STAGE(PG8_SB(0, 1), b2 + hstep, voffB); PG8_STAGE(PG8_SA(0, 0), a2, voffA);
;             PG8_WAIT_V(8); PG8_WAIT_L(0); PG8_BAR; PG8_MMA(1, 0, At, B0); PG8_MMA(1, 1, At, B1); PG8_BAR; PG8_SCHED;
.Ldefbar_skip_1:
.LBB0_506:
	ds_read_b128 v[146:149], v137
	ds_read_b128 v[154:157], v137 offset:1024
	ds_read_b128 v[158:161], v137 offset:2048
	ds_read_b128 v[162:165], v137 offset:3072
	ds_read_b128 v[166:169], v152
	ds_read_b128 v[170:173], v152 offset:1024
	ds_read_b128 v[174:177], v152 offset:2048
	ds_read_b128 v[178:181], v152 offset:3072
	s_add_i32 s52, s34, 2
	s_add_u32 s35, s30, 0xfff80080
	s_addc_u32 s36, s31, -1
	s_cmp_eq_u32 s39, s34
	s_cselect_b32 s34, s38, s42
	s_cselect_b32 s37, s3, s36
	s_cselect_b32 s36, s23, s35
	s_cselect_b32 s35, s25, s43
	v_lshl_add_u64 v[214:215], s[30:31], 0, v[140:141]
	s_add_i32 m0, s75, 0xc000
	ds_read_b128 v[182:185], v153
	ds_read_b128 v[186:189], v153 offset:1024
	ds_read_b128 v[190:193], v153 offset:2048
	ds_read_b128 v[194:197], v153 offset:3072
	ds_read_b128 v[198:201], v153 offset:4096
	ds_read_b128 v[202:205], v153 offset:5120
	ds_read_b128 v[206:209], v153 offset:6144
	ds_read_b128 v[210:213], v153 offset:7168
	global_load_lds_dwordx4 v[214:215], off
	v_lshl_add_u64 v[214:215], s[30:31], 0, v[142:143]
	s_add_i32 m0, s75, 0xe000
	s_nop 0
	global_load_lds_dwordx4 v[214:215], off
	s_setprio 1
	s_waitcnt vmcnt(8) lgkmcnt(0)
	s_barrier
	v_mfma_f32_16x16x32_bf16 v[124:127], v[146:149], v[182:185], v[124:127]
	v_mfma_f32_16x16x32_bf16 v[120:123], v[158:161], v[182:185], v[120:123]
	v_mfma_f32_16x16x32_bf16 v[108:111], v[146:149], v[190:193], v[108:111]
	v_mfma_f32_16x16x32_bf16 v[104:107], v[158:161], v[190:193], v[104:107]
	v_mfma_f32_16x16x32_bf16 v[92:95], v[146:149], v[198:201], v[92:95]
	v_mfma_f32_16x16x32_bf16 v[88:91], v[158:161], v[198:201], v[88:91]
	v_mfma_f32_16x16x32_bf16 v[76:79], v[146:149], v[206:209], v[76:79]
	v_mfma_f32_16x16x32_bf16 v[72:75], v[158:161], v[206:209], v[72:75]
	v_mfma_f32_16x16x32_bf16 v[124:127], v[154:157], v[186:189], v[124:127]
	v_mfma_f32_16x16x32_bf16 v[120:123], v[162:165], v[186:189], v[120:123]
	v_mfma_f32_16x16x32_bf16 v[108:111], v[154:157], v[194:197], v[108:111]
	v_mfma_f32_16x16x32_bf16 v[104:107], v[162:165], v[194:197], v[104:107]
	v_mfma_f32_16x16x32_bf16 v[92:95], v[154:157], v[202:205], v[92:95]
	v_mfma_f32_16x16x32_bf16 v[88:91], v[162:165], v[202:205], v[88:91]
	v_mfma_f32_16x16x32_bf16 v[76:79], v[154:157], v[210:213], v[76:79]
	v_mfma_f32_16x16x32_bf16 v[72:75], v[162:165], v[210:213], v[72:75]
	v_mfma_f32_16x16x32_bf16 v[116:119], v[166:169], v[182:185], v[116:119]
	v_mfma_f32_16x16x32_bf16 v[112:115], v[174:177], v[182:185], v[112:115]
	v_mfma_f32_16x16x32_bf16 v[100:103], v[166:169], v[190:193], v[100:103]
	v_mfma_f32_16x16x32_bf16 v[96:99], v[174:177], v[190:193], v[96:99]
	v_mfma_f32_16x16x32_bf16 v[84:87], v[166:169], v[198:201], v[84:87]
	v_mfma_f32_16x16x32_bf16 v[80:83], v[174:177], v[198:201], v[80:83]
	v_mfma_f32_16x16x32_bf16 v[68:71], v[166:169], v[206:209], v[68:71]
	v_mfma_f32_16x16x32_bf16 v[64:67], v[174:177], v[206:209], v[64:67]
	v_mfma_f32_16x16x32_bf16 v[116:119], v[170:173], v[186:189], v[116:119]
	v_mfma_f32_16x16x32_bf16 v[112:115], v[178:181], v[186:189], v[112:115]
	v_mfma_f32_16x16x32_bf16 v[100:103], v[170:173], v[194:197], v[100:103]
	v_mfma_f32_16x16x32_bf16 v[96:99], v[178:181], v[194:197], v[96:99]
	v_mfma_f32_16x16x32_bf16 v[84:87], v[170:173], v[202:205], v[84:87]
	v_mfma_f32_16x16x32_bf16 v[80:83], v[178:181], v[202:205], v[80:83]
	v_mfma_f32_16x16x32_bf16 v[68:71], v[170:173], v[210:213], v[68:71]
	v_mfma_f32_16x16x32_bf16 v[64:67], v[178:181], v[210:213], v[64:67]
	s_barrier
	s_setprio 0
	s_add_i32 s54, s86, s48
	v_lshl_add_u64 v[214:215], s[34:35], 0, v[132:133]
	s_mov_b32 m0, s54
	ds_read_b128 v[182:185], v153 offset:16384
	ds_read_b128 v[186:189], v153 offset:17408
	ds_read_b128 v[190:193], v153 offset:18432
	ds_read_b128 v[194:197], v153 offset:19456
	ds_read_b128 v[198:201], v153 offset:20480
	ds_read_b128 v[202:205], v153 offset:21504
	ds_read_b128 v[206:209], v153 offset:22528
	ds_read_b128 v[210:213], v153 offset:23552
	global_load_lds_dwordx4 v[214:215], off
	s_add_i32 m0, s54, 0x2000
	s_add_u32 s64, s34, 0x80000
	v_lshl_add_u64 v[216:217], s[34:35], 0, v[128:129]
	s_addc_u32 s65, s35, 0
	s_add_i32 s54, s87, s48
	global_load_lds_dwordx4 v[216:217], off
	v_lshl_add_u64 v[218:219], s[64:65], 0, v[132:133]
	s_mov_b32 m0, s54
	v_lshl_add_u64 v[220:221], s[36:37], 0, v[130:131]
	global_load_lds_dwordx4 v[218:219], off
	v_lshl_add_u64 v[218:219], s[64:65], 0, v[128:129]
	s_add_i32 m0, s54, 0x2000
	s_nop 0
	global_load_lds_dwordx4 v[218:219], off
	v_lshl_add_u64 v[218:219], s[36:37], 0, v[134:135]
	s_mov_b32 m0, s75
	s_nop 0
	global_load_lds_dwordx4 v[218:219], off
	s_mov_b32 m0, s76
	s_nop 0
	global_load_lds_dwordx4 v[220:221], off
	s_setprio 1
	s_waitcnt vmcnt(8) lgkmcnt(0)
	s_barrier
; #define PG8_STAGE(bufoff, gbase, voff) do { _Pragma("unroll") for (int _i = 0; _i < 2; ++_i) \
;         __builtin_amdgcn_global_load_lds((const unsigned*)((const char*)(gbase) + (voff)[_i]), (LAS unsigned*)(lds + (bufoff) + ldsw + _i * 8192), 16, 0, 0); } while (0)
; #define PG8_LDA(dst, b, h) do { _Pragma("unroll") for (int m = 0; m < 4; ++m) _Pragma("unroll") for (int k = 0; k < 2; ++k) dst[m][k] = *(const LAS bf16x8*)(lds + PG8_SA(b, h) + aoff + m * 2048 + k * KOFF); } while (0)
; #define PG8_LDB(dst, b, h) do { _Pragma("unroll") for (int n = 0; n < 2; ++n) _Pragma("unroll") for (int k = 0; k < 2; ++k) dst[n][k] = *(const LAS bf16x8*)(lds + PG8_SB(b, h) + boff + n * 2048 + k * KOFF); } while (0)
; #define PG8_WAIT_V(n) asm volatile("s_waitcnt vmcnt(" #n ")" ::: "memory")
; #define PG8_WAIT_L(n) asm volatile("s_waitcnt lgkmcnt(" #n ")" ::: "memory")
; #define PG8_BAR __builtin_amdgcn_s_barrier()
; #define PG8_SCHED __builtin_amdgcn_sched_barrier(0)
; template <class Epi, bool ALIGN_EPI = true, bool FP8 = false>
; __device__ __forceinline__ void gemm_phase(LAS unsigned char* lds, const Gemm g, const StaticOrder& S, const Epi& E, const int wid) {
;     ...
;             PG8_WAIT_V(8); PG8_WAIT_L(0); PG8_BAR; PG8_MMA(1, 0, At, B0); PG8_MMA(1, 1, At, B1); PG8_BAR; PG8_SCHED;
;             PG8_LDB(B0, 1, 0); PG8_LDB(B1, 1, 1); PG8_SCHED; PG8_LDA(At, 1, 0); PG8_STAGE(PG8_SA(0, 1), a2 + hstep, voffA);
;             PG8_WAIT_V(8); PG8_WAIT_L(0); PG8_BAR; PG8_MMA(0, 0, At, B0); PG8_MMA(0, 1, At, B1); PG8_BAR; PG8_SCHED;
	v_mfma_f32_16x16x32_bf16 v[60:63], v[146:149], v[182:185], v[60:63]
	v_mfma_f32_16x16x32_bf16 v[56:59], v[158:161], v[182:185], v[56:59]
	v_mfma_f32_16x16x32_bf16 v[44:47], v[146:149], v[190:193], v[44:47]
	v_mfma_f32_16x16x32_bf16 v[40:43], v[158:161], v[190:193], v[40:43]
	v_mfma_f32_16x16x32_bf16 v[28:31], v[146:149], v[198:201], v[28:31]
	v_mfma_f32_16x16x32_bf16 v[24:27], v[158:161], v[198:201], v[24:27]
	v_mfma_f32_16x16x32_bf16 v[12:15], v[146:149], v[206:209], v[12:15]
	v_mfma_f32_16x16x32_bf16 v[8:11], v[158:161], v[206:209], v[8:11]
	v_mfma_f32_16x16x32_bf16 v[60:63], v[154:157], v[186:189], v[60:63]
	v_mfma_f32_16x16x32_bf16 v[56:59], v[162:165], v[186:189], v[56:59]
	v_mfma_f32_16x16x32_bf16 v[44:47], v[154:157], v[194:197], v[44:47]
	v_mfma_f32_16x16x32_bf16 v[40:43], v[162:165], v[194:197], v[40:43]
	v_mfma_f32_16x16x32_bf16 v[28:31], v[154:157], v[202:205], v[28:31]
	v_mfma_f32_16x16x32_bf16 v[24:27], v[162:165], v[202:205], v[24:27]
	v_mfma_f32_16x16x32_bf16 v[12:15], v[154:157], v[210:213], v[12:15]
	v_mfma_f32_16x16x32_bf16 v[8:11], v[162:165], v[210:213], v[8:11]
	v_mfma_f32_16x16x32_bf16 v[52:55], v[166:169], v[182:185], v[52:55]
	v_mfma_f32_16x16x32_bf16 v[48:51], v[174:177], v[182:185], v[48:51]
	v_mfma_f32_16x16x32_bf16 v[36:39], v[166:169], v[190:193], v[36:39]
	v_mfma_f32_16x16x32_bf16 v[32:35], v[174:177], v[190:193], v[32:35]
	v_mfma_f32_16x16x32_bf16 v[20:23], v[166:169], v[198:201], v[20:23]
	v_mfma_f32_16x16x32_bf16 v[16:19], v[174:177], v[198:201], v[16:19]
	v_mfma_f32_16x16x32_bf16 v[4:7], v[166:169], v[206:209], v[4:7]
	v_mfma_f32_16x16x32_bf16 v[0:3], v[174:177], v[206:209], v[0:3]
	v_mfma_f32_16x16x32_bf16 v[52:55], v[170:173], v[186:189], v[52:55]
	v_mfma_f32_16x16x32_bf16 v[48:51], v[178:181], v[186:189], v[48:51]
	v_mfma_f32_16x16x32_bf16 v[36:39], v[170:173], v[194:197], v[36:39]
	v_mfma_f32_16x16x32_bf16 v[32:35], v[178:181], v[194:197], v[32:35]
	v_mfma_f32_16x16x32_bf16 v[20:23], v[170:173], v[202:205], v[20:23]
	v_mfma_f32_16x16x32_bf16 v[16:19], v[178:181], v[202:205], v[16:19]
	v_mfma_f32_16x16x32_bf16 v[4:7], v[170:173], v[210:213], v[4:7]
	v_mfma_f32_16x16x32_bf16 v[0:3], v[178:181], v[210:213], v[0:3]
	s_barrier
	s_setprio 0
	s_add_i32 s54, 0, 0x18000
	s_add_i32 s64, 0, 0x1c000
	v_add_u32_e32 v162, s54, v150
	v_add_u32_e32 v178, s64, v150
	ds_read_b128 v[146:149], v162
	ds_read_b128 v[154:157], v162 offset:1024
	ds_read_b128 v[158:161], v162 offset:2048
	ds_read_b128 v[162:165], v162 offset:3072
	ds_read_b128 v[166:169], v178
	ds_read_b128 v[170:173], v178 offset:1024
	ds_read_b128 v[174:177], v178 offset:2048
	ds_read_b128 v[178:181], v178 offset:3072
	s_add_u32 s36, s36, 0x80000
	s_addc_u32 s37, s37, 0
	s_mov_b32 m0, s77
	v_lshl_add_u64 v[222:223], s[36:37], 0, v[134:135]
	ds_read_b128 v[182:185], v153 offset:32768
	ds_read_b128 v[186:189], v153 offset:33792
	ds_read_b128 v[190:193], v153 offset:34816
	ds_read_b128 v[194:197], v153 offset:35840
	ds_read_b128 v[198:201], v153 offset:36864
	ds_read_b128 v[202:205], v153 offset:37888
	ds_read_b128 v[206:209], v153 offset:38912
	ds_read_b128 v[210:213], v153 offset:39936
	global_load_lds_dwordx4 v[222:223], off
	v_lshl_add_u64 v[222:223], s[36:37], 0, v[130:131]
	s_mov_b32 m0, s78
	s_nop 0
	global_load_lds_dwordx4 v[222:223], off
	s_setprio 1
	s_waitcnt vmcnt(8) lgkmcnt(0)
	s_barrier
	v_mfma_f32_16x16x32_bf16 v[124:127], v[146:149], v[182:185], v[124:127]
	v_mfma_f32_16x16x32_bf16 v[120:123], v[158:161], v[182:185], v[120:123]
	v_mfma_f32_16x16x32_bf16 v[108:111], v[146:149], v[190:193], v[108:111]
	v_mfma_f32_16x16x32_bf16 v[104:107], v[158:161], v[190:193], v[104:107]
	v_mfma_f32_16x16x32_bf16 v[92:95], v[146:149], v[198:201], v[92:95]
	v_mfma_f32_16x16x32_bf16 v[88:91], v[158:161], v[198:201], v[88:91]
	v_mfma_f32_16x16x32_bf16 v[76:79], v[146:149], v[206:209], v[76:79]
	v_mfma_f32_16x16x32_bf16 v[72:75], v[158:161], v[206:209], v[72:75]
	v_mfma_f32_16x16x32_bf16 v[124:127], v[154:157], v[186:189], v[124:127]
	v_mfma_f32_16x16x32_bf16 v[120:123], v[162:165], v[186:189], v[120:123]
	v_mfma_f32_16x16x32_bf16 v[108:111], v[154:157], v[194:197], v[108:111]
	v_mfma_f32_16x16x32_bf16 v[104:107], v[162:165], v[194:197], v[104:107]
	v_mfma_f32_16x16x32_bf16 v[92:95], v[154:157], v[202:205], v[92:95]
	v_mfma_f32_16x16x32_bf16 v[88:91], v[162:165], v[202:205], v[88:91]
	v_mfma_f32_16x16x32_bf16 v[76:79], v[154:157], v[210:213], v[76:79]
	v_mfma_f32_16x16x32_bf16 v[72:75], v[162:165], v[210:213], v[72:75]
	v_mfma_f32_16x16x32_bf16 v[116:119], v[166:169], v[182:185], v[116:119]
	v_mfma_f32_16x16x32_bf16 v[112:115], v[174:177], v[182:185], v[112:115]
	v_mfma_f32_16x16x32_bf16 v[100:103], v[166:169], v[190:193], v[100:103]
	v_mfma_f32_16x16x32_bf16 v[96:99], v[174:177], v[190:193], v[96:99]
	v_mfma_f32_16x16x32_bf16 v[84:87], v[166:169], v[198:201], v[84:87]
	v_mfma_f32_16x16x32_bf16 v[80:83], v[174:177], v[198:201], v[80:83]
	v_mfma_f32_16x16x32_bf16 v[68:71], v[166:169], v[206:209], v[68:71]
	v_mfma_f32_16x16x32_bf16 v[64:67], v[174:177], v[206:209], v[64:67]
	v_mfma_f32_16x16x32_bf16 v[116:119], v[170:173], v[186:189], v[116:119]
	v_mfma_f32_16x16x32_bf16 v[112:115], v[178:181], v[186:189], v[112:115]
	v_mfma_f32_16x16x32_bf16 v[100:103], v[170:173], v[194:197], v[100:103]
	v_mfma_f32_16x16x32_bf16 v[96:99], v[178:181], v[194:197], v[96:99]
	v_mfma_f32_16x16x32_bf16 v[84:87], v[170:173], v[202:205], v[84:87]
	v_mfma_f32_16x16x32_bf16 v[80:83], v[178:181], v[202:205], v[80:83]
	v_mfma_f32_16x16x32_bf16 v[68:71], v[170:173], v[210:213], v[68:71]
	v_mfma_f32_16x16x32_bf16 v[64:67], v[178:181], v[210:213], v[64:67]
	s_barrier
; #define PG8_STAGE(bufoff, gbase, voff) do { _Pragma("unroll") for (int _i = 0; _i < 2; ++_i) \
;         __builtin_amdgcn_global_load_lds((const unsigned*)((const char*)(gbase) + (voff)[_i]), (LAS unsigned*)(lds + (bufoff) + ldsw + _i * 8192), 16, 0, 0); } while (0)
; #define PG8_LDA(dst, b, h) do { _Pragma("unroll") for (int m = 0; m < 4; ++m) _Pragma("unroll") for (int k = 0; k < 2; ++k) dst[m][k] = *(const LAS bf16x8*)(lds + PG8_SA(b, h) + aoff + m * 2048 + k * KOFF); } while (0)
; #define PG8_WAIT_V(n) asm volatile("s_waitcnt vmcnt(" #n ")" ::: "memory")
; #define PG8_WAIT_L(n) asm volatile("s_waitcnt lgkmcnt(" #n ")" ::: "memory")
; #define PG8_BAR __builtin_amdgcn_s_barrier()
; #define PG8_SCHED __builtin_amdgcn_sched_barrier(0)
; template <class Epi, bool ALIGN_EPI = true, bool FP8 = false>
; __device__ __forceinline__ void gemm_phase(LAS unsigned char* lds, const Gemm g, const StaticOrder& S, const Epi& E, const int wid) {
;     ...
;             PG8_LDA(At, 1, 1); PG8_STAGE(PG8_SB(1, 0), b3, voffB); PG8_STAGE(PG8_SB(1, 1), b3 + hstep, voffB); PG8_STAGE(PG8_SA(1, 0), a3, voffA);
;             PG8_WAIT_V(8); PG8_WAIT_L(0); PG8_BAR; PG8_MMA(1, 0, At, B0); PG8_MMA(1, 1, At, B1); PG8_BAR; PG8_SCHED;
;         }
	s_setprio 0
	s_add_i32 s36, s54, s48
	v_lshl_add_u64 v[214:215], v[214:215], 0, s[16:17]
	s_mov_b32 m0, s36
	ds_read_b128 v[182:185], v153 offset:49152
	ds_read_b128 v[186:189], v153 offset:50176
	ds_read_b128 v[190:193], v153 offset:51200
	ds_read_b128 v[194:197], v153 offset:52224
	ds_read_b128 v[198:201], v153 offset:53248
	ds_read_b128 v[202:205], v153 offset:54272
	ds_read_b128 v[206:209], v153 offset:55296
	ds_read_b128 v[210:213], v153 offset:56320
	global_load_lds_dwordx4 v[214:215], off
	s_add_i32 m0, s36, 0x2000
	s_add_u32 s34, s34, 0x80080
	v_lshl_add_u64 v[214:215], v[216:217], 0, s[16:17]
	s_addc_u32 s35, s35, 0
	s_add_i32 s36, s64, s48
	global_load_lds_dwordx4 v[214:215], off
	v_lshl_add_u64 v[214:215], s[34:35], 0, v[132:133]
	s_mov_b32 m0, s36
	s_nop 0
	global_load_lds_dwordx4 v[214:215], off
	v_lshl_add_u64 v[214:215], s[34:35], 0, v[128:129]
	s_add_i32 m0, s36, 0x2000
	s_nop 0
	global_load_lds_dwordx4 v[214:215], off
	v_lshl_add_u64 v[214:215], v[218:219], 0, s[16:17]
	s_mov_b32 m0, s83
	s_nop 0
	global_load_lds_dwordx4 v[214:215], off
	v_lshl_add_u64 v[214:215], v[220:221], 0, s[16:17]
	s_mov_b32 m0, s84
	s_nop 0
	global_load_lds_dwordx4 v[214:215], off
	s_setprio 1
	s_waitcnt vmcnt(8) lgkmcnt(0)
	s_barrier
	v_mfma_f32_16x16x32_bf16 v[60:63], v[146:149], v[182:185], v[60:63]
	v_mfma_f32_16x16x32_bf16 v[56:59], v[158:161], v[182:185], v[56:59]
	v_mfma_f32_16x16x32_bf16 v[44:47], v[146:149], v[190:193], v[44:47]
	v_mfma_f32_16x16x32_bf16 v[40:43], v[158:161], v[190:193], v[40:43]
	v_mfma_f32_16x16x32_bf16 v[28:31], v[146:149], v[198:201], v[28:31]
	v_mfma_f32_16x16x32_bf16 v[24:27], v[158:161], v[198:201], v[24:27]
	v_mfma_f32_16x16x32_bf16 v[12:15], v[146:149], v[206:209], v[12:15]
	v_mfma_f32_16x16x32_bf16 v[8:11], v[158:161], v[206:209], v[8:11]
	v_mfma_f32_16x16x32_bf16 v[60:63], v[154:157], v[186:189], v[60:63]
	v_mfma_f32_16x16x32_bf16 v[56:59], v[162:165], v[186:189], v[56:59]
	v_mfma_f32_16x16x32_bf16 v[44:47], v[154:157], v[194:197], v[44:47]
	v_mfma_f32_16x16x32_bf16 v[40:43], v[162:165], v[194:197], v[40:43]
	v_mfma_f32_16x16x32_bf16 v[28:31], v[154:157], v[202:205], v[28:31]
	v_mfma_f32_16x16x32_bf16 v[24:27], v[162:165], v[202:205], v[24:27]
	v_mfma_f32_16x16x32_bf16 v[12:15], v[154:157], v[210:213], v[12:15]
	v_mfma_f32_16x16x32_bf16 v[8:11], v[162:165], v[210:213], v[8:11]
	v_mfma_f32_16x16x32_bf16 v[52:55], v[166:169], v[182:185], v[52:55]
	v_mfma_f32_16x16x32_bf16 v[48:51], v[174:177], v[182:185], v[48:51]
	v_mfma_f32_16x16x32_bf16 v[36:39], v[166:169], v[190:193], v[36:39]
	v_mfma_f32_16x16x32_bf16 v[32:35], v[174:177], v[190:193], v[32:35]
	v_mfma_f32_16x16x32_bf16 v[20:23], v[166:169], v[198:201], v[20:23]
	v_mfma_f32_16x16x32_bf16 v[16:19], v[174:177], v[198:201], v[16:19]
	v_mfma_f32_16x16x32_bf16 v[4:7], v[166:169], v[206:209], v[4:7]
	v_mfma_f32_16x16x32_bf16 v[0:3], v[174:177], v[206:209], v[0:3]
	v_mfma_f32_16x16x32_bf16 v[52:55], v[170:173], v[186:189], v[52:55]
	v_mfma_f32_16x16x32_bf16 v[48:51], v[178:181], v[186:189], v[48:51]
	v_mfma_f32_16x16x32_bf16 v[36:39], v[170:173], v[194:197], v[36:39]
	v_mfma_f32_16x16x32_bf16 v[32:35], v[178:181], v[194:197], v[32:35]
	v_mfma_f32_16x16x32_bf16 v[20:23], v[170:173], v[202:205], v[20:23]
	v_mfma_f32_16x16x32_bf16 v[16:19], v[178:181], v[202:205], v[16:19]
	v_mfma_f32_16x16x32_bf16 v[4:7], v[170:173], v[210:213], v[4:7]
	v_mfma_f32_16x16x32_bf16 v[0:3], v[178:181], v[210:213], v[0:3]
	s_barrier
	s_setprio 0
	s_add_u32 s30, s30, 0x100
	s_addc_u32 s31, s31, 0
	s_add_u32 s42, s42, 0x100
	s_addc_u32 s43, s43, 0
	s_cmp_ge_u32 s52, s9
	s_mov_b32 s34, s52
	s_cbranch_scc0 .LBB0_506
	s_and_b64 vcc, exec, s[12:13]
	s_cbranch_vccz .LBB0_509

; #define PG8_BAR __builtin_amdgcn_s_barrier()
; template <class Epi, bool ALIGN_EPI = true, bool FP8 = false>
; __device__ __forceinline__ void gemm_phase(LAS unsigned char* lds, const Gemm g, const StaticOrder& S, const Epi& E, const int wid) {
;     ...
;         if (!has_next) break;
; #pragma unroll
;         for (int a = 0; a < 2; ++a)
; #pragma unroll
;             for (int b = 0; b < 2; ++b)
; #pragma unroll
;                 for (int m = 0; m < 4; ++m) {
;                     if (!keep) { acc[a][b][m][0] = (f32x4){0.f, 0.f, 0.f, 0.f}; acc[a][b][m][1] = (f32x4){0.f, 0.f, 0.f, 0.f}; }
;                     if constexpr (FP8) acc8[a][b][m] = __builtin_shufflevector(acc[a][b][m][0], acc[a][b][m][1], 0, 1, 2, 3, 4, 5, 6, 7); }
;         cur = nxt; cA = nA; cB = nB; ++ui;
;         if constexpr (ALIGN_EPI) { if (wr == 1) PG8_BAR; }
.LBB0_555:
	s_or_b64 exec, exec, s[30:31]
	s_andn2_b64 vcc, exec, s[6:7]
	s_mov_b64 s[6:7], -1
	s_cbranch_vccnz .LBB0_503
	s_and_b64 vcc, exec, s[4:5]
	s_cbranch_vccnz .LBB0_502
	s_mov_b32 s100, 1
	s_branch .LBB0_502
.LBB0_558:
	s_cmp_eq_u32 s100, 0
	s_cbranch_scc1 .Ldefbar_skip_2
	s_mov_b32 s100, 0
	s_barrier

; #define PG8_BAR __builtin_amdgcn_s_barrier()
;     __device__ __forceinline__ bool next(int i, Unit& u) const {
;         const bool hm = c < nmini, mini = hm && i == 0;
;         int j = i - (hm ? 1 : 0); j = j < 0 ? 0 : j;
;         const int ip = j >> pair;
;         const bool sk = skew > 0 && ip >= nfull;
;         const long L = sk ? (long)nfull * G + (long)(ip - nfull) * (G - skew) + (c - skew) : (long)ip * G + c; const bool ok = L < nwg && (!sk || c >= skew);
;         int wgid = ok ? (int)L : 0; { const int q = nwg / NXCD, r = nwg % NXCD, xcd = wgid % NXCD, off = wgid / NXCD; wgid = (xcd < r ? xcd * (q + 1) : r * (q + 1) + (xcd - r) * q) + off; }
;         const int nig = WGM * nN, gid = wgid / nig, fm = gid * WGM, gsz = (nM - fm) < WGM ? (nM - fm) : WGM;
;         const int fpm = fm + ((wgid % nig) % gsz), fpn = (wgid % nig) / gsz;
;         const int ns = nsplit > 0 ? nsplit : 1, t = c / ns, ks = c - t * ns, mpm = mini_pm0 + t / nN, mpn = t % nN;
;         u.pm = __builtin_amdgcn_readfirstlane(mini ? mpm : fpm); u.pn = __builtin_amdgcn_readfirstlane(mini ? mpn : fpn);
;         const int kh = mini_pair ? ns / 2 : ns, msub = mini_pair ? ks / kh : 0, mk = ks - msub * kh;
;         u.sub = __builtin_amdgcn_readfirstlane(mini ? msub : (j & ((1 << pair) - 1))); u.kt0 = __builtin_amdgcn_readfirstlane(mini ? mk * mini_nkt : 0); u.nkt = mini ? mini_nkt : nkt_full; u.part = mini ? 1 + ks : 0;
; template <class Epi, bool ALIGN_EPI = true, bool FP8 = false>
; __device__ __forceinline__ void gemm_phase(LAS unsigned char* lds, const Gemm g, const StaticOrder& S, const Epi& E, const int wid) {
;     ...
; #pragma unroll
;         for (int a = 0; a < 2; ++a)
; #pragma unroll
;             for (int b = 0; b < 2; ++b)
; #pragma unroll
;                 for (int m = 0; m < 4; ++m) {
;                     if (!keep) { acc[a][b][m][0] = (f32x4){0.f, 0.f, 0.f, 0.f}; acc[a][b][m][1] = (f32x4){0.f, 0.f, 0.f, 0.f}; }
;                     if constexpr (FP8) acc8[a][b][m] = __builtin_shufflevector(acc[a][b][m][0], acc[a][b][m][1], 0, 1, 2, 3, 4, 5, 6, 7); }
;         cur = nxt; cA = nA; cB = nB; ++ui;
;         if constexpr (ALIGN_EPI) { if (wr == 1) PG8_BAR; }
.LBB0_570:
	v_cmp_gt_i64_e32 vcc, s[20:21], v[176:177]
	s_or_b64 s[16:17], s[16:17], vcc
	v_cmp_lt_i64_e32 vcc, s[20:21], v[174:175]
	s_and_b64 s[16:17], s[16:17], exec
	v_readfirstlane_b32 s16, v189
	v_cndmask_b32_e64 v0, 0, 1, vcc
	s_nop 0
	v_readfirstlane_b32 s3, v0
	s_cselect_b32 s3, s3, s16
	s_bitcmp1_b32 s3, 0
	s_cselect_b64 s[16:17], -1, 0
	s_and_b64 s[22:23], s[16:17], exec
	s_cselect_b32 s3, s20, 0
	s_ashr_i32 s20, s3, 31
	s_lshr_b32 s20, s20, 29
	s_add_i32 s20, s3, s20
	s_ashr_i32 s21, s20, 3
	s_and_b32 s20, s20, -8
	s_sub_i32 s3, s3, s20
	s_cmp_lt_i32 s3, 0
	s_cselect_b32 s20, s74, 0x186
	s_mul_i32 s3, s3, s20
	s_add_i32 s3, s3, s21
	s_mul_hi_i32 s20, s3, 0x2aaaaaab
	s_lshr_b32 s21, s20, 31
	s_ashr_i32 s20, s20, 4
	s_add_i32 s20, s20, s21
	s_lshl_b32 s21, s20, 2
	s_sub_i32 s22, 0x82, s21
	s_min_i32 s22, s22, 4
	s_abs_i32 s23, s22
	v_cvt_f32_u32_e32 v0, s23
	s_sub_i32 s25, 0, s23
	s_mulk_i32 s20, 0x60
	s_sub_i32 s3, s3, s20
	v_rcp_iflag_f32_e32 v0, v0
	s_abs_i32 s24, s3
	s_xor_b32 s20, s3, s22
	s_ashr_i32 s20, s20, 31
	v_mul_f32_e32 v0, 0x4f7ffffe, v0
	v_cvt_u32_f32_e32 v0, v0
	s_nop 0
	v_readfirstlane_b32 s28, v0
	s_mul_i32 s25, s25, s28
	s_mul_hi_u32 s25, s28, s25
	s_add_i32 s28, s28, s25
	s_mul_hi_u32 s25, s24, s28
	s_mul_i32 s28, s25, s23
	s_sub_i32 s24, s24, s28
	s_add_i32 s28, s25, 1
	s_sub_i32 s29, s24, s23
	s_cmp_ge_u32 s24, s23
	s_cselect_b32 s25, s28, s25
	s_cselect_b32 s24, s29, s24
	s_add_i32 s28, s25, 1
	s_cmp_ge_u32 s24, s23
	s_cselect_b32 s23, s28, s25
	s_xor_b32 s23, s23, s20
	s_sub_i32 s23, s23, s20
	s_mul_i32 s20, s23, s22
	s_sub_i32 s3, s3, s20
	s_add_i32 s20, s21, s3
	s_cmp_gt_i32 s23, 3
	s_cselect_b32 s3, 8, 0
	s_add_i32 s3, s3, s23
	s_cmp_lt_i32 s23, 8
	s_cselect_b32 s21, 0, 8
	s_add_i32 s22, s3, s21
	s_ashr_i32 s21, s20, 31
	s_lshl_b64 s[24:25], s[20:21], 19
	s_add_u32 s24, s38, s24
	s_addc_u32 s25, s39, s25
	s_ashr_i32 s23, s22, 31
	s_lshl_b64 s[28:29], s[22:23], 19
	s_add_u32 s28, s51, s28
	s_addc_u32 s29, s53, s29
	s_cmp_eq_u32 s83, 0
	s_cbranch_scc1 .LBB0_582
	s_and_b64 s[36:37], s[16:17], exec
	s_cselect_b32 s21, s25, s31
	s_cselect_b32 s23, s24, s30
	s_cselect_b32 s84, s29, s35
	s_cselect_b32 s85, s28, s34
	s_add_i32 s86, s83, -2
	s_add_u32 s30, s30, 0x40080
	s_addc_u32 s31, s31, 0
	s_add_u32 s87, s34, 0x100
	v_mov_b32_e32 v0, 0
	s_addc_u32 s88, s35, 0
	s_mov_b32 s34, 0
	v_mov_b32_e32 v1, v0
	v_mov_b32_e32 v2, v0
	v_mov_b32_e32 v3, v0
	v_mov_b32_e32 v4, v0
	v_mov_b32_e32 v5, v0
	v_mov_b32_e32 v6, v0
	v_mov_b32_e32 v7, v0
	v_mov_b32_e32 v8, v0
	v_mov_b32_e32 v9, v0
	v_mov_b32_e32 v10, v0
	v_mov_b32_e32 v11, v0
	v_mov_b32_e32 v12, v0
	v_mov_b32_e32 v13, v0
	v_mov_b32_e32 v14, v0
	v_mov_b32_e32 v15, v0
	v_mov_b32_e32 v16, v0
	v_mov_b32_e32 v17, v0
	v_mov_b32_e32 v18, v0
	v_mov_b32_e32 v19, v0
	v_mov_b32_e32 v20, v0
	v_mov_b32_e32 v21, v0
	v_mov_b32_e32 v22, v0
	v_mov_b32_e32 v23, v0
	v_mov_b32_e32 v32, v0
	s_waitcnt lgkmcnt(0)
	v_mov_b32_e32 v33, v0
	v_mov_b32_e32 v34, v0
	v_mov_b32_e32 v35, v0
	v_mov_b32_e32 v36, v0
	v_mov_b32_e32 v37, v0
	v_mov_b32_e32 v38, v0
	v_mov_b32_e32 v39, v0
	v_mov_b32_e32 v24, v0
	v_mov_b32_e32 v25, v0
	v_mov_b32_e32 v26, v0
	v_mov_b32_e32 v27, v0
	v_mov_b32_e32 v28, v0
	v_mov_b32_e32 v29, v0
	v_mov_b32_e32 v30, v0
	v_mov_b32_e32 v31, v0
	v_mov_b32_e32 v40, v0
	v_mov_b32_e32 v41, v0
	v_mov_b32_e32 v42, v0
	v_mov_b32_e32 v43, v0
	v_mov_b32_e32 v44, v0
	v_mov_b32_e32 v45, v0
	v_mov_b32_e32 v46, v0
	v_mov_b32_e32 v47, v0
	v_mov_b32_e32 v48, v0
	v_mov_b32_e32 v49, v0
	v_mov_b32_e32 v50, v0
	v_mov_b32_e32 v51, v0
	v_mov_b32_e32 v52, v0
	v_mov_b32_e32 v53, v0
	v_mov_b32_e32 v54, v0
	v_mov_b32_e32 v55, v0
	v_mov_b32_e32 v56, v0
	v_mov_b32_e32 v57, v0
	v_mov_b32_e32 v58, v0
	v_mov_b32_e32 v59, v0
	v_mov_b32_e32 v60, v0
	v_mov_b32_e32 v61, v0
	v_mov_b32_e32 v62, v0
	v_mov_b32_e32 v63, v0
	v_mov_b32_e32 v64, v0
	v_mov_b32_e32 v65, v0
	v_mov_b32_e32 v66, v0
	v_mov_b32_e32 v67, v0
	v_mov_b32_e32 v68, v0
	v_mov_b32_e32 v69, v0
	v_mov_b32_e32 v70, v0
	v_mov_b32_e32 v71, v0
	v_mov_b32_e32 v72, v0
	v_mov_b32_e32 v73, v0
	v_mov_b32_e32 v74, v0
	v_mov_b32_e32 v75, v0
	v_mov_b32_e32 v76, v0
	v_mov_b32_e32 v77, v0
	v_mov_b32_e32 v78, v0
	v_mov_b32_e32 v79, v0
	v_mov_b32_e32 v80, v0
	v_mov_b32_e32 v81, v0
	v_mov_b32_e32 v82, v0
	v_mov_b32_e32 v83, v0
	v_mov_b32_e32 v84, v0
	v_mov_b32_e32 v85, v0
	v_mov_b32_e32 v86, v0
	v_mov_b32_e32 v87, v0
	v_mov_b32_e32 v96, v0
	v_mov_b32_e32 v97, v0
	v_mov_b32_e32 v98, v0
	v_mov_b32_e32 v99, v0
	v_mov_b32_e32 v100, v0
	v_mov_b32_e32 v101, v0
	v_mov_b32_e32 v102, v0
	v_mov_b32_e32 v103, v0
	v_mov_b32_e32 v88, v0
	v_mov_b32_e32 v89, v0
	v_mov_b32_e32 v90, v0
	v_mov_b32_e32 v91, v0
	v_mov_b32_e32 v92, v0
	v_mov_b32_e32 v93, v0
	v_mov_b32_e32 v94, v0
	v_mov_b32_e32 v95, v0
	v_mov_b32_e32 v104, v0
	v_mov_b32_e32 v105, v0
	v_mov_b32_e32 v106, v0
	v_mov_b32_e32 v107, v0
	v_mov_b32_e32 v108, v0
	v_mov_b32_e32 v109, v0
	v_mov_b32_e32 v110, v0
	v_mov_b32_e32 v111, v0
	v_mov_b32_e32 v112, v0
	v_mov_b32_e32 v113, v0
	v_mov_b32_e32 v114, v0
	v_mov_b32_e32 v115, v0
	v_mov_b32_e32 v116, v0
	v_mov_b32_e32 v117, v0
	v_mov_b32_e32 v118, v0
	v_mov_b32_e32 v119, v0
	v_mov_b32_e32 v120, v0
	v_mov_b32_e32 v121, v0
	v_mov_b32_e32 v122, v0
	v_mov_b32_e32 v123, v0
	v_mov_b32_e32 v124, v0
	v_mov_b32_e32 v125, v0
	v_mov_b32_e32 v126, v0
	v_mov_b32_e32 v127, v0
	s_cmp_eq_u32 s100, 0
	s_cbranch_scc1 .Ldefbar_skip_3
	s_mov_b32 s100, 0
	s_barrier
; #define PG8_STAGE(bufoff, gbase, voff) do { _Pragma("unroll") for (int _i = 0; _i < 2; ++_i) \
;         __builtin_amdgcn_global_load_lds((const unsigned*)((const char*)(gbase) + (voff)[_i]), (LAS unsigned*)(lds + (bufoff) + ldsw + _i * 8192), 16, 0, 0); } while (0)
; #define PG8_LDA(dst, b, h) do { _Pragma("unroll") for (int m = 0; m < 4; ++m) _Pragma("unroll") for (int k = 0; k < 2; ++k) dst[m][k] = *(const LAS bf16x8*)(lds + PG8_SA(b, h) + aoff + m * 2048 + k * KOFF); } while (0)
; #define PG8_LDB(dst, b, h) do { _Pragma("unroll") for (int n = 0; n < 2; ++n) _Pragma("unroll") for (int k = 0; k < 2; ++k) dst[n][k] = *(const LAS bf16x8*)(lds + PG8_SB(b, h) + boff + n * 2048 + k * KOFF); } while (0)
; #define PG8_WAIT_V(n) asm volatile("s_waitcnt vmcnt(" #n ")" ::: "memory")
; #define PG8_WAIT_L(n) asm volatile("s_waitcnt lgkmcnt(" #n ")" ::: "memory")
; #define PG8_BAR __builtin_amdgcn_s_barrier()
; #define PG8_SCHED __builtin_amdgcn_sched_barrier(0)
; template <class Epi, bool ALIGN_EPI = true, bool FP8 = false>
; __device__ __forceinline__ void gemm_phase(LAS unsigned char* lds, const Gemm g, const StaticOrder& S, const Epi& E, const int wid) {
;     ...
;             const char* a1 = cA + (size_t)(t + 1) * kstep;
;             const char* a2 = last ? nA : cA + (size_t)(t + 2) * kstep; const char* b2 = last ? nB : cB + (size_t)(t + 2) * kstep;
;             const char* a3 = a2 + kstep; const char* b3 = b2 + kstep;
;             PG8_LDB(B0, 0, 0); PG8_LDB(B1, 0, 1); PG8_SCHED; PG8_LDA(At, 0, 0); PG8_STAGE(PG8_SA(1, 1), a1 + hstep, voffA);
;             PG8_WAIT_V(8); PG8_WAIT_L(0); PG8_BAR; PG8_MMA(0, 0, At, B0); PG8_MMA(0, 1, At, B1); PG8_BAR; PG8_SCHED;
;             PG8_LDA(At, 0, 1); PG8_STAGE(PG8_SB(0, 0), b2, voffB); PG8_STAGE(PG8_SB(0, 1), b2 + hstep, voffB); PG8_STAGE(PG8_SA(0, 0), a2, voffA);
;             PG8_WAIT_V(8); PG8_WAIT_L(0); PG8_BAR; PG8_MMA(1, 0, At, B0); PG8_MMA(1, 1, At, B1); PG8_BAR; PG8_SCHED;
;             PG8_LDB(B0, 1, 0); PG8_LDB(B1, 1, 1); PG8_SCHED; PG8_LDA(At, 1, 0); PG8_STAGE(PG8_SA(0, 1), a2 + hstep, voffA);
;             PG8_WAIT_V(8); PG8_WAIT_L(0); PG8_BAR; PG8_MMA(0, 0, At, B0); PG8_MMA(0, 1, At, B1); PG8_BAR; PG8_SCHED;
.Ldefbar_skip_3:
.LBB0_572:
	ds_read_b128 v[152:155], v190
	ds_read_b128 v[156:159], v190 offset:1024
	ds_read_b128 v[144:147], v190 offset:2048
	ds_read_b128 v[148:151], v190 offset:3072
	ds_read_b128 v[136:139], v191
	ds_read_b128 v[140:143], v191 offset:1024
	ds_read_b128 v[128:131], v191 offset:2048
	ds_read_b128 v[132:135], v191 offset:3072
	s_add_i32 s3, s34, 2
	s_add_u32 s35, s30, 0xfffc0080
	s_addc_u32 s36, s31, -1
	s_cmp_eq_u32 s86, s34
	s_cselect_b32 s34, s85, s87
	s_cselect_b32 s37, s21, s36
	s_cselect_b32 s36, s23, s35
	s_cselect_b32 s35, s84, s88
	v_lshl_add_u64 v[220:221], s[30:31], 0, v[170:171]
	s_add_i32 m0, s27, 0xc000
	ds_read_b128 v[178:181], v192
	ds_read_b128 v[182:185], v192 offset:1024
	ds_read_b128 v[196:199], v192 offset:2048
	ds_read_b128 v[200:203], v192 offset:3072
	ds_read_b128 v[204:207], v192 offset:4096
	ds_read_b128 v[208:211], v192 offset:5120
	ds_read_b128 v[212:215], v192 offset:6144
	ds_read_b128 v[216:219], v192 offset:7168
	global_load_lds_dwordx4 v[220:221], off
	v_lshl_add_u64 v[220:221], s[30:31], 0, v[172:173]
	s_add_i32 m0, s27, 0xe000
	s_nop 0
	global_load_lds_dwordx4 v[220:221], off
	s_setprio 1
	s_waitcnt vmcnt(8) lgkmcnt(0)
	s_barrier
	v_mfma_f32_16x16x128_f8f6f4 v[120:123], v[152:159], v[178:185], v[120:123]
	v_mfma_f32_16x16x128_f8f6f4 v[124:127], v[144:151], v[178:185], v[124:127]
	v_mfma_f32_16x16x128_f8f6f4 v[112:115], v[152:159], v[196:203], v[112:115]
	v_mfma_f32_16x16x128_f8f6f4 v[116:119], v[144:151], v[196:203], v[116:119]
	v_mfma_f32_16x16x128_f8f6f4 v[104:107], v[152:159], v[204:211], v[104:107]
	v_mfma_f32_16x16x128_f8f6f4 v[108:111], v[144:151], v[204:211], v[108:111]
	v_mfma_f32_16x16x128_f8f6f4 v[88:91], v[152:159], v[212:219], v[88:91]
	v_mfma_f32_16x16x128_f8f6f4 v[92:95], v[144:151], v[212:219], v[92:95]
	v_mfma_f32_16x16x128_f8f6f4 v[96:99], v[136:143], v[178:185], v[96:99]
	v_mfma_f32_16x16x128_f8f6f4 v[100:103], v[128:135], v[178:185], v[100:103]
	v_mfma_f32_16x16x128_f8f6f4 v[80:83], v[136:143], v[196:203], v[80:83]
	v_mfma_f32_16x16x128_f8f6f4 v[84:87], v[128:135], v[196:203], v[84:87]
	v_mfma_f32_16x16x128_f8f6f4 v[72:75], v[136:143], v[204:211], v[72:75]
	v_mfma_f32_16x16x128_f8f6f4 v[76:79], v[128:135], v[204:211], v[76:79]
	v_mfma_f32_16x16x128_f8f6f4 v[64:67], v[136:143], v[212:219], v[64:67]
	v_mfma_f32_16x16x128_f8f6f4 v[68:71], v[128:135], v[212:219], v[68:71]
	s_barrier
	s_setprio 0
	s_add_i32 s42, s75, s48
	v_lshl_add_u64 v[178:179], s[34:35], 0, v[164:165]
	s_mov_b32 m0, s42
	ds_read_b128 v[196:199], v192 offset:16384
	ds_read_b128 v[200:203], v192 offset:17408
	ds_read_b128 v[204:207], v192 offset:18432
	ds_read_b128 v[208:211], v192 offset:19456
	ds_read_b128 v[212:215], v192 offset:20480
	ds_read_b128 v[216:219], v192 offset:21504
	ds_read_b128 v[220:223], v192 offset:22528
	ds_read_b128 v[224:227], v192 offset:23552
	global_load_lds_dwordx4 v[178:179], off
	s_add_i32 m0, s42, 0x2000
	s_add_u32 s42, s34, 0x40000
	v_lshl_add_u64 v[180:181], s[34:35], 0, v[160:161]
	s_addc_u32 s43, s35, 0
	s_add_i32 s52, s76, s48
	global_load_lds_dwordx4 v[180:181], off
	v_lshl_add_u64 v[182:183], s[42:43], 0, v[164:165]
	s_mov_b32 m0, s52
	v_lshl_add_u64 v[184:185], s[36:37], 0, v[162:163]
	global_load_lds_dwordx4 v[182:183], off
	v_lshl_add_u64 v[182:183], s[42:43], 0, v[160:161]
	s_add_i32 m0, s52, 0x2000
	s_nop 0
	global_load_lds_dwordx4 v[182:183], off
	v_lshl_add_u64 v[182:183], s[36:37], 0, v[166:167]
	s_mov_b32 m0, s27
	s_nop 0
	global_load_lds_dwordx4 v[182:183], off
	s_mov_b32 m0, s55
	s_nop 0
	global_load_lds_dwordx4 v[184:185], off
	s_setprio 1
	s_waitcnt vmcnt(8) lgkmcnt(0)
	s_barrier
	v_mfma_f32_16x16x128_f8f6f4 v[56:59], v[152:159], v[196:203], v[56:59]
	v_mfma_f32_16x16x128_f8f6f4 v[60:63], v[144:151], v[196:203], v[60:63]
	v_mfma_f32_16x16x128_f8f6f4 v[48:51], v[152:159], v[204:211], v[48:51]
	v_mfma_f32_16x16x128_f8f6f4 v[52:55], v[144:151], v[204:211], v[52:55]
	v_mfma_f32_16x16x128_f8f6f4 v[40:43], v[152:159], v[212:219], v[40:43]
	v_mfma_f32_16x16x128_f8f6f4 v[44:47], v[144:151], v[212:219], v[44:47]
	v_mfma_f32_16x16x128_f8f6f4 v[228:231], v[152:159], v[220:227], v[24:27]
	v_mfma_f32_16x16x128_f8f6f4 v[232:235], v[144:151], v[220:227], v[28:31]
	v_mfma_f32_16x16x128_f8f6f4 v[236:239], v[136:143], v[196:203], v[32:35]
	v_mfma_f32_16x16x128_f8f6f4 v[240:243], v[128:135], v[196:203], v[36:39]
	v_mfma_f32_16x16x128_f8f6f4 v[244:247], v[136:143], v[204:211], v[16:19]
	v_mfma_f32_16x16x128_f8f6f4 v[204:207], v[128:135], v[204:211], v[20:23]
	v_mfma_f32_16x16x128_f8f6f4 v[208:211], v[136:143], v[212:219], v[8:11]
	v_mfma_f32_16x16x128_f8f6f4 v[212:215], v[128:135], v[212:219], v[12:15]
	v_mfma_f32_16x16x128_f8f6f4 v[216:219], v[136:143], v[220:227], v[0:3]
	v_mfma_f32_16x16x128_f8f6f4 v[220:223], v[128:135], v[220:227], v[4:7]
	s_barrier
	s_setprio 0
	s_add_i32 s42, 0, 0x18000
	s_add_i32 s43, 0, 0x1c000
	s_nop 0
	v_add_u32_e32 v12, s42, v187
	v_add_u32_e32 v16, s43, v187
	ds_read_b128 v[0:3], v12
	ds_read_b128 v[4:7], v12 offset:1024
	ds_read_b128 v[8:11], v12 offset:2048
	ds_read_b128 v[12:15], v12 offset:3072
	ds_read_b128 v[128:131], v16
	ds_read_b128 v[132:135], v16 offset:1024
	ds_read_b128 v[136:139], v16 offset:2048
	ds_read_b128 v[140:143], v16 offset:3072
	s_add_u32 s36, s36, 0x40000
	s_addc_u32 s37, s37, 0
	s_mov_b32 m0, s64
	v_lshl_add_u64 v[152:153], s[36:37], 0, v[166:167]
	ds_read_b128 v[16:19], v192 offset:32768
	ds_read_b128 v[20:23], v192 offset:33792
	ds_read_b128 v[24:27], v192 offset:34816
	ds_read_b128 v[28:31], v192 offset:35840
	ds_read_b128 v[32:35], v192 offset:36864
	ds_read_b128 v[36:39], v192 offset:37888
	ds_read_b128 v[144:147], v192 offset:38912
	ds_read_b128 v[148:151], v192 offset:39936
	global_load_lds_dwordx4 v[152:153], off
	v_lshl_add_u64 v[152:153], s[36:37], 0, v[162:163]
	s_mov_b32 m0, s65
	s_nop 0
	global_load_lds_dwordx4 v[152:153], off
	s_setprio 1
	s_waitcnt vmcnt(8) lgkmcnt(0)
	s_barrier
; #define PG8_STAGE(bufoff, gbase, voff) do { _Pragma("unroll") for (int _i = 0; _i < 2; ++_i) \
;         __builtin_amdgcn_global_load_lds((const unsigned*)((const char*)(gbase) + (voff)[_i]), (LAS unsigned*)(lds + (bufoff) + ldsw + _i * 8192), 16, 0, 0); } while (0)
; #define PG8_LDA(dst, b, h) do { _Pragma("unroll") for (int m = 0; m < 4; ++m) _Pragma("unroll") for (int k = 0; k < 2; ++k) dst[m][k] = *(const LAS bf16x8*)(lds + PG8_SA(b, h) + aoff + m * 2048 + k * KOFF); } while (0)
; #define PG8_WAIT_V(n) asm volatile("s_waitcnt vmcnt(" #n ")" ::: "memory")
; #define PG8_WAIT_L(n) asm volatile("s_waitcnt lgkmcnt(" #n ")" ::: "memory")
; #define PG8_BAR __builtin_amdgcn_s_barrier()
; #define PG8_SCHED __builtin_amdgcn_sched_barrier(0)
; template <class Epi, bool ALIGN_EPI = true, bool FP8 = false>
; __device__ __forceinline__ void gemm_phase(LAS unsigned char* lds, const Gemm g, const StaticOrder& S, const Epi& E, const int wid) {
;     ...
;             PG8_WAIT_V(8); PG8_WAIT_L(0); PG8_BAR; PG8_MMA(0, 0, At, B0); PG8_MMA(0, 1, At, B1); PG8_BAR; PG8_SCHED;
;             PG8_LDA(At, 1, 1); PG8_STAGE(PG8_SB(1, 0), b3, voffB); PG8_STAGE(PG8_SB(1, 1), b3 + hstep, voffB); PG8_STAGE(PG8_SA(1, 0), a3, voffA);
;             PG8_WAIT_V(8); PG8_WAIT_L(0); PG8_BAR; PG8_MMA(1, 0, At, B0); PG8_MMA(1, 1, At, B1); PG8_BAR; PG8_SCHED;
;         }
	v_mfma_f32_16x16x128_f8f6f4 v[120:123], v[0:7], v[16:23], v[120:123]
	v_mfma_f32_16x16x128_f8f6f4 v[124:127], v[8:15], v[16:23], v[124:127]
	v_mfma_f32_16x16x128_f8f6f4 v[112:115], v[0:7], v[24:31], v[112:115]
	v_mfma_f32_16x16x128_f8f6f4 v[116:119], v[8:15], v[24:31], v[116:119]
	v_mfma_f32_16x16x128_f8f6f4 v[104:107], v[0:7], v[32:39], v[104:107]
	v_mfma_f32_16x16x128_f8f6f4 v[108:111], v[8:15], v[32:39], v[108:111]
	v_mfma_f32_16x16x128_f8f6f4 v[88:91], v[0:7], v[144:151], v[88:91]
	v_mfma_f32_16x16x128_f8f6f4 v[92:95], v[8:15], v[144:151], v[92:95]
	v_mfma_f32_16x16x128_f8f6f4 v[96:99], v[128:135], v[16:23], v[96:99]
	v_mfma_f32_16x16x128_f8f6f4 v[100:103], v[136:143], v[16:23], v[100:103]
	v_mfma_f32_16x16x128_f8f6f4 v[80:83], v[128:135], v[24:31], v[80:83]
	v_mfma_f32_16x16x128_f8f6f4 v[84:87], v[136:143], v[24:31], v[84:87]
	v_mfma_f32_16x16x128_f8f6f4 v[72:75], v[128:135], v[32:39], v[72:75]
	v_mfma_f32_16x16x128_f8f6f4 v[76:79], v[136:143], v[32:39], v[76:79]
	v_mfma_f32_16x16x128_f8f6f4 v[64:67], v[128:135], v[144:151], v[64:67]
	v_mfma_f32_16x16x128_f8f6f4 v[68:71], v[136:143], v[144:151], v[68:71]
	s_barrier
	s_setprio 0
	s_add_i32 s36, s42, s48
	v_lshl_add_u64 v[24:25], v[178:179], 0, s[8:9]
	s_mov_b32 m0, s36
	ds_read_b128 v[16:19], v192 offset:49152
	ds_read_b128 v[20:23], v192 offset:50176
	ds_read_b128 v[144:147], v192 offset:51200
	ds_read_b128 v[148:151], v192 offset:52224
	ds_read_b128 v[152:155], v192 offset:53248
	ds_read_b128 v[156:159], v192 offset:54272
	ds_read_b128 v[196:199], v192 offset:55296
	ds_read_b128 v[200:203], v192 offset:56320
	global_load_lds_dwordx4 v[24:25], off
	s_add_i32 m0, s36, 0x2000
	s_add_u32 s34, s34, 0x40080
	v_lshl_add_u64 v[24:25], v[180:181], 0, s[8:9]
	s_addc_u32 s35, s35, 0
	s_add_i32 s36, s43, s48
	global_load_lds_dwordx4 v[24:25], off
	v_lshl_add_u64 v[24:25], s[34:35], 0, v[164:165]
	s_mov_b32 m0, s36
	s_nop 0
	global_load_lds_dwordx4 v[24:25], off
	v_lshl_add_u64 v[24:25], s[34:35], 0, v[160:161]
	s_add_i32 m0, s36, 0x2000
	s_nop 0
	global_load_lds_dwordx4 v[24:25], off
	v_lshl_add_u64 v[24:25], v[182:183], 0, s[8:9]
	s_mov_b32 m0, s70
	s_nop 0
	global_load_lds_dwordx4 v[24:25], off
	v_lshl_add_u64 v[24:25], v[184:185], 0, s[8:9]
	s_mov_b32 m0, s71
	s_nop 0
	global_load_lds_dwordx4 v[24:25], off
	s_setprio 1
	s_waitcnt vmcnt(8) lgkmcnt(0)
	s_barrier
	v_mfma_f32_16x16x128_f8f6f4 v[56:59], v[0:7], v[16:23], v[56:59]
	v_mfma_f32_16x16x128_f8f6f4 v[60:63], v[8:15], v[16:23], v[60:63]
	v_mfma_f32_16x16x128_f8f6f4 v[48:51], v[0:7], v[144:151], v[48:51]
	v_mfma_f32_16x16x128_f8f6f4 v[52:55], v[8:15], v[144:151], v[52:55]
	v_mfma_f32_16x16x128_f8f6f4 v[40:43], v[0:7], v[152:159], v[40:43]
	v_mfma_f32_16x16x128_f8f6f4 v[44:47], v[8:15], v[152:159], v[44:47]
	v_mfma_f32_16x16x128_f8f6f4 v[24:27], v[0:7], v[196:203], v[228:231]
	v_mfma_f32_16x16x128_f8f6f4 v[28:31], v[8:15], v[196:203], v[232:235]
	v_mfma_f32_16x16x128_f8f6f4 v[32:35], v[128:135], v[16:23], v[236:239]
	v_mfma_f32_16x16x128_f8f6f4 v[36:39], v[136:143], v[16:23], v[240:243]
	v_mfma_f32_16x16x128_f8f6f4 v[16:19], v[128:135], v[144:151], v[244:247]
	v_mfma_f32_16x16x128_f8f6f4 v[20:23], v[136:143], v[144:151], v[204:207]
	v_mfma_f32_16x16x128_f8f6f4 v[8:11], v[128:135], v[152:159], v[208:211]
	v_mfma_f32_16x16x128_f8f6f4 v[12:15], v[136:143], v[152:159], v[212:215]
	v_mfma_f32_16x16x128_f8f6f4 v[0:3], v[128:135], v[196:203], v[216:219]
	v_mfma_f32_16x16x128_f8f6f4 v[4:7], v[136:143], v[196:203], v[220:223]
	s_barrier
	s_setprio 0
	s_add_u32 s30, s30, 0x100
	s_addc_u32 s31, s31, 0
	s_add_u32 s87, s87, 0x100
	s_addc_u32 s88, s88, 0
	s_cmp_ge_u32 s3, s83
	s_mov_b32 s34, s3
	s_cbranch_scc0 .LBB0_572
;     __device__ __forceinline__ void operator()(const Acc& acc, const Unit& u, int wr, int wc, int fr, int fq) const {
;     ...
;                         const f32x4 v0 = acc[ai][bj][m][0] * QS, v1 = acc[ai][bj][m][1] * QS;
; template <class Epi, bool ALIGN_EPI = true, bool FP8 = false>
; __device__ __forceinline__ void gemm_phase(LAS unsigned char* lds, const Gemm g, const StaticOrder& S, const Epi& E, const int wid) {
;     ...
;         if constexpr (FP8) {
; #pragma unroll
;             for (int a = 0; a < 2; ++a)
; #pragma unroll
;                 for (int b = 0; b < 2; ++b)
; #pragma unroll
;                     for (int m = 0; m < 4; ++m) { const f32x8 c_ = acc8[a][b][m]; acc[a][b][m][0] = __builtin_shufflevector(c_, c_, 0, 1, 2, 3); acc[a][b][m][1] = __builtin_shufflevector(c_, c_, 4, 5, 6, 7); }
;         }
	v_pk_mul_f32 v[122:123], v[122:123], s[14:15] op_sel_hi:[1,0]
	v_pk_mul_f32 v[128:129], v[120:121], s[14:15] op_sel_hi:[1,0]
	v_pk_mul_f32 v[120:121], v[126:127], s[14:15] op_sel_hi:[1,0]
	v_pk_mul_f32 v[124:125], v[124:125], s[14:15] op_sel_hi:[1,0]
	v_pk_mul_f32 v[132:133], v[98:99], s[14:15] op_sel_hi:[1,0]
	v_pk_mul_f32 v[136:137], v[96:97], s[14:15] op_sel_hi:[1,0]
	v_pk_mul_f32 v[130:131], v[102:103], s[14:15] op_sel_hi:[1,0]
	v_pk_mul_f32 v[134:135], v[100:101], s[14:15] op_sel_hi:[1,0]
	v_pk_mul_f32 v[100:101], v[114:115], s[14:15] op_sel_hi:[1,0]
	v_pk_mul_f32 v[112:113], v[112:113], s[14:15] op_sel_hi:[1,0]
	v_pk_mul_f32 v[96:97], v[118:119], s[14:15] op_sel_hi:[1,0]
	v_pk_mul_f32 v[102:103], v[116:117], s[14:15] op_sel_hi:[1,0]
	v_pk_mul_f32 v[116:117], v[82:83], s[14:15] op_sel_hi:[1,0]
	v_pk_mul_f32 v[126:127], v[80:81], s[14:15] op_sel_hi:[1,0]
	v_pk_mul_f32 v[114:115], v[86:87], s[14:15] op_sel_hi:[1,0]
	v_pk_mul_f32 v[118:119], v[84:85], s[14:15] op_sel_hi:[1,0]
	v_pk_mul_f32 v[82:83], v[106:107], s[14:15] op_sel_hi:[1,0]
	v_pk_mul_f32 v[86:87], v[104:105], s[14:15] op_sel_hi:[1,0]
	v_pk_mul_f32 v[80:81], v[110:111], s[14:15] op_sel_hi:[1,0]
	v_pk_mul_f32 v[84:85], v[108:109], s[14:15] op_sel_hi:[1,0]
	v_pk_mul_f32 v[104:105], v[74:75], s[14:15] op_sel_hi:[1,0]
	v_pk_mul_f32 v[108:109], v[72:73], s[14:15] op_sel_hi:[1,0]
	v_pk_mul_f32 v[98:99], v[78:79], s[14:15] op_sel_hi:[1,0]
	v_pk_mul_f32 v[106:107], v[76:77], s[14:15] op_sel_hi:[1,0]
	v_pk_mul_f32 v[74:75], v[90:91], s[14:15] op_sel_hi:[1,0]
	v_pk_mul_f32 v[78:79], v[88:89], s[14:15] op_sel_hi:[1,0]
	v_pk_mul_f32 v[72:73], v[94:95], s[14:15] op_sel_hi:[1,0]
	v_pk_mul_f32 v[76:77], v[92:93], s[14:15] op_sel_hi:[1,0]
	v_pk_mul_f32 v[66:67], v[66:67], s[14:15] op_sel_hi:[1,0]
	v_pk_mul_f32 v[88:89], v[64:65], s[14:15] op_sel_hi:[1,0]
	v_pk_mul_f32 v[64:65], v[70:71], s[14:15] op_sel_hi:[1,0]
	v_pk_mul_f32 v[68:69], v[68:69], s[14:15] op_sel_hi:[1,0]
	v_pk_mul_f32 v[58:59], v[58:59], s[14:15] op_sel_hi:[1,0]
	v_pk_mul_f32 v[70:71], v[56:57], s[14:15] op_sel_hi:[1,0]
	v_pk_mul_f32 v[56:57], v[62:63], s[14:15] op_sel_hi:[1,0]
	v_pk_mul_f32 v[60:61], v[60:61], s[14:15] op_sel_hi:[1,0]
	v_pk_mul_f32 v[92:93], v[34:35], s[14:15] op_sel_hi:[1,0]
	v_pk_mul_f32 v[110:111], v[32:33], s[14:15] op_sel_hi:[1,0]
	v_pk_mul_f32 v[90:91], v[38:39], s[14:15] op_sel_hi:[1,0]
	v_pk_mul_f32 v[94:95], v[36:37], s[14:15] op_sel_hi:[1,0]
	v_pk_mul_f32 v[36:37], v[50:51], s[14:15] op_sel_hi:[1,0]
	v_pk_mul_f32 v[48:49], v[48:49], s[14:15] op_sel_hi:[1,0]
	v_pk_mul_f32 v[32:33], v[54:55], s[14:15] op_sel_hi:[1,0]
	v_pk_mul_f32 v[38:39], v[52:53], s[14:15] op_sel_hi:[1,0]
	v_pk_mul_f32 v[52:53], v[18:19], s[14:15] op_sel_hi:[1,0]
	v_pk_mul_f32 v[62:63], v[16:17], s[14:15] op_sel_hi:[1,0]
	v_pk_mul_f32 v[50:51], v[22:23], s[14:15] op_sel_hi:[1,0]
	v_pk_mul_f32 v[54:55], v[20:21], s[14:15] op_sel_hi:[1,0]
	v_pk_mul_f32 v[18:19], v[42:43], s[14:15] op_sel_hi:[1,0]
	v_pk_mul_f32 v[22:23], v[40:41], s[14:15] op_sel_hi:[1,0]
	v_pk_mul_f32 v[16:17], v[46:47], s[14:15] op_sel_hi:[1,0]
	v_pk_mul_f32 v[20:21], v[44:45], s[14:15] op_sel_hi:[1,0]
	v_pk_mul_f32 v[40:41], v[10:11], s[14:15] op_sel_hi:[1,0]
	v_pk_mul_f32 v[44:45], v[8:9], s[14:15] op_sel_hi:[1,0]
	v_pk_mul_f32 v[34:35], v[14:15], s[14:15] op_sel_hi:[1,0]
	v_pk_mul_f32 v[42:43], v[12:13], s[14:15] op_sel_hi:[1,0]
	v_pk_mul_f32 v[10:11], v[26:27], s[14:15] op_sel_hi:[1,0]
	v_pk_mul_f32 v[14:15], v[24:25], s[14:15] op_sel_hi:[1,0]
	v_pk_mul_f32 v[8:9], v[30:31], s[14:15] op_sel_hi:[1,0]
	v_pk_mul_f32 v[12:13], v[28:29], s[14:15] op_sel_hi:[1,0]
	v_pk_mul_f32 v[2:3], v[2:3], s[14:15] op_sel_hi:[1,0]
	v_pk_mul_f32 v[24:25], v[0:1], s[14:15] op_sel_hi:[1,0]
	v_pk_mul_f32 v[0:1], v[6:7], s[14:15] op_sel_hi:[1,0]
	v_pk_mul_f32 v[4:5], v[4:5], s[14:15] op_sel_hi:[1,0]
	s_and_b64 vcc, exec, s[12:13]
	s_cbranch_vccz .LBB0_575

; #define PG8_BAR __builtin_amdgcn_s_barrier()
; template <class Epi, bool ALIGN_EPI = true, bool FP8 = false>
; __device__ __forceinline__ void gemm_phase(LAS unsigned char* lds, const Gemm g, const StaticOrder& S, const Epi& E, const int wid) {
;     ...
;         if (!has_next) break;
; #pragma unroll
;         for (int a = 0; a < 2; ++a)
; #pragma unroll
;             for (int b = 0; b < 2; ++b)
; #pragma unroll
;                 for (int m = 0; m < 4; ++m) {
;                     if (!keep) { acc[a][b][m][0] = (f32x4){0.f, 0.f, 0.f, 0.f}; acc[a][b][m][1] = (f32x4){0.f, 0.f, 0.f, 0.f}; }
;                     if constexpr (FP8) acc8[a][b][m] = __builtin_shufflevector(acc[a][b][m][0], acc[a][b][m][1], 0, 1, 2, 3, 4, 5, 6, 7); }
;         cur = nxt; cA = nA; cB = nB; ++ui;
;         if constexpr (ALIGN_EPI) { if (wr == 1) PG8_BAR; }
.LBB0_580:
	s_and_b64 vcc, exec, s[4:5]
	s_cbranch_vccnz .LBB0_564
	s_mov_b32 s100, 1
	s_branch .LBB0_564

; #define PG8_BAR __builtin_amdgcn_s_barrier()
;     __device__ __forceinline__ bool next(int i, Unit& u) const {
;         const bool hm = c < nmini, mini = hm && i == 0;
;         int j = i - (hm ? 1 : 0); j = j < 0 ? 0 : j;
;         const int ip = j >> pair;
;         const bool sk = skew > 0 && ip >= nfull;
;         const long L = sk ? (long)nfull * G + (long)(ip - nfull) * (G - skew) + (c - skew) : (long)ip * G + c; const bool ok = L < nwg && (!sk || c >= skew);
;         int wgid = ok ? (int)L : 0; { const int q = nwg / NXCD, r = nwg % NXCD, xcd = wgid % NXCD, off = wgid / NXCD; wgid = (xcd < r ? xcd * (q + 1) : r * (q + 1) + (xcd - r) * q) + off; }
;         const int nig = WGM * nN, gid = wgid / nig, fm = gid * WGM, gsz = (nM - fm) < WGM ? (nM - fm) : WGM;
;         const int fpm = fm + ((wgid % nig) % gsz), fpn = (wgid % nig) / gsz;
;         const int ns = nsplit > 0 ? nsplit : 1, t = c / ns, ks = c - t * ns, mpm = mini_pm0 + t / nN, mpn = t % nN;
;         u.pm = __builtin_amdgcn_readfirstlane(mini ? mpm : fpm); u.pn = __builtin_amdgcn_readfirstlane(mini ? mpn : fpn);
;         const int kh = mini_pair ? ns / 2 : ns, msub = mini_pair ? ks / kh : 0, mk = ks - msub * kh;
;         u.sub = __builtin_amdgcn_readfirstlane(mini ? msub : (j & ((1 << pair) - 1))); u.kt0 = __builtin_amdgcn_readfirstlane(mini ? mk * mini_nkt : 0); u.nkt = mini ? mini_nkt : nkt_full; u.part = mini ? 1 + ks : 0;
; template <class Epi, bool ALIGN_EPI = true, bool FP8 = false>
; __device__ __forceinline__ void gemm_phase(LAS unsigned char* lds, const Gemm g, const StaticOrder& S, const Epi& E, const int wid) {
;     ...
;             const char* a1 = cA + (size_t)(t + 1) * kstep;
;             const char* a2 = last ? nA : cA + (size_t)(t + 2) * kstep; const char* b2 = last ? nB : cB + (size_t)(t + 2) * kstep;
;             const char* a3 = a2 + kstep; const char* b3 = b2 + kstep;
;             PG8_LDB(B0, 0, 0); PG8_LDB(B1, 0, 1); PG8_SCHED; PG8_LDA(At, 0, 0); PG8_STAGE(PG8_SA(1, 1), a1 + hstep, voffA);
;             PG8_WAIT_V(8); PG8_WAIT_L(0); PG8_BAR; PG8_MMA(0, 0, At, B0); PG8_MMA(0, 1, At, B1); PG8_BAR; PG8_SCHED;
;             PG8_LDA(At, 0, 1); PG8_STAGE(PG8_SB(0, 0), b2, voffB); PG8_STAGE(PG8_SB(0, 1), b2 + hstep, voffB); PG8_STAGE(PG8_SA(0, 0), a2, voffA);
;             PG8_WAIT_V(8); PG8_WAIT_L(0); PG8_BAR; PG8_MMA(1, 0, At, B0); PG8_MMA(1, 1, At, B1); PG8_BAR; PG8_SCHED;
.LBB0_2057:
	s_add_i32 s11, s16, s29
	s_ashr_i32 s16, s11, 31
	s_lshr_b32 s16, s16, 27
	s_add_i32 s16, s11, s16
	s_ashr_i32 s29, s16, 5
	s_lshl_b32 s29, s29, 2
	s_sub_i32 s30, 0x80, s29
	s_min_i32 s31, s30, 4
	s_abs_i32 s30, s31
	v_cvt_f32_u32_e32 v128, s30
	s_sub_i32 s35, 0, s30
	s_andn2_b32 s16, s16, 31
	s_sub_i32 s11, s11, s16
	v_rcp_iflag_f32_e32 v128, v128
	s_abs_i32 s16, s11
	s_xor_b32 s34, s11, s31
	s_ashr_i32 s34, s34, 31
	v_mul_f32_e32 v128, 0x4f7ffffe, v128
	v_cvt_u32_f32_e32 v128, v128
	s_mov_b32 s42, 0
	v_readfirstlane_b32 s36, v128
	s_mul_i32 s35, s35, s36
	s_mul_hi_u32 s35, s36, s35
	s_add_i32 s36, s36, s35
	s_mul_hi_u32 s35, s16, s36
	s_mul_i32 s36, s35, s30
	s_sub_i32 s16, s16, s36
	s_add_i32 s37, s35, 1
	s_sub_i32 s36, s16, s30
	s_cmp_ge_u32 s16, s30
	s_cselect_b32 s35, s37, s35
	s_cselect_b32 s16, s36, s16
	s_add_i32 s36, s35, 1
	s_cmp_ge_u32 s16, s30
	s_cselect_b32 s16, s36, s35
	s_xor_b32 s16, s16, s34
	s_sub_i32 s30, s16, s34
	s_mul_i32 s16, s30, s31
	s_sub_i32 s11, s11, s16
	s_add_i32 s34, s29, s11
	s_ashr_i32 s35, s34, 31
	s_and_b32 s49, s3, 1
	s_lshl_b64 s[36:37], s[34:35], 18
	s_cmp_eq_u32 s49, 0
	s_cselect_b32 s11, s56, s51
	s_cselect_b32 s3, s57, s53
	s_cselect_b32 s29, s27, s55
	s_cselect_b32 s35, s50, s70
	s_add_u32 s36, s11, s36
	s_addc_u32 s37, s3, s37
	s_and_b64 s[38:39], s[6:7], exec
	s_cselect_b32 s11, s37, s65
	s_cselect_b32 s16, s36, s64
	s_ashr_i32 s31, s30, 31
	s_lshl_b64 s[38:39], s[30:31], 18
	s_add_u32 s38, s29, s38
	s_addc_u32 s39, s35, s39
	s_and_b64 s[68:69], s[6:7], exec
	s_cselect_b32 s29, s39, s67
	s_cselect_b32 s31, s38, s66
	s_add_i32 s35, s9, -2
	s_add_u32 s64, s64, 0x20080
	s_addc_u32 s65, s65, 0
	s_add_u32 s89, s66, 0x100
	s_addc_u32 s90, s67, 0
	s_cmp_eq_u32 s100, 0
	s_cbranch_scc1 .Ldefbar_skip_5
	s_mov_b32 s100, 0
	s_barrier
.Ldefbar_skip_5:
.LBB0_2058:
	v_add_u32_e32 v128, s83, v192
	v_add_u32_e32 v132, s84, v192
	ds_read_b128 v[152:155], v128
	ds_read_b128 v[156:159], v128 offset:1024
	ds_read_b128 v[144:147], v128 offset:2048
	ds_read_b128 v[148:151], v128 offset:3072
	ds_read_b128 v[136:139], v132
	ds_read_b128 v[140:143], v132 offset:1024
	ds_read_b128 v[128:131], v132 offset:2048
	ds_read_b128 v[132:135], v132 offset:3072
	s_add_i32 s3, s42, 2
	s_add_u32 s43, s64, 0xfffe0080
	s_addc_u32 s52, s65, -1
	s_cmp_eq_u32 s35, s42
	s_cselect_b32 s69, s11, s52
	s_cselect_b32 s68, s16, s43
	s_cselect_b32 s67, s29, s90
	s_cselect_b32 s66, s31, s89
	v_lshl_add_u64 v[188:189], s[64:65], 0, v[174:175]
	s_add_i32 m0, s72, 0xc000
	ds_read_b128 v[180:183], v193
	ds_read_b128 v[184:187], v193 offset:1024
	ds_read_b128 v[196:199], v193 offset:2048
	ds_read_b128 v[200:203], v193 offset:3072
	ds_read_b128 v[204:207], v193 offset:4096
	ds_read_b128 v[208:211], v193 offset:5120
	ds_read_b128 v[212:215], v193 offset:6144
	ds_read_b128 v[216:219], v193 offset:7168
	global_load_lds_dwordx4 v[188:189], off
	v_lshl_add_u64 v[188:189], s[64:65], 0, v[176:177]
	s_add_i32 m0, s72, 0xe000
	s_nop 0
	global_load_lds_dwordx4 v[188:189], off
	s_setprio 1
	s_waitcnt vmcnt(8) lgkmcnt(0)
	s_barrier
	v_mfma_f32_16x16x128_f8f6f4 v[120:123], v[152:159], v[180:187], v[120:123]
	v_mfma_f32_16x16x128_f8f6f4 v[124:127], v[144:151], v[180:187], v[124:127]
	v_mfma_f32_16x16x128_f8f6f4 v[112:115], v[152:159], v[196:203], v[112:115]
	v_mfma_f32_16x16x128_f8f6f4 v[116:119], v[144:151], v[196:203], v[116:119]
	v_mfma_f32_16x16x128_f8f6f4 v[104:107], v[152:159], v[204:211], v[104:107]
	v_mfma_f32_16x16x128_f8f6f4 v[108:111], v[144:151], v[204:211], v[108:111]
	v_mfma_f32_16x16x128_f8f6f4 v[96:99], v[152:159], v[212:219], v[96:99]
	v_mfma_f32_16x16x128_f8f6f4 v[100:103], v[144:151], v[212:219], v[100:103]
	v_mfma_f32_16x16x128_f8f6f4 v[88:91], v[136:143], v[180:187], v[88:91]
	v_mfma_f32_16x16x128_f8f6f4 v[92:95], v[128:135], v[180:187], v[92:95]
	v_mfma_f32_16x16x128_f8f6f4 v[80:83], v[136:143], v[196:203], v[80:83]
	v_mfma_f32_16x16x128_f8f6f4 v[84:87], v[128:135], v[196:203], v[84:87]
	v_mfma_f32_16x16x128_f8f6f4 v[72:75], v[136:143], v[204:211], v[72:75]
	v_mfma_f32_16x16x128_f8f6f4 v[76:79], v[128:135], v[204:211], v[76:79]
	v_mfma_f32_16x16x128_f8f6f4 v[64:67], v[136:143], v[212:219], v[64:67]
	v_mfma_f32_16x16x128_f8f6f4 v[68:71], v[128:135], v[212:219], v[68:71]
	s_barrier
	s_setprio 0
	s_add_i32 s42, s83, s71
	v_lshl_add_u64 v[180:181], s[66:67], 0, v[162:163]
	s_mov_b32 m0, s42
	ds_read_b128 v[196:199], v193 offset:16384
	ds_read_b128 v[200:203], v193 offset:17408
	ds_read_b128 v[204:207], v193 offset:18432
	ds_read_b128 v[208:211], v193 offset:19456
	ds_read_b128 v[212:215], v193 offset:20480
	ds_read_b128 v[216:219], v193 offset:21504
	ds_read_b128 v[220:223], v193 offset:22528
	ds_read_b128 v[224:227], v193 offset:23552
	global_load_lds_dwordx4 v[180:181], off
	s_add_i32 m0, s42, 0x2000
	s_add_u32 s42, s66, 0x20000
	v_lshl_add_u64 v[182:183], s[66:67], 0, v[166:167]
	s_addc_u32 s43, s67, 0
	s_add_i32 s52, s84, s71
	global_load_lds_dwordx4 v[182:183], off
	v_lshl_add_u64 v[184:185], s[42:43], 0, v[162:163]
	s_mov_b32 m0, s52
	v_lshl_add_u64 v[186:187], s[68:69], 0, v[164:165]
	global_load_lds_dwordx4 v[184:185], off
	v_lshl_add_u64 v[184:185], s[42:43], 0, v[166:167]
	s_add_i32 m0, s52, 0x2000
	s_nop 0
	global_load_lds_dwordx4 v[184:185], off
	v_lshl_add_u64 v[184:185], s[68:69], 0, v[160:161]
	s_mov_b32 m0, s72
	s_nop 0
	global_load_lds_dwordx4 v[184:185], off
	s_mov_b32 m0, s73
	s_nop 0
	global_load_lds_dwordx4 v[186:187], off
	s_setprio 1
	s_waitcnt vmcnt(8) lgkmcnt(0)
	s_barrier
; #define PG8_STAGE(bufoff, gbase, voff) do { _Pragma("unroll") for (int _i = 0; _i < 2; ++_i) \
;         __builtin_amdgcn_global_load_lds((const unsigned*)((const char*)(gbase) + (voff)[_i]), (LAS unsigned*)(lds + (bufoff) + ldsw + _i * 8192), 16, 0, 0); } while (0)
; #define PG8_LDA(dst, b, h) do { _Pragma("unroll") for (int m = 0; m < 4; ++m) _Pragma("unroll") for (int k = 0; k < 2; ++k) dst[m][k] = *(const LAS bf16x8*)(lds + PG8_SA(b, h) + aoff + m * 2048 + k * KOFF); } while (0)
; #define PG8_LDB(dst, b, h) do { _Pragma("unroll") for (int n = 0; n < 2; ++n) _Pragma("unroll") for (int k = 0; k < 2; ++k) dst[n][k] = *(const LAS bf16x8*)(lds + PG8_SB(b, h) + boff + n * 2048 + k * KOFF); } while (0)
; #define PG8_WAIT_V(n) asm volatile("s_waitcnt vmcnt(" #n ")" ::: "memory")
; #define PG8_WAIT_L(n) asm volatile("s_waitcnt lgkmcnt(" #n ")" ::: "memory")
; #define PG8_BAR __builtin_amdgcn_s_barrier()
; #define PG8_SCHED __builtin_amdgcn_sched_barrier(0)
; template <class Epi, bool ALIGN_EPI = true, bool FP8 = false>
; __device__ __forceinline__ void gemm_phase(LAS unsigned char* lds, const Gemm g, const StaticOrder& S, const Epi& E, const int wid) {
;     ...
;             PG8_WAIT_V(8); PG8_WAIT_L(0); PG8_BAR; PG8_MMA(1, 0, At, B0); PG8_MMA(1, 1, At, B1); PG8_BAR; PG8_SCHED;
;             PG8_LDB(B0, 1, 0); PG8_LDB(B1, 1, 1); PG8_SCHED; PG8_LDA(At, 1, 0); PG8_STAGE(PG8_SA(0, 1), a2 + hstep, voffA);
;             PG8_WAIT_V(8); PG8_WAIT_L(0); PG8_BAR; PG8_MMA(0, 0, At, B0); PG8_MMA(0, 1, At, B1); PG8_BAR; PG8_SCHED;
;             PG8_LDA(At, 1, 1); PG8_STAGE(PG8_SB(1, 0), b3, voffB); PG8_STAGE(PG8_SB(1, 1), b3 + hstep, voffB); PG8_STAGE(PG8_SA(1, 0), a3, voffA);
;             PG8_WAIT_V(8); PG8_WAIT_L(0); PG8_BAR; PG8_MMA(1, 0, At, B0); PG8_MMA(1, 1, At, B1); PG8_BAR; PG8_SCHED;
;         }
	v_mfma_f32_16x16x128_f8f6f4 v[56:59], v[152:159], v[196:203], v[56:59]
	v_mfma_f32_16x16x128_f8f6f4 v[60:63], v[144:151], v[196:203], v[60:63]
	v_mfma_f32_16x16x128_f8f6f4 v[48:51], v[152:159], v[204:211], v[48:51]
	v_mfma_f32_16x16x128_f8f6f4 v[52:55], v[144:151], v[204:211], v[52:55]
	v_mfma_f32_16x16x128_f8f6f4 v[40:43], v[152:159], v[212:219], v[40:43]
	v_mfma_f32_16x16x128_f8f6f4 v[44:47], v[144:151], v[212:219], v[44:47]
	v_mfma_f32_16x16x128_f8f6f4 v[188:191], v[152:159], v[220:227], v[32:35]
	v_mfma_f32_16x16x128_f8f6f4 v[228:231], v[144:151], v[220:227], v[36:39]
	v_mfma_f32_16x16x128_f8f6f4 v[232:235], v[136:143], v[196:203], v[24:27]
	v_mfma_f32_16x16x128_f8f6f4 v[236:239], v[128:135], v[196:203], v[28:31]
	v_mfma_f32_16x16x128_f8f6f4 v[240:243], v[136:143], v[204:211], v[16:19]
	v_mfma_f32_16x16x128_f8f6f4 v[204:207], v[128:135], v[204:211], v[20:23]
	v_mfma_f32_16x16x128_f8f6f4 v[208:211], v[136:143], v[212:219], v[8:11]
	v_mfma_f32_16x16x128_f8f6f4 v[212:215], v[128:135], v[212:219], v[12:15]
	v_mfma_f32_16x16x128_f8f6f4 v[216:219], v[136:143], v[220:227], v[0:3]
	v_mfma_f32_16x16x128_f8f6f4 v[220:223], v[128:135], v[220:227], v[4:7]
	s_barrier
	s_setprio 0
	s_add_i32 s52, 0, 0x18000
	s_add_i32 s54, 0, 0x1c000
	s_nop 0
	v_add_u32_e32 v12, s52, v192
	v_add_u32_e32 v16, s54, v192
	ds_read_b128 v[0:3], v12
	ds_read_b128 v[4:7], v12 offset:1024
	ds_read_b128 v[8:11], v12 offset:2048
	ds_read_b128 v[12:15], v12 offset:3072
	ds_read_b128 v[128:131], v16
	ds_read_b128 v[132:135], v16 offset:1024
	ds_read_b128 v[136:139], v16 offset:2048
	ds_read_b128 v[140:143], v16 offset:3072
	s_add_u32 s42, s68, 0x20000
	s_addc_u32 s43, s69, 0
	s_mov_b32 m0, s74
	v_lshl_add_u64 v[152:153], s[42:43], 0, v[160:161]
	ds_read_b128 v[16:19], v193 offset:32768
	ds_read_b128 v[20:23], v193 offset:33792
	ds_read_b128 v[24:27], v193 offset:34816
	ds_read_b128 v[28:31], v193 offset:35840
	ds_read_b128 v[32:35], v193 offset:36864
	ds_read_b128 v[36:39], v193 offset:37888
	ds_read_b128 v[144:147], v193 offset:38912
	ds_read_b128 v[148:151], v193 offset:39936
	global_load_lds_dwordx4 v[152:153], off
	v_lshl_add_u64 v[152:153], s[42:43], 0, v[164:165]
	s_mov_b32 m0, s75
	s_nop 0
	global_load_lds_dwordx4 v[152:153], off
	s_setprio 1
	s_waitcnt vmcnt(8) lgkmcnt(0)
	s_barrier
	v_mfma_f32_16x16x128_f8f6f4 v[120:123], v[0:7], v[16:23], v[120:123]
	v_mfma_f32_16x16x128_f8f6f4 v[124:127], v[8:15], v[16:23], v[124:127]
	v_mfma_f32_16x16x128_f8f6f4 v[112:115], v[0:7], v[24:31], v[112:115]
	v_mfma_f32_16x16x128_f8f6f4 v[116:119], v[8:15], v[24:31], v[116:119]
	v_mfma_f32_16x16x128_f8f6f4 v[104:107], v[0:7], v[32:39], v[104:107]
	v_mfma_f32_16x16x128_f8f6f4 v[108:111], v[8:15], v[32:39], v[108:111]
	v_mfma_f32_16x16x128_f8f6f4 v[96:99], v[0:7], v[144:151], v[96:99]
	v_mfma_f32_16x16x128_f8f6f4 v[100:103], v[8:15], v[144:151], v[100:103]
	v_mfma_f32_16x16x128_f8f6f4 v[88:91], v[128:135], v[16:23], v[88:91]
	v_mfma_f32_16x16x128_f8f6f4 v[92:95], v[136:143], v[16:23], v[92:95]
	v_mfma_f32_16x16x128_f8f6f4 v[80:83], v[128:135], v[24:31], v[80:83]
	v_mfma_f32_16x16x128_f8f6f4 v[84:87], v[136:143], v[24:31], v[84:87]
	v_mfma_f32_16x16x128_f8f6f4 v[72:75], v[128:135], v[32:39], v[72:75]
	v_mfma_f32_16x16x128_f8f6f4 v[76:79], v[136:143], v[32:39], v[76:79]
	v_mfma_f32_16x16x128_f8f6f4 v[64:67], v[128:135], v[144:151], v[64:67]
	v_mfma_f32_16x16x128_f8f6f4 v[68:71], v[136:143], v[144:151], v[68:71]
	s_barrier
	s_setprio 0
	s_add_i32 s42, s52, s71
	v_lshl_add_u64 v[24:25], v[180:181], 0, s[20:21]
	s_mov_b32 m0, s42
	ds_read_b128 v[16:19], v193 offset:49152
	ds_read_b128 v[20:23], v193 offset:50176
	ds_read_b128 v[144:147], v193 offset:51200
	ds_read_b128 v[148:151], v193 offset:52224
	ds_read_b128 v[152:155], v193 offset:53248
	ds_read_b128 v[156:159], v193 offset:54272
	ds_read_b128 v[196:199], v193 offset:55296
	ds_read_b128 v[200:203], v193 offset:56320
	global_load_lds_dwordx4 v[24:25], off
	s_add_i32 m0, s42, 0x2000
	s_add_u32 s42, s66, 0x20080
	v_lshl_add_u64 v[24:25], v[182:183], 0, s[20:21]
	s_addc_u32 s43, s67, 0
	s_add_i32 s52, s54, s71
	global_load_lds_dwordx4 v[24:25], off
	v_lshl_add_u64 v[24:25], s[42:43], 0, v[162:163]
	s_mov_b32 m0, s52
	s_nop 0
	global_load_lds_dwordx4 v[24:25], off
	v_lshl_add_u64 v[24:25], s[42:43], 0, v[166:167]
	s_add_i32 m0, s52, 0x2000
	s_nop 0
	global_load_lds_dwordx4 v[24:25], off
	v_lshl_add_u64 v[24:25], v[184:185], 0, s[20:21]
	s_mov_b32 m0, s80
	s_nop 0
	global_load_lds_dwordx4 v[24:25], off
	v_lshl_add_u64 v[24:25], v[186:187], 0, s[20:21]
	s_mov_b32 m0, s81
	s_nop 0
	global_load_lds_dwordx4 v[24:25], off
	s_setprio 1
	s_waitcnt vmcnt(8) lgkmcnt(0)
	s_barrier
	v_mfma_f32_16x16x128_f8f6f4 v[56:59], v[0:7], v[16:23], v[56:59]
	v_mfma_f32_16x16x128_f8f6f4 v[60:63], v[8:15], v[16:23], v[60:63]
	v_mfma_f32_16x16x128_f8f6f4 v[48:51], v[0:7], v[144:151], v[48:51]
	v_mfma_f32_16x16x128_f8f6f4 v[52:55], v[8:15], v[144:151], v[52:55]
	v_mfma_f32_16x16x128_f8f6f4 v[40:43], v[0:7], v[152:159], v[40:43]
	v_mfma_f32_16x16x128_f8f6f4 v[44:47], v[8:15], v[152:159], v[44:47]
	v_mfma_f32_16x16x128_f8f6f4 v[32:35], v[0:7], v[196:203], v[188:191]
	v_mfma_f32_16x16x128_f8f6f4 v[36:39], v[8:15], v[196:203], v[228:231]
	v_mfma_f32_16x16x128_f8f6f4 v[24:27], v[128:135], v[16:23], v[232:235]
	v_mfma_f32_16x16x128_f8f6f4 v[28:31], v[136:143], v[16:23], v[236:239]
	v_mfma_f32_16x16x128_f8f6f4 v[16:19], v[128:135], v[144:151], v[240:243]
	v_mfma_f32_16x16x128_f8f6f4 v[20:23], v[136:143], v[144:151], v[204:207]
	v_mfma_f32_16x16x128_f8f6f4 v[8:11], v[128:135], v[152:159], v[208:211]
	v_mfma_f32_16x16x128_f8f6f4 v[12:15], v[136:143], v[152:159], v[212:215]
	v_mfma_f32_16x16x128_f8f6f4 v[0:3], v[128:135], v[196:203], v[216:219]
	v_mfma_f32_16x16x128_f8f6f4 v[4:7], v[136:143], v[196:203], v[220:223]
	s_barrier
	s_setprio 0
	s_add_u32 s64, s64, 0x100
	s_addc_u32 s65, s65, 0
	s_add_u32 s89, s89, 0x100
	s_addc_u32 s90, s90, 0
	s_cmp_ge_u32 s3, s9
	s_mov_b32 s42, s3
	s_cbranch_scc0 .LBB0_2058
	s_and_b64 vcc, exec, s[22:23]
	s_cbranch_vccz .LBB0_2061
	s_barrier

; #define PG8_BAR __builtin_amdgcn_s_barrier()
; template <class Epi, bool ALIGN_EPI = true, bool FP8 = false>
; __device__ __forceinline__ void gemm_phase(LAS unsigned char* lds, const Gemm g, const StaticOrder& S, const Epi& E, const int wid) {
;     ...
;         if (!has_next) break;
; #pragma unroll
;         for (int a = 0; a < 2; ++a)
; #pragma unroll
;             for (int b = 0; b < 2; ++b)
; #pragma unroll
;                 for (int m = 0; m < 4; ++m) {
;                     if (!keep) { acc[a][b][m][0] = (f32x4){0.f, 0.f, 0.f, 0.f}; acc[a][b][m][1] = (f32x4){0.f, 0.f, 0.f, 0.f}; }
;                     if constexpr (FP8) acc8[a][b][m] = __builtin_shufflevector(acc[a][b][m][0], acc[a][b][m][1], 0, 1, 2, 3, 4, 5, 6, 7); }
;         cur = nxt; cA = nA; cB = nB; ++ui;
;         if constexpr (ALIGN_EPI) { if (wr == 1) PG8_BAR; }
.LBB0_2158:
	s_andn2_b64 vcc, exec, s[6:7]
	s_mov_b64 s[6:7], -1
	s_cbranch_vccnz .LBB0_2052
	s_andn2_b64 vcc, exec, s[14:15]
	s_cbranch_vccnz .LBB0_2051
	s_mov_b32 s100, 1
	s_branch .LBB0_2051

; #define PG8_BAR __builtin_amdgcn_s_barrier()
;     __device__ __forceinline__ bool next(int i, Unit& u) const {
;         const bool hm = c < nmini, mini = hm && i == 0;
;         int j = i - (hm ? 1 : 0); j = j < 0 ? 0 : j;
;         const int ip = j >> pair;
;         const bool sk = skew > 0 && ip >= nfull;
;         const long L = sk ? (long)nfull * G + (long)(ip - nfull) * (G - skew) + (c - skew) : (long)ip * G + c; const bool ok = L < nwg && (!sk || c >= skew);
;         int wgid = ok ? (int)L : 0; { const int q = nwg / NXCD, r = nwg % NXCD, xcd = wgid % NXCD, off = wgid / NXCD; wgid = (xcd < r ? xcd * (q + 1) : r * (q + 1) + (xcd - r) * q) + off; }
;         const int nig = WGM * nN, gid = wgid / nig, fm = gid * WGM, gsz = (nM - fm) < WGM ? (nM - fm) : WGM;
;         const int fpm = fm + ((wgid % nig) % gsz), fpn = (wgid % nig) / gsz;
;         const int ns = nsplit > 0 ? nsplit : 1, t = c / ns, ks = c - t * ns, mpm = mini_pm0 + t / nN, mpn = t % nN;
;         u.pm = __builtin_amdgcn_readfirstlane(mini ? mpm : fpm); u.pn = __builtin_amdgcn_readfirstlane(mini ? mpn : fpn);
;         const int kh = mini_pair ? ns / 2 : ns, msub = mini_pair ? ks / kh : 0, mk = ks - msub * kh;
;         u.sub = __builtin_amdgcn_readfirstlane(mini ? msub : (j & ((1 << pair) - 1))); u.kt0 = __builtin_amdgcn_readfirstlane(mini ? mk * mini_nkt : 0); u.nkt = mini ? mini_nkt : nkt_full; u.part = mini ? 1 + ks : 0;
; template <class Epi, bool ALIGN_EPI = true, bool FP8 = false>
; __device__ __forceinline__ void gemm_phase(LAS unsigned char* lds, const Gemm g, const StaticOrder& S, const Epi& E, const int wid) {
;     ...
; #pragma unroll
;         for (int a = 0; a < 2; ++a)
; #pragma unroll
;             for (int b = 0; b < 2; ++b)
; #pragma unroll
;                 for (int m = 0; m < 4; ++m) {
;                     if (!keep) { acc[a][b][m][0] = (f32x4){0.f, 0.f, 0.f, 0.f}; acc[a][b][m][1] = (f32x4){0.f, 0.f, 0.f, 0.f}; }
;                     if constexpr (FP8) acc8[a][b][m] = __builtin_shufflevector(acc[a][b][m][0], acc[a][b][m][1], 0, 1, 2, 3, 4, 5, 6, 7); }
;         cur = nxt; cA = nA; cB = nB; ++ui;
;         if constexpr (ALIGN_EPI) { if (wr == 1) PG8_BAR; }
.LBB0_2289:
	s_ashr_i32 s3, s3, 3
	s_add_i32 s3, s21, s3
	s_ashr_i32 s18, s3, 31
	s_lshr_b32 s18, s18, 27
	s_add_i32 s18, s3, s18
	s_ashr_i32 s19, s18, 5
	s_lshl_b32 s19, s19, 2
	s_sub_i32 s20, 0x80, s19
	s_min_i32 s20, s20, 4
	s_abs_i32 s21, s20
	v_cvt_f32_u32_e32 v0, s21
	s_sub_i32 s23, 0, s21
	s_andn2_b32 s18, s18, 31
	s_sub_i32 s3, s3, s18
	v_rcp_iflag_f32_e32 v0, v0
	s_abs_i32 s18, s3
	s_xor_b32 s22, s3, s20
	s_ashr_i32 s22, s22, 31
	v_mul_f32_e32 v0, 0x4f7ffffe, v0
	v_cvt_u32_f32_e32 v0, v0
	s_mov_b32 s38, 0
	v_readfirstlane_b32 s24, v0
	s_mul_i32 s23, s23, s24
	s_mul_hi_u32 s23, s24, s23
	s_add_i32 s24, s24, s23
	s_mul_hi_u32 s23, s18, s24
	s_mul_i32 s24, s23, s21
	s_sub_i32 s18, s18, s24
	s_add_i32 s25, s23, 1
	s_sub_i32 s24, s18, s21
	s_cmp_ge_u32 s18, s21
	s_cselect_b32 s23, s25, s23
	s_cselect_b32 s18, s24, s18
	s_add_i32 s24, s23, 1
	s_cmp_ge_u32 s18, s21
	s_cselect_b32 s18, s24, s23
	s_xor_b32 s18, s18, s22
	s_sub_i32 s18, s18, s22
	s_mul_i32 s20, s18, s20
	s_sub_i32 s3, s3, s20
	s_add_i32 s20, s19, s3
	s_ashr_i32 s21, s20, 31
	s_lshl_b64 s[22:23], s[20:21], 19
	s_add_u32 s22, s48, s22
	s_addc_u32 s23, s49, s23
	s_and_b64 s[24:25], s[4:5], exec
	s_cselect_b32 s21, s23, s35
	s_cselect_b32 s31, s22, s34
	s_ashr_i32 s19, s18, 31
	s_lshl_b64 s[24:25], s[18:19], 19
	s_add_u32 s24, s50, s24
	s_addc_u32 s25, s51, s25
	s_and_b64 s[42:43], s[4:5], exec
	s_cselect_b32 s19, s25, s37
	s_cselect_b32 s87, s24, s36
	s_add_i32 s88, s29, -2
	s_add_u32 s34, s34, 0x40080
	s_addc_u32 s35, s35, 0
	s_add_u32 s89, s36, 0x100
	v_mov_b32_e32 v0, 0
	s_addc_u32 s90, s37, 0
	v_mov_b32_e32 v1, v0
	v_mov_b32_e32 v2, v0
	v_mov_b32_e32 v3, v0
	v_mov_b32_e32 v4, v0
	v_mov_b32_e32 v5, v0
	v_mov_b32_e32 v6, v0
	v_mov_b32_e32 v7, v0
	v_mov_b32_e32 v8, v0
	v_mov_b32_e32 v9, v0
	v_mov_b32_e32 v10, v0
	v_mov_b32_e32 v11, v0
	v_mov_b32_e32 v12, v0
	v_mov_b32_e32 v13, v0
	v_mov_b32_e32 v14, v0
	v_mov_b32_e32 v15, v0
	v_mov_b32_e32 v24, v0
	v_mov_b32_e32 v25, v0
	v_mov_b32_e32 v26, v0
	v_mov_b32_e32 v27, v0
	v_mov_b32_e32 v28, v0
	v_mov_b32_e32 v29, v0
	v_mov_b32_e32 v30, v0
	v_mov_b32_e32 v31, v0
	v_mov_b32_e32 v40, v0
	v_mov_b32_e32 v41, v0
	v_mov_b32_e32 v42, v0
	v_mov_b32_e32 v43, v0
	v_mov_b32_e32 v44, v0
	v_mov_b32_e32 v45, v0
	v_mov_b32_e32 v46, v0
	v_mov_b32_e32 v47, v0
	v_mov_b32_e32 v16, v0
	v_mov_b32_e32 v17, v0
	v_mov_b32_e32 v18, v0
	v_mov_b32_e32 v19, v0
	v_mov_b32_e32 v20, v0
	v_mov_b32_e32 v21, v0
	v_mov_b32_e32 v22, v0
	v_mov_b32_e32 v23, v0
	v_mov_b32_e32 v32, v0
	s_waitcnt lgkmcnt(0)
	v_mov_b32_e32 v33, v0
	v_mov_b32_e32 v34, v0
	v_mov_b32_e32 v35, v0
	v_mov_b32_e32 v36, v0
	v_mov_b32_e32 v37, v0
	v_mov_b32_e32 v38, v0
	v_mov_b32_e32 v39, v0
	v_mov_b32_e32 v48, v0
	v_mov_b32_e32 v49, v0
	v_mov_b32_e32 v50, v0
	v_mov_b32_e32 v51, v0
	v_mov_b32_e32 v52, v0
	v_mov_b32_e32 v53, v0
	v_mov_b32_e32 v54, v0
	v_mov_b32_e32 v55, v0
	v_mov_b32_e32 v56, v0
	v_mov_b32_e32 v57, v0
	v_mov_b32_e32 v58, v0
	v_mov_b32_e32 v59, v0
	v_mov_b32_e32 v60, v0
	v_mov_b32_e32 v61, v0
	v_mov_b32_e32 v62, v0
	v_mov_b32_e32 v63, v0
	v_mov_b32_e32 v64, v0
	v_mov_b32_e32 v65, v0
	v_mov_b32_e32 v66, v0
	v_mov_b32_e32 v67, v0
	v_mov_b32_e32 v68, v0
	v_mov_b32_e32 v69, v0
	v_mov_b32_e32 v70, v0
	v_mov_b32_e32 v71, v0
	v_mov_b32_e32 v72, v0
	v_mov_b32_e32 v73, v0
	v_mov_b32_e32 v74, v0
	v_mov_b32_e32 v75, v0
	v_mov_b32_e32 v76, v0
	v_mov_b32_e32 v77, v0
	v_mov_b32_e32 v78, v0
	v_mov_b32_e32 v79, v0
	v_mov_b32_e32 v88, v0
	v_mov_b32_e32 v89, v0
	v_mov_b32_e32 v90, v0
	v_mov_b32_e32 v91, v0
	v_mov_b32_e32 v92, v0
	v_mov_b32_e32 v93, v0
	v_mov_b32_e32 v94, v0
	v_mov_b32_e32 v95, v0
	v_mov_b32_e32 v112, v0
	v_mov_b32_e32 v113, v0
	v_mov_b32_e32 v114, v0
	v_mov_b32_e32 v115, v0
	v_mov_b32_e32 v116, v0
	v_mov_b32_e32 v117, v0
	v_mov_b32_e32 v118, v0
	v_mov_b32_e32 v119, v0
	v_mov_b32_e32 v80, v0
	v_mov_b32_e32 v81, v0
	v_mov_b32_e32 v82, v0
	v_mov_b32_e32 v83, v0
	v_mov_b32_e32 v84, v0
	v_mov_b32_e32 v85, v0
	v_mov_b32_e32 v86, v0
	v_mov_b32_e32 v87, v0
	v_mov_b32_e32 v96, v0
	v_mov_b32_e32 v97, v0
	v_mov_b32_e32 v98, v0
	v_mov_b32_e32 v99, v0
	v_mov_b32_e32 v100, v0
	v_mov_b32_e32 v101, v0
	v_mov_b32_e32 v102, v0
	v_mov_b32_e32 v103, v0
	v_mov_b32_e32 v104, v0
	v_mov_b32_e32 v105, v0
	v_mov_b32_e32 v106, v0
	v_mov_b32_e32 v107, v0
	v_mov_b32_e32 v108, v0
	v_mov_b32_e32 v109, v0
	v_mov_b32_e32 v110, v0
	v_mov_b32_e32 v111, v0
	v_mov_b32_e32 v120, v0
	v_mov_b32_e32 v121, v0
	v_mov_b32_e32 v122, v0
	v_mov_b32_e32 v123, v0
	v_mov_b32_e32 v124, v0
	v_mov_b32_e32 v125, v0
	v_mov_b32_e32 v126, v0
	v_mov_b32_e32 v127, v0
	s_waitcnt vmcnt(0)
	s_cmp_eq_u32 s100, 0
	s_cbranch_scc1 .Ldefbar_skip_6
	s_mov_b32 s100, 0
	s_barrier
; #define PG8_STAGE(bufoff, gbase, voff) do { _Pragma("unroll") for (int _i = 0; _i < 2; ++_i) \
;         __builtin_amdgcn_global_load_lds((const unsigned*)((const char*)(gbase) + (voff)[_i]), (LAS unsigned*)(lds + (bufoff) + ldsw + _i * 8192), 16, 0, 0); } while (0)
; #define PG8_LDA(dst, b, h) do { _Pragma("unroll") for (int m = 0; m < 4; ++m) _Pragma("unroll") for (int k = 0; k < 2; ++k) dst[m][k] = *(const LAS bf16x8*)(lds + PG8_SA(b, h) + aoff + m * 2048 + k * KOFF); } while (0)
; #define PG8_LDB(dst, b, h) do { _Pragma("unroll") for (int n = 0; n < 2; ++n) _Pragma("unroll") for (int k = 0; k < 2; ++k) dst[n][k] = *(const LAS bf16x8*)(lds + PG8_SB(b, h) + boff + n * 2048 + k * KOFF); } while (0)
; #define PG8_WAIT_V(n) asm volatile("s_waitcnt vmcnt(" #n ")" ::: "memory")
; #define PG8_WAIT_L(n) asm volatile("s_waitcnt lgkmcnt(" #n ")" ::: "memory")
; #define PG8_BAR __builtin_amdgcn_s_barrier()
; #define PG8_SCHED __builtin_amdgcn_sched_barrier(0)
; template <class Epi, bool ALIGN_EPI = true, bool FP8 = false>
; __device__ __forceinline__ void gemm_phase(LAS unsigned char* lds, const Gemm g, const StaticOrder& S, const Epi& E, const int wid) {
;     ...
;             const char* a1 = cA + (size_t)(t + 1) * kstep;
;             const char* a2 = last ? nA : cA + (size_t)(t + 2) * kstep; const char* b2 = last ? nB : cB + (size_t)(t + 2) * kstep;
;             const char* a3 = a2 + kstep; const char* b3 = b2 + kstep;
;             PG8_LDB(B0, 0, 0); PG8_LDB(B1, 0, 1); PG8_SCHED; PG8_LDA(At, 0, 0); PG8_STAGE(PG8_SA(1, 1), a1 + hstep, voffA);
;             PG8_WAIT_V(8); PG8_WAIT_L(0); PG8_BAR; PG8_MMA(0, 0, At, B0); PG8_MMA(0, 1, At, B1); PG8_BAR; PG8_SCHED;
;             PG8_LDA(At, 0, 1); PG8_STAGE(PG8_SB(0, 0), b2, voffB); PG8_STAGE(PG8_SB(0, 1), b2 + hstep, voffB); PG8_STAGE(PG8_SA(0, 0), a2, voffA);
;             PG8_WAIT_V(8); PG8_WAIT_L(0); PG8_BAR; PG8_MMA(1, 0, At, B0); PG8_MMA(1, 1, At, B1); PG8_BAR; PG8_SCHED;
.Ldefbar_skip_6:
.LBB0_2290:
	ds_read_b128 v[152:155], v218
	ds_read_b128 v[156:159], v218 offset:1024
	ds_read_b128 v[144:147], v218 offset:2048
	ds_read_b128 v[148:151], v218 offset:3072
	ds_read_b128 v[136:139], v219
	ds_read_b128 v[140:143], v219 offset:1024
	ds_read_b128 v[128:131], v219 offset:2048
	ds_read_b128 v[132:135], v219 offset:3072
	s_add_i32 s3, s38, 2
	s_add_u32 s36, s34, 0xfffc0080
	s_addc_u32 s37, s35, -1
	s_cmp_eq_u32 s88, s38
	s_cselect_b32 s38, s31, s36
	s_cselect_b32 s39, s21, s37
	s_cselect_b32 s37, s19, s90
	s_cselect_b32 s36, s87, s89
	v_lshl_add_u64 v[212:213], s[34:35], 0, v[198:199]
	s_add_i32 m0, s27, 0xc000
	ds_read_b128 v[160:163], v220
	ds_read_b128 v[164:167], v220 offset:1024
	ds_read_b128 v[168:171], v220 offset:2048
	ds_read_b128 v[172:175], v220 offset:3072
	ds_read_b128 v[176:179], v220 offset:4096
	ds_read_b128 v[180:183], v220 offset:5120
	ds_read_b128 v[204:207], v220 offset:6144
	ds_read_b128 v[208:211], v220 offset:7168
	global_load_lds_dwordx4 v[212:213], off
	v_lshl_add_u64 v[212:213], s[34:35], 0, v[200:201]
	s_add_i32 m0, s27, 0xe000
	s_nop 0
	global_load_lds_dwordx4 v[212:213], off
	s_setprio 1
	s_waitcnt vmcnt(8) lgkmcnt(0)
	s_barrier
	v_mfma_f32_16x16x128_f8f6f4 v[120:123], v[152:159], v[160:167], v[120:123]
	v_mfma_f32_16x16x128_f8f6f4 v[124:127], v[144:151], v[160:167], v[124:127]
	v_mfma_f32_16x16x128_f8f6f4 v[104:107], v[152:159], v[168:175], v[104:107]
	v_mfma_f32_16x16x128_f8f6f4 v[108:111], v[144:151], v[168:175], v[108:111]
	v_mfma_f32_16x16x128_f8f6f4 v[96:99], v[152:159], v[176:183], v[96:99]
	v_mfma_f32_16x16x128_f8f6f4 v[100:103], v[144:151], v[176:183], v[100:103]
	v_mfma_f32_16x16x128_f8f6f4 v[80:83], v[152:159], v[204:211], v[80:83]
	v_mfma_f32_16x16x128_f8f6f4 v[84:87], v[144:151], v[204:211], v[84:87]
	v_mfma_f32_16x16x128_f8f6f4 v[112:115], v[136:143], v[160:167], v[112:115]
	v_mfma_f32_16x16x128_f8f6f4 v[116:119], v[128:135], v[160:167], v[116:119]
	v_mfma_f32_16x16x128_f8f6f4 v[88:91], v[136:143], v[168:175], v[88:91]
	v_mfma_f32_16x16x128_f8f6f4 v[92:95], v[128:135], v[168:175], v[92:95]
	v_mfma_f32_16x16x128_f8f6f4 v[72:75], v[136:143], v[176:183], v[72:75]
	v_mfma_f32_16x16x128_f8f6f4 v[76:79], v[128:135], v[176:183], v[76:79]
	v_mfma_f32_16x16x128_f8f6f4 v[64:67], v[136:143], v[204:211], v[64:67]
	v_mfma_f32_16x16x128_f8f6f4 v[68:71], v[128:135], v[204:211], v[68:71]
	s_barrier
	s_setprio 0
	s_add_i32 s42, s75, s53
	v_lshl_add_u64 v[160:161], s[36:37], 0, v[188:189]
	s_mov_b32 m0, s42
	ds_read_b128 v[168:171], v220 offset:16384
	ds_read_b128 v[172:175], v220 offset:17408
	ds_read_b128 v[176:179], v220 offset:18432
	ds_read_b128 v[180:183], v220 offset:19456
	ds_read_b128 v[204:207], v220 offset:20480
	ds_read_b128 v[208:211], v220 offset:21504
	ds_read_b128 v[222:225], v220 offset:22528
	ds_read_b128 v[226:229], v220 offset:23552
	global_load_lds_dwordx4 v[160:161], off
	s_add_i32 m0, s42, 0x2000
	s_add_u32 s42, s36, 0x40000
	v_lshl_add_u64 v[162:163], s[36:37], 0, v[184:185]
	s_addc_u32 s43, s37, 0
	s_add_i32 s52, s76, s53
	global_load_lds_dwordx4 v[162:163], off
	v_lshl_add_u64 v[164:165], s[42:43], 0, v[188:189]
	s_mov_b32 m0, s52
	v_lshl_add_u64 v[166:167], s[38:39], 0, v[186:187]
	global_load_lds_dwordx4 v[164:165], off
	v_lshl_add_u64 v[164:165], s[42:43], 0, v[184:185]
	s_add_i32 m0, s52, 0x2000
	s_nop 0
	global_load_lds_dwordx4 v[164:165], off
	v_lshl_add_u64 v[164:165], s[38:39], 0, v[190:191]
	s_mov_b32 m0, s27
	s_nop 0
	global_load_lds_dwordx4 v[164:165], off
	s_mov_b32 m0, s55
	s_nop 0
	global_load_lds_dwordx4 v[166:167], off
	s_setprio 1
	s_waitcnt vmcnt(8) lgkmcnt(0)
	s_barrier
	v_mfma_f32_16x16x128_f8f6f4 v[56:59], v[152:159], v[168:175], v[56:59]
	v_mfma_f32_16x16x128_f8f6f4 v[60:63], v[144:151], v[168:175], v[60:63]
	v_mfma_f32_16x16x128_f8f6f4 v[48:51], v[152:159], v[176:183], v[48:51]
	v_mfma_f32_16x16x128_f8f6f4 v[52:55], v[144:151], v[176:183], v[52:55]
	v_mfma_f32_16x16x128_f8f6f4 v[32:35], v[152:159], v[204:211], v[32:35]
	v_mfma_f32_16x16x128_f8f6f4 v[212:215], v[144:151], v[204:211], v[36:39]
	v_mfma_f32_16x16x128_f8f6f4 v[230:233], v[152:159], v[222:229], v[16:19]
	v_mfma_f32_16x16x128_f8f6f4 v[234:237], v[144:151], v[222:229], v[20:23]
	v_mfma_f32_16x16x128_f8f6f4 v[44:47], v[128:135], v[168:175], v[44:47]
	v_mfma_f32_16x16x128_f8f6f4 v[238:241], v[136:143], v[168:175], v[40:43]
	v_mfma_f32_16x16x128_f8f6f4 v[242:245], v[136:143], v[176:183], v[24:27]
	v_mfma_f32_16x16x128_f8f6f4 v[176:179], v[128:135], v[176:183], v[28:31]
	v_mfma_f32_16x16x128_f8f6f4 v[180:183], v[136:143], v[204:211], v[8:11]
	v_mfma_f32_16x16x128_f8f6f4 v[204:207], v[128:135], v[204:211], v[12:15]
	v_mfma_f32_16x16x128_f8f6f4 v[208:211], v[136:143], v[222:229], v[0:3]
	v_mfma_f32_16x16x128_f8f6f4 v[222:225], v[128:135], v[222:229], v[4:7]
	s_barrier
; #define PG8_STAGE(bufoff, gbase, voff) do { _Pragma("unroll") for (int _i = 0; _i < 2; ++_i) \
;         __builtin_amdgcn_global_load_lds((const unsigned*)((const char*)(gbase) + (voff)[_i]), (LAS unsigned*)(lds + (bufoff) + ldsw + _i * 8192), 16, 0, 0); } while (0)
; #define PG8_LDA(dst, b, h) do { _Pragma("unroll") for (int m = 0; m < 4; ++m) _Pragma("unroll") for (int k = 0; k < 2; ++k) dst[m][k] = *(const LAS bf16x8*)(lds + PG8_SA(b, h) + aoff + m * 2048 + k * KOFF); } while (0)
; #define PG8_LDB(dst, b, h) do { _Pragma("unroll") for (int n = 0; n < 2; ++n) _Pragma("unroll") for (int k = 0; k < 2; ++k) dst[n][k] = *(const LAS bf16x8*)(lds + PG8_SB(b, h) + boff + n * 2048 + k * KOFF); } while (0)
; #define PG8_WAIT_V(n) asm volatile("s_waitcnt vmcnt(" #n ")" ::: "memory")
; #define PG8_WAIT_L(n) asm volatile("s_waitcnt lgkmcnt(" #n ")" ::: "memory")
; #define PG8_BAR __builtin_amdgcn_s_barrier()
; #define PG8_SCHED __builtin_amdgcn_sched_barrier(0)
; template <class Epi, bool ALIGN_EPI = true, bool FP8 = false>
; __device__ __forceinline__ void gemm_phase(LAS unsigned char* lds, const Gemm g, const StaticOrder& S, const Epi& E, const int wid) {
;     ...
;             PG8_LDB(B0, 1, 0); PG8_LDB(B1, 1, 1); PG8_SCHED; PG8_LDA(At, 1, 0); PG8_STAGE(PG8_SA(0, 1), a2 + hstep, voffA);
;             PG8_WAIT_V(8); PG8_WAIT_L(0); PG8_BAR; PG8_MMA(0, 0, At, B0); PG8_MMA(0, 1, At, B1); PG8_BAR; PG8_SCHED;
;             PG8_LDA(At, 1, 1); PG8_STAGE(PG8_SB(1, 0), b3, voffB); PG8_STAGE(PG8_SB(1, 1), b3 + hstep, voffB); PG8_STAGE(PG8_SA(1, 0), a3, voffA);
;             PG8_WAIT_V(8); PG8_WAIT_L(0); PG8_BAR; PG8_MMA(1, 0, At, B0); PG8_MMA(1, 1, At, B1); PG8_BAR; PG8_SCHED;
;         }
	s_setprio 0
	s_add_i32 s42, 0, 0x18000
	s_add_i32 s43, 0, 0x1c000
	s_nop 0
	v_add_u32_e32 v12, s42, v217
	v_add_u32_e32 v16, s43, v217
	ds_read_b128 v[0:3], v12
	ds_read_b128 v[4:7], v12 offset:1024
	ds_read_b128 v[8:11], v12 offset:2048
	ds_read_b128 v[12:15], v12 offset:3072
	ds_read_b128 v[128:131], v16
	ds_read_b128 v[132:135], v16 offset:1024
	ds_read_b128 v[136:139], v16 offset:2048
	ds_read_b128 v[140:143], v16 offset:3072
	s_add_u32 s38, s38, 0x40000
	s_addc_u32 s39, s39, 0
	s_mov_b32 m0, s64
	v_lshl_add_u64 v[152:153], s[38:39], 0, v[190:191]
	ds_read_b128 v[16:19], v220 offset:32768
	ds_read_b128 v[20:23], v220 offset:33792
	ds_read_b128 v[24:27], v220 offset:34816
	ds_read_b128 v[28:31], v220 offset:35840
	ds_read_b128 v[36:39], v220 offset:36864
	ds_read_b128 v[40:43], v220 offset:37888
	ds_read_b128 v[144:147], v220 offset:38912
	ds_read_b128 v[148:151], v220 offset:39936
	global_load_lds_dwordx4 v[152:153], off
	v_lshl_add_u64 v[152:153], s[38:39], 0, v[186:187]
	s_mov_b32 m0, s65
	s_nop 0
	global_load_lds_dwordx4 v[152:153], off
	s_setprio 1
	s_waitcnt vmcnt(8) lgkmcnt(0)
	s_barrier
	v_mfma_f32_16x16x128_f8f6f4 v[120:123], v[0:7], v[16:23], v[120:123]
	v_mfma_f32_16x16x128_f8f6f4 v[124:127], v[8:15], v[16:23], v[124:127]
	v_mfma_f32_16x16x128_f8f6f4 v[104:107], v[0:7], v[24:31], v[104:107]
	v_mfma_f32_16x16x128_f8f6f4 v[108:111], v[8:15], v[24:31], v[108:111]
	v_mfma_f32_16x16x128_f8f6f4 v[96:99], v[0:7], v[36:43], v[96:99]
	v_mfma_f32_16x16x128_f8f6f4 v[100:103], v[8:15], v[36:43], v[100:103]
	v_mfma_f32_16x16x128_f8f6f4 v[80:83], v[0:7], v[144:151], v[80:83]
	v_mfma_f32_16x16x128_f8f6f4 v[84:87], v[8:15], v[144:151], v[84:87]
	v_mfma_f32_16x16x128_f8f6f4 v[112:115], v[128:135], v[16:23], v[112:115]
	v_mfma_f32_16x16x128_f8f6f4 v[116:119], v[136:143], v[16:23], v[116:119]
	v_mfma_f32_16x16x128_f8f6f4 v[88:91], v[128:135], v[24:31], v[88:91]
	v_mfma_f32_16x16x128_f8f6f4 v[92:95], v[136:143], v[24:31], v[92:95]
	v_mfma_f32_16x16x128_f8f6f4 v[72:75], v[128:135], v[36:43], v[72:75]
	v_mfma_f32_16x16x128_f8f6f4 v[76:79], v[136:143], v[36:43], v[76:79]
	v_mfma_f32_16x16x128_f8f6f4 v[64:67], v[128:135], v[144:151], v[64:67]
	v_mfma_f32_16x16x128_f8f6f4 v[68:71], v[136:143], v[144:151], v[68:71]
	s_barrier
	s_setprio 0
	s_add_i32 s38, s42, s53
	v_lshl_add_u64 v[16:17], v[160:161], 0, s[14:15]
	s_mov_b32 m0, s38
	ds_read_b128 v[24:27], v220 offset:49152
	ds_read_b128 v[28:31], v220 offset:50176
	ds_read_b128 v[144:147], v220 offset:51200
	ds_read_b128 v[148:151], v220 offset:52224
	ds_read_b128 v[152:155], v220 offset:53248
	ds_read_b128 v[156:159], v220 offset:54272
	ds_read_b128 v[168:171], v220 offset:55296
	ds_read_b128 v[172:175], v220 offset:56320
	global_load_lds_dwordx4 v[16:17], off
	s_add_i32 m0, s38, 0x2000
	s_add_u32 s36, s36, 0x40080
	v_lshl_add_u64 v[16:17], v[162:163], 0, s[14:15]
	s_addc_u32 s37, s37, 0
	s_add_i32 s38, s43, s53
	global_load_lds_dwordx4 v[16:17], off
	v_lshl_add_u64 v[16:17], s[36:37], 0, v[188:189]
	s_mov_b32 m0, s38
	s_nop 0
	global_load_lds_dwordx4 v[16:17], off
	v_lshl_add_u64 v[16:17], s[36:37], 0, v[184:185]
	s_add_i32 m0, s38, 0x2000
	s_nop 0
	global_load_lds_dwordx4 v[16:17], off
	v_lshl_add_u64 v[16:17], v[164:165], 0, s[14:15]
	s_mov_b32 m0, s71
	s_nop 0
	global_load_lds_dwordx4 v[16:17], off
	v_lshl_add_u64 v[16:17], v[166:167], 0, s[14:15]
	s_mov_b32 m0, s72
	s_nop 0
	global_load_lds_dwordx4 v[16:17], off
	s_setprio 1
	s_waitcnt vmcnt(8) lgkmcnt(0)
	s_barrier
	v_mfma_f32_16x16x128_f8f6f4 v[56:59], v[0:7], v[24:31], v[56:59]
	v_mfma_f32_16x16x128_f8f6f4 v[60:63], v[8:15], v[24:31], v[60:63]
	v_mfma_f32_16x16x128_f8f6f4 v[48:51], v[0:7], v[144:151], v[48:51]
	v_mfma_f32_16x16x128_f8f6f4 v[52:55], v[8:15], v[144:151], v[52:55]
	v_mfma_f32_16x16x128_f8f6f4 v[32:35], v[0:7], v[152:159], v[32:35]
	v_mfma_f32_16x16x128_f8f6f4 v[36:39], v[8:15], v[152:159], v[212:215]
	v_mfma_f32_16x16x128_f8f6f4 v[16:19], v[0:7], v[168:175], v[230:233]
	v_mfma_f32_16x16x128_f8f6f4 v[20:23], v[8:15], v[168:175], v[234:237]
	v_mfma_f32_16x16x128_f8f6f4 v[40:43], v[128:135], v[24:31], v[238:241]
	v_mfma_f32_16x16x128_f8f6f4 v[44:47], v[136:143], v[24:31], v[44:47]
	v_mfma_f32_16x16x128_f8f6f4 v[24:27], v[128:135], v[144:151], v[242:245]
	v_mfma_f32_16x16x128_f8f6f4 v[28:31], v[136:143], v[144:151], v[176:179]
	v_mfma_f32_16x16x128_f8f6f4 v[8:11], v[128:135], v[152:159], v[180:183]
	v_mfma_f32_16x16x128_f8f6f4 v[12:15], v[136:143], v[152:159], v[204:207]
	v_mfma_f32_16x16x128_f8f6f4 v[0:3], v[128:135], v[168:175], v[208:211]
	v_mfma_f32_16x16x128_f8f6f4 v[4:7], v[136:143], v[168:175], v[222:225]
	s_barrier
	s_setprio 0
	s_add_u32 s34, s34, 0x100
	s_addc_u32 s35, s35, 0
	s_add_u32 s89, s89, 0x100
	s_addc_u32 s90, s90, 0
	s_cmp_ge_u32 s3, s29
	s_mov_b32 s38, s3
	s_cbranch_scc0 .LBB0_2290
	s_and_b64 vcc, exec, s[12:13]
	s_cbranch_vccz .LBB0_2293
	s_barrier

; #define PG8_BAR __builtin_amdgcn_s_barrier()
; template <class Epi, bool ALIGN_EPI = true, bool FP8 = false>
; __device__ __forceinline__ void gemm_phase(LAS unsigned char* lds, const Gemm g, const StaticOrder& S, const Epi& E, const int wid) {
;     ...
;         if (!has_next) break;
; #pragma unroll
;         for (int a = 0; a < 2; ++a)
; #pragma unroll
;             for (int b = 0; b < 2; ++b)
; #pragma unroll
;                 for (int m = 0; m < 4; ++m) {
;                     if (!keep) { acc[a][b][m][0] = (f32x4){0.f, 0.f, 0.f, 0.f}; acc[a][b][m][1] = (f32x4){0.f, 0.f, 0.f, 0.f}; }
;                     if constexpr (FP8) acc8[a][b][m] = __builtin_shufflevector(acc[a][b][m][0], acc[a][b][m][1], 0, 1, 2, 3, 4, 5, 6, 7); }
;         cur = nxt; cA = nA; cB = nB; ++ui;
;         if constexpr (ALIGN_EPI) { if (wr == 1) PG8_BAR; }
.LBB0_2296:
	s_andn2_b64 vcc, exec, s[4:5]
	s_mov_b64 s[4:5], -1
	s_cbranch_vccnz .LBB0_2284
	s_andn2_b64 vcc, exec, s[8:9]
	s_cbranch_vccnz .LBB0_2283
	s_mov_b32 s100, 1
	s_branch .LBB0_2283

; #define PG8_BAR __builtin_amdgcn_s_barrier()
;     __device__ __forceinline__ bool next(int i, Unit& u) const {
;         const bool hm = c < nmini, mini = hm && i == 0;
;         int j = i - (hm ? 1 : 0); j = j < 0 ? 0 : j;
;         const int ip = j >> pair;
;         const bool sk = skew > 0 && ip >= nfull;
;         const long L = sk ? (long)nfull * G + (long)(ip - nfull) * (G - skew) + (c - skew) : (long)ip * G + c; const bool ok = L < nwg && (!sk || c >= skew);
;         int wgid = ok ? (int)L : 0; { const int q = nwg / NXCD, r = nwg % NXCD, xcd = wgid % NXCD, off = wgid / NXCD; wgid = (xcd < r ? xcd * (q + 1) : r * (q + 1) + (xcd - r) * q) + off; }
;         const int nig = WGM * nN, gid = wgid / nig, fm = gid * WGM, gsz = (nM - fm) < WGM ? (nM - fm) : WGM;
;         const int fpm = fm + ((wgid % nig) % gsz), fpn = (wgid % nig) / gsz;
;         const int ns = nsplit > 0 ? nsplit : 1, t = c / ns, ks = c - t * ns, mpm = mini_pm0 + t / nN, mpn = t % nN;
;         u.pm = __builtin_amdgcn_readfirstlane(mini ? mpm : fpm); u.pn = __builtin_amdgcn_readfirstlane(mini ? mpn : fpn);
;         const int kh = mini_pair ? ns / 2 : ns, msub = mini_pair ? ks / kh : 0, mk = ks - msub * kh;
;         u.sub = __builtin_amdgcn_readfirstlane(mini ? msub : (j & ((1 << pair) - 1))); u.kt0 = __builtin_amdgcn_readfirstlane(mini ? mk * mini_nkt : 0); u.nkt = mini ? mini_nkt : nkt_full; u.part = mini ? 1 + ks : 0;
; template <class Epi, bool ALIGN_EPI = true, bool FP8 = false>
; __device__ __forceinline__ void gemm_phase(LAS unsigned char* lds, const Gemm g, const StaticOrder& S, const Epi& E, const int wid) {
;     ...
; #pragma unroll
;         for (int a = 0; a < 2; ++a)
; #pragma unroll
;             for (int b = 0; b < 2; ++b)
; #pragma unroll
;                 for (int m = 0; m < 4; ++m) {
;                     if (!keep) { acc[a][b][m][0] = (f32x4){0.f, 0.f, 0.f, 0.f}; acc[a][b][m][1] = (f32x4){0.f, 0.f, 0.f, 0.f}; }
;                     if constexpr (FP8) acc8[a][b][m] = __builtin_shufflevector(acc[a][b][m][0], acc[a][b][m][1], 0, 1, 2, 3, 4, 5, 6, 7); }
;         cur = nxt; cA = nA; cB = nB; ++ui;
;         if constexpr (ALIGN_EPI) { if (wr == 1) PG8_BAR; }
.LBB0_2450:
	s_add_i32 s74, s74, 1
	s_add_i32 s3, s74, s50
	s_mul_i32 s4, s3, s51
	s_mul_hi_u32 s5, s3, s33
	s_add_i32 s5, s5, s4
	s_mul_i32 s3, s3, s33
	s_add_u32 s16, s3, s2
	s_addc_u32 s17, s5, s50
	v_cmp_lt_i64_e64 s[4:5], s[16:17], v[142:143]
	s_and_b64 s[18:19], s[4:5], exec
	s_cselect_b32 s3, s16, 0
	s_ashr_i32 s16, s3, 31
	s_lshr_b32 s16, s16, 29
	s_add_i32 s16, s3, s16
	s_ashr_i32 s17, s16, 3
	s_and_b32 s16, s16, -8
	s_sub_i32 s3, s3, s16
	s_cmp_lt_i32 s3, 0
	s_cselect_b32 s16, s64, 0x2cb
	s_mul_i32 s3, s3, s16
	s_add_i32 s3, s3, s17
	s_mul_hi_i32 s16, s3, 0x2e8ba2e9
	s_lshr_b32 s17, s16, 31
	s_ashr_i32 s16, s16, 5
	s_add_i32 s16, s16, s17
	s_lshl_b32 s17, s16, 2
	s_sub_i32 s18, 0x82, s17
	s_min_i32 s18, s18, 4
	s_abs_i32 s19, s18
	v_cvt_f32_u32_e32 v0, s19
	s_sub_i32 s21, 0, s19
	s_mulk_i32 s16, 0xb0
	s_sub_i32 s3, s3, s16
	v_rcp_iflag_f32_e32 v0, v0
	s_abs_i32 s20, s3
	s_xor_b32 s16, s3, s18
	s_ashr_i32 s16, s16, 31
	v_mul_f32_e32 v0, 0x4f7ffffe, v0
	v_cvt_u32_f32_e32 v0, v0
	s_nop 0
	v_readfirstlane_b32 s22, v0
	s_mul_i32 s21, s21, s22
	s_mul_hi_u32 s21, s22, s21
	s_add_i32 s22, s22, s21
	s_mul_hi_u32 s21, s20, s22
	s_mul_i32 s22, s21, s19
	s_sub_i32 s20, s20, s22
	s_add_i32 s22, s21, 1
	s_sub_i32 s23, s20, s19
	s_cmp_ge_u32 s20, s19
	s_cselect_b32 s21, s22, s21
	s_cselect_b32 s20, s23, s20
	s_add_i32 s22, s21, 1
	s_cmp_ge_u32 s20, s19
	s_cselect_b32 s19, s22, s21
	s_xor_b32 s19, s19, s16
	s_sub_i32 s16, s19, s16
	s_mul_i32 s18, s16, s18
	s_sub_i32 s3, s3, s18
	s_add_i32 s18, s17, s3
	s_ashr_i32 s19, s18, 31
	s_lshl_b64 s[20:21], s[18:19], 20
	s_add_u32 s20, s56, s20
	s_addc_u32 s21, s57, s21
	s_ashr_i32 s17, s16, 31
	s_lshl_b64 s[22:23], s[16:17], 20
	s_add_u32 s22, s36, s22
	s_addc_u32 s23, s37, s23
	s_cmp_eq_u32 s54, 0
	s_cbranch_scc1 .LBB0_2458
	s_and_b64 s[34:35], s[4:5], exec
	s_cselect_b32 s3, s21, s29
	s_cselect_b32 s17, s20, s28
	s_cselect_b32 s19, s23, s31
	s_cselect_b32 s42, s22, s30
	s_add_i32 s43, s54, -2
	s_add_u32 s28, s28, 0x80080
	s_addc_u32 s29, s29, 0
	s_add_u32 s52, s30, 0x100
	v_mov_b32_e32 v0, 0
	s_addc_u32 s75, s31, 0
	s_mov_b32 s30, 0
	v_mov_b32_e32 v1, v0
	v_mov_b32_e32 v2, v0
	v_mov_b32_e32 v3, v0
	v_mov_b32_e32 v8, v0
	v_mov_b32_e32 v9, v0
	v_mov_b32_e32 v10, v0
	v_mov_b32_e32 v11, v0
	v_mov_b32_e32 v16, v0
	v_mov_b32_e32 v17, v0
	v_mov_b32_e32 v18, v0
	v_mov_b32_e32 v19, v0
	v_mov_b32_e32 v24, v0
	v_mov_b32_e32 v25, v0
	v_mov_b32_e32 v26, v0
	v_mov_b32_e32 v27, v0
	v_mov_b32_e32 v32, v0
	s_waitcnt lgkmcnt(0)
	v_mov_b32_e32 v33, v0
	v_mov_b32_e32 v34, v0
	v_mov_b32_e32 v35, v0
	v_mov_b32_e32 v40, v0
	v_mov_b32_e32 v41, v0
	v_mov_b32_e32 v42, v0
	v_mov_b32_e32 v43, v0
	v_mov_b32_e32 v48, v0
	v_mov_b32_e32 v49, v0
	v_mov_b32_e32 v50, v0
	v_mov_b32_e32 v51, v0
	v_mov_b32_e32 v56, v0
	v_mov_b32_e32 v57, v0
	v_mov_b32_e32 v58, v0
	v_mov_b32_e32 v59, v0
	v_mov_b32_e32 v4, v0
	v_mov_b32_e32 v5, v0
	v_mov_b32_e32 v6, v0
	v_mov_b32_e32 v7, v0
	v_mov_b32_e32 v12, v0
	v_mov_b32_e32 v13, v0
	v_mov_b32_e32 v14, v0
	v_mov_b32_e32 v15, v0
	v_mov_b32_e32 v20, v0
	v_mov_b32_e32 v21, v0
	v_mov_b32_e32 v22, v0
	v_mov_b32_e32 v23, v0
	v_mov_b32_e32 v28, v0
	v_mov_b32_e32 v29, v0
	v_mov_b32_e32 v30, v0
	v_mov_b32_e32 v31, v0
	v_mov_b32_e32 v36, v0
	v_mov_b32_e32 v37, v0
	v_mov_b32_e32 v38, v0
	v_mov_b32_e32 v39, v0
	v_mov_b32_e32 v44, v0
	v_mov_b32_e32 v45, v0
	v_mov_b32_e32 v46, v0
	v_mov_b32_e32 v47, v0
	v_mov_b32_e32 v52, v0
	v_mov_b32_e32 v53, v0
	v_mov_b32_e32 v54, v0
	v_mov_b32_e32 v55, v0
	v_mov_b32_e32 v60, v0
	v_mov_b32_e32 v61, v0
	v_mov_b32_e32 v62, v0
	v_mov_b32_e32 v63, v0
	v_mov_b32_e32 v64, v0
	v_mov_b32_e32 v65, v0
	v_mov_b32_e32 v66, v0
	v_mov_b32_e32 v67, v0
	v_mov_b32_e32 v72, v0
	v_mov_b32_e32 v73, v0
	v_mov_b32_e32 v74, v0
	v_mov_b32_e32 v75, v0
	v_mov_b32_e32 v80, v0
	v_mov_b32_e32 v81, v0
	v_mov_b32_e32 v82, v0
	v_mov_b32_e32 v83, v0
	v_mov_b32_e32 v88, v0
	v_mov_b32_e32 v89, v0
	v_mov_b32_e32 v90, v0
	v_mov_b32_e32 v91, v0
	v_mov_b32_e32 v96, v0
	v_mov_b32_e32 v97, v0
	v_mov_b32_e32 v98, v0
	v_mov_b32_e32 v99, v0
	v_mov_b32_e32 v104, v0
	v_mov_b32_e32 v105, v0
	v_mov_b32_e32 v106, v0
	v_mov_b32_e32 v107, v0
	v_mov_b32_e32 v112, v0
	v_mov_b32_e32 v113, v0
	v_mov_b32_e32 v114, v0
	v_mov_b32_e32 v115, v0
	v_mov_b32_e32 v120, v0
	v_mov_b32_e32 v121, v0
	v_mov_b32_e32 v122, v0
	v_mov_b32_e32 v123, v0
	v_mov_b32_e32 v68, v0
	v_mov_b32_e32 v69, v0
	v_mov_b32_e32 v70, v0
	v_mov_b32_e32 v71, v0
	v_mov_b32_e32 v76, v0
	v_mov_b32_e32 v77, v0
	v_mov_b32_e32 v78, v0
	v_mov_b32_e32 v79, v0
	v_mov_b32_e32 v84, v0
	v_mov_b32_e32 v85, v0
	v_mov_b32_e32 v86, v0
	v_mov_b32_e32 v87, v0
	v_mov_b32_e32 v92, v0
	v_mov_b32_e32 v93, v0
	v_mov_b32_e32 v94, v0
	v_mov_b32_e32 v95, v0
	v_mov_b32_e32 v100, v0
	v_mov_b32_e32 v101, v0
	v_mov_b32_e32 v102, v0
	v_mov_b32_e32 v103, v0
	v_mov_b32_e32 v108, v0
	v_mov_b32_e32 v109, v0
	v_mov_b32_e32 v110, v0
	v_mov_b32_e32 v111, v0
	v_mov_b32_e32 v116, v0
	v_mov_b32_e32 v117, v0
	v_mov_b32_e32 v118, v0
	v_mov_b32_e32 v119, v0
	v_mov_b32_e32 v124, v0
	v_mov_b32_e32 v125, v0
	v_mov_b32_e32 v126, v0
	v_mov_b32_e32 v127, v0
	s_cmp_eq_u32 s100, 0
	s_cbranch_scc1 .Ldefbar_skip_7
	s_mov_b32 s100, 0
	s_barrier
; #define PG8_STAGE(bufoff, gbase, voff) do { _Pragma("unroll") for (int _i = 0; _i < 2; ++_i) \
;         __builtin_amdgcn_global_load_lds((const unsigned*)((const char*)(gbase) + (voff)[_i]), (LAS unsigned*)(lds + (bufoff) + ldsw + _i * 8192), 16, 0, 0); } while (0)
; #define PG8_LDA(dst, b, h) do { _Pragma("unroll") for (int m = 0; m < 4; ++m) _Pragma("unroll") for (int k = 0; k < 2; ++k) dst[m][k] = *(const LAS bf16x8*)(lds + PG8_SA(b, h) + aoff + m * 2048 + k * KOFF); } while (0)
; #define PG8_LDB(dst, b, h) do { _Pragma("unroll") for (int n = 0; n < 2; ++n) _Pragma("unroll") for (int k = 0; k < 2; ++k) dst[n][k] = *(const LAS bf16x8*)(lds + PG8_SB(b, h) + boff + n * 2048 + k * KOFF); } while (0)
; #define PG8_WAIT_V(n) asm volatile("s_waitcnt vmcnt(" #n ")" ::: "memory")
; #define PG8_WAIT_L(n) asm volatile("s_waitcnt lgkmcnt(" #n ")" ::: "memory")
; #define PG8_BAR __builtin_amdgcn_s_barrier()
; #define PG8_SCHED __builtin_amdgcn_sched_barrier(0)
; template <class Epi, bool ALIGN_EPI = true, bool FP8 = false>
; __device__ __forceinline__ void gemm_phase(LAS unsigned char* lds, const Gemm g, const StaticOrder& S, const Epi& E, const int wid) {
;     ...
;             const char* a1 = cA + (size_t)(t + 1) * kstep;
;             const char* a2 = last ? nA : cA + (size_t)(t + 2) * kstep; const char* b2 = last ? nB : cB + (size_t)(t + 2) * kstep;
;             const char* a3 = a2 + kstep; const char* b3 = b2 + kstep;
;             PG8_LDB(B0, 0, 0); PG8_LDB(B1, 0, 1); PG8_SCHED; PG8_LDA(At, 0, 0); PG8_STAGE(PG8_SA(1, 1), a1 + hstep, voffA);
;             PG8_WAIT_V(8); PG8_WAIT_L(0); PG8_BAR; PG8_MMA(0, 0, At, B0); PG8_MMA(0, 1, At, B1); PG8_BAR; PG8_SCHED;
;             PG8_LDA(At, 0, 1); PG8_STAGE(PG8_SB(0, 0), b2, voffB); PG8_STAGE(PG8_SB(0, 1), b2 + hstep, voffB); PG8_STAGE(PG8_SA(0, 0), a2, voffA);
;             PG8_WAIT_V(8); PG8_WAIT_L(0); PG8_BAR; PG8_MMA(1, 0, At, B0); PG8_MMA(1, 1, At, B1); PG8_BAR; PG8_SCHED;
.Ldefbar_skip_7:
.LBB0_2452:
	ds_read_b128 v[152:155], v148
	ds_read_b128 v[156:159], v148 offset:1024
	ds_read_b128 v[160:163], v148 offset:2048
	ds_read_b128 v[164:167], v148 offset:3072
	ds_read_b128 v[168:171], v149
	ds_read_b128 v[172:175], v149 offset:1024
	ds_read_b128 v[176:179], v149 offset:2048
	ds_read_b128 v[180:183], v149 offset:3072
	s_add_i32 s76, s30, 2
	s_add_u32 s31, s28, 0xfff80080
	s_addc_u32 s34, s29, -1
	s_cmp_eq_u32 s43, s30
	s_cselect_b32 s30, s42, s52
	s_cselect_b32 s35, s3, s34
	s_cselect_b32 s34, s17, s31
	s_cselect_b32 s31, s19, s75
	v_lshl_add_u64 v[144:145], s[28:29], 0, v[138:139]
	s_add_i32 m0, s25, 0xc000
	ds_read_b128 v[184:187], v150
	ds_read_b128 v[188:191], v150 offset:1024
	ds_read_b128 v[192:195], v150 offset:2048
	ds_read_b128 v[196:199], v150 offset:3072
	ds_read_b128 v[200:203], v150 offset:4096
	ds_read_b128 v[204:207], v150 offset:5120
	ds_read_b128 v[208:211], v150 offset:6144
	ds_read_b128 v[212:215], v150 offset:7168
	global_load_lds_dwordx4 v[144:145], off
	v_lshl_add_u64 v[144:145], s[28:29], 0, v[140:141]
	s_add_i32 m0, s25, 0xe000
	s_nop 0
	global_load_lds_dwordx4 v[144:145], off
	s_setprio 1
	s_waitcnt vmcnt(8) lgkmcnt(0)
	s_barrier
	v_mfma_f32_16x16x32_bf16 v[124:127], v[152:155], v[184:187], v[124:127]
	v_mfma_f32_16x16x32_bf16 v[116:119], v[160:163], v[184:187], v[116:119]
	v_mfma_f32_16x16x32_bf16 v[108:111], v[152:155], v[192:195], v[108:111]
	v_mfma_f32_16x16x32_bf16 v[100:103], v[160:163], v[192:195], v[100:103]
	v_mfma_f32_16x16x32_bf16 v[92:95], v[152:155], v[200:203], v[92:95]
	v_mfma_f32_16x16x32_bf16 v[84:87], v[160:163], v[200:203], v[84:87]
	v_mfma_f32_16x16x32_bf16 v[76:79], v[152:155], v[208:211], v[76:79]
	v_mfma_f32_16x16x32_bf16 v[68:71], v[160:163], v[208:211], v[68:71]
	v_mfma_f32_16x16x32_bf16 v[124:127], v[156:159], v[188:191], v[124:127]
	v_mfma_f32_16x16x32_bf16 v[116:119], v[164:167], v[188:191], v[116:119]
	v_mfma_f32_16x16x32_bf16 v[108:111], v[156:159], v[196:199], v[108:111]
	v_mfma_f32_16x16x32_bf16 v[100:103], v[164:167], v[196:199], v[100:103]
	v_mfma_f32_16x16x32_bf16 v[92:95], v[156:159], v[204:207], v[92:95]
	v_mfma_f32_16x16x32_bf16 v[84:87], v[164:167], v[204:207], v[84:87]
	v_mfma_f32_16x16x32_bf16 v[76:79], v[156:159], v[212:215], v[76:79]
	v_mfma_f32_16x16x32_bf16 v[68:71], v[164:167], v[212:215], v[68:71]
	v_mfma_f32_16x16x32_bf16 v[120:123], v[168:171], v[184:187], v[120:123]
	v_mfma_f32_16x16x32_bf16 v[112:115], v[176:179], v[184:187], v[112:115]
	v_mfma_f32_16x16x32_bf16 v[104:107], v[168:171], v[192:195], v[104:107]
	v_mfma_f32_16x16x32_bf16 v[96:99], v[176:179], v[192:195], v[96:99]
	v_mfma_f32_16x16x32_bf16 v[88:91], v[168:171], v[200:203], v[88:91]
	v_mfma_f32_16x16x32_bf16 v[80:83], v[176:179], v[200:203], v[80:83]
	v_mfma_f32_16x16x32_bf16 v[72:75], v[168:171], v[208:211], v[72:75]
	v_mfma_f32_16x16x32_bf16 v[64:67], v[176:179], v[208:211], v[64:67]
	v_mfma_f32_16x16x32_bf16 v[120:123], v[172:175], v[188:191], v[120:123]
	v_mfma_f32_16x16x32_bf16 v[112:115], v[180:183], v[188:191], v[112:115]
	v_mfma_f32_16x16x32_bf16 v[104:107], v[172:175], v[196:199], v[104:107]
	v_mfma_f32_16x16x32_bf16 v[96:99], v[180:183], v[196:199], v[96:99]
	v_mfma_f32_16x16x32_bf16 v[88:91], v[172:175], v[204:207], v[88:91]
	v_mfma_f32_16x16x32_bf16 v[80:83], v[180:183], v[204:207], v[80:83]
	v_mfma_f32_16x16x32_bf16 v[72:75], v[172:175], v[212:215], v[72:75]
	v_mfma_f32_16x16x32_bf16 v[64:67], v[180:183], v[212:215], v[64:67]
	s_barrier
	s_setprio 0
	s_add_i32 s77, s65, s38
	v_lshl_add_u64 v[144:145], s[30:31], 0, v[132:133]
	s_mov_b32 m0, s77
	ds_read_b128 v[184:187], v150 offset:16384
	ds_read_b128 v[188:191], v150 offset:17408
	ds_read_b128 v[192:195], v150 offset:18432
	ds_read_b128 v[196:199], v150 offset:19456
	ds_read_b128 v[200:203], v150 offset:20480
	ds_read_b128 v[204:207], v150 offset:21504
	ds_read_b128 v[208:211], v150 offset:22528
	ds_read_b128 v[212:215], v150 offset:23552
	global_load_lds_dwordx4 v[144:145], off
	s_add_i32 m0, s77, 0x2000
	s_add_u32 s78, s30, 0x80000
	v_lshl_add_u64 v[216:217], s[30:31], 0, v[128:129]
	s_addc_u32 s79, s31, 0
	s_add_i32 s77, s66, s38
	global_load_lds_dwordx4 v[216:217], off
	v_lshl_add_u64 v[218:219], s[78:79], 0, v[132:133]
	s_mov_b32 m0, s77
	v_lshl_add_u64 v[220:221], s[34:35], 0, v[130:131]
	global_load_lds_dwordx4 v[218:219], off
	v_lshl_add_u64 v[218:219], s[78:79], 0, v[128:129]
	s_add_i32 m0, s77, 0x2000
	s_nop 0
	global_load_lds_dwordx4 v[218:219], off
	v_lshl_add_u64 v[218:219], s[34:35], 0, v[134:135]
	s_mov_b32 m0, s25
	s_nop 0
	global_load_lds_dwordx4 v[218:219], off
	s_mov_b32 m0, s27
	s_nop 0
	global_load_lds_dwordx4 v[220:221], off
	s_setprio 1
	s_waitcnt vmcnt(8) lgkmcnt(0)
	s_barrier
; #define PG8_STAGE(bufoff, gbase, voff) do { _Pragma("unroll") for (int _i = 0; _i < 2; ++_i) \
;         __builtin_amdgcn_global_load_lds((const unsigned*)((const char*)(gbase) + (voff)[_i]), (LAS unsigned*)(lds + (bufoff) + ldsw + _i * 8192), 16, 0, 0); } while (0)
; #define PG8_LDA(dst, b, h) do { _Pragma("unroll") for (int m = 0; m < 4; ++m) _Pragma("unroll") for (int k = 0; k < 2; ++k) dst[m][k] = *(const LAS bf16x8*)(lds + PG8_SA(b, h) + aoff + m * 2048 + k * KOFF); } while (0)
; #define PG8_LDB(dst, b, h) do { _Pragma("unroll") for (int n = 0; n < 2; ++n) _Pragma("unroll") for (int k = 0; k < 2; ++k) dst[n][k] = *(const LAS bf16x8*)(lds + PG8_SB(b, h) + boff + n * 2048 + k * KOFF); } while (0)
; #define PG8_WAIT_V(n) asm volatile("s_waitcnt vmcnt(" #n ")" ::: "memory")
; #define PG8_WAIT_L(n) asm volatile("s_waitcnt lgkmcnt(" #n ")" ::: "memory")
; #define PG8_BAR __builtin_amdgcn_s_barrier()
; #define PG8_SCHED __builtin_amdgcn_sched_barrier(0)
; template <class Epi, bool ALIGN_EPI = true, bool FP8 = false>
; __device__ __forceinline__ void gemm_phase(LAS unsigned char* lds, const Gemm g, const StaticOrder& S, const Epi& E, const int wid) {
;     ...
;             PG8_WAIT_V(8); PG8_WAIT_L(0); PG8_BAR; PG8_MMA(1, 0, At, B0); PG8_MMA(1, 1, At, B1); PG8_BAR; PG8_SCHED;
;             PG8_LDB(B0, 1, 0); PG8_LDB(B1, 1, 1); PG8_SCHED; PG8_LDA(At, 1, 0); PG8_STAGE(PG8_SA(0, 1), a2 + hstep, voffA);
;             PG8_WAIT_V(8); PG8_WAIT_L(0); PG8_BAR; PG8_MMA(0, 0, At, B0); PG8_MMA(0, 1, At, B1); PG8_BAR; PG8_SCHED;
	v_mfma_f32_16x16x32_bf16 v[60:63], v[152:155], v[184:187], v[60:63]
	v_mfma_f32_16x16x32_bf16 v[52:55], v[160:163], v[184:187], v[52:55]
	v_mfma_f32_16x16x32_bf16 v[44:47], v[152:155], v[192:195], v[44:47]
	v_mfma_f32_16x16x32_bf16 v[36:39], v[160:163], v[192:195], v[36:39]
	v_mfma_f32_16x16x32_bf16 v[28:31], v[152:155], v[200:203], v[28:31]
	v_mfma_f32_16x16x32_bf16 v[20:23], v[160:163], v[200:203], v[20:23]
	v_mfma_f32_16x16x32_bf16 v[12:15], v[152:155], v[208:211], v[12:15]
	v_mfma_f32_16x16x32_bf16 v[4:7], v[160:163], v[208:211], v[4:7]
	v_mfma_f32_16x16x32_bf16 v[60:63], v[156:159], v[188:191], v[60:63]
	v_mfma_f32_16x16x32_bf16 v[52:55], v[164:167], v[188:191], v[52:55]
	v_mfma_f32_16x16x32_bf16 v[44:47], v[156:159], v[196:199], v[44:47]
	v_mfma_f32_16x16x32_bf16 v[36:39], v[164:167], v[196:199], v[36:39]
	v_mfma_f32_16x16x32_bf16 v[28:31], v[156:159], v[204:207], v[28:31]
	v_mfma_f32_16x16x32_bf16 v[20:23], v[164:167], v[204:207], v[20:23]
	v_mfma_f32_16x16x32_bf16 v[12:15], v[156:159], v[212:215], v[12:15]
	v_mfma_f32_16x16x32_bf16 v[4:7], v[164:167], v[212:215], v[4:7]
	v_mfma_f32_16x16x32_bf16 v[56:59], v[168:171], v[184:187], v[56:59]
	v_mfma_f32_16x16x32_bf16 v[48:51], v[176:179], v[184:187], v[48:51]
	v_mfma_f32_16x16x32_bf16 v[40:43], v[168:171], v[192:195], v[40:43]
	v_mfma_f32_16x16x32_bf16 v[32:35], v[176:179], v[192:195], v[32:35]
	v_mfma_f32_16x16x32_bf16 v[24:27], v[168:171], v[200:203], v[24:27]
	v_mfma_f32_16x16x32_bf16 v[16:19], v[176:179], v[200:203], v[16:19]
	v_mfma_f32_16x16x32_bf16 v[8:11], v[168:171], v[208:211], v[8:11]
	v_mfma_f32_16x16x32_bf16 v[0:3], v[176:179], v[208:211], v[0:3]
	v_mfma_f32_16x16x32_bf16 v[56:59], v[172:175], v[188:191], v[56:59]
	v_mfma_f32_16x16x32_bf16 v[48:51], v[180:183], v[188:191], v[48:51]
	v_mfma_f32_16x16x32_bf16 v[40:43], v[172:175], v[196:199], v[40:43]
	v_mfma_f32_16x16x32_bf16 v[32:35], v[180:183], v[196:199], v[32:35]
	v_mfma_f32_16x16x32_bf16 v[24:27], v[172:175], v[204:207], v[24:27]
	v_mfma_f32_16x16x32_bf16 v[16:19], v[180:183], v[204:207], v[16:19]
	v_mfma_f32_16x16x32_bf16 v[8:11], v[172:175], v[212:215], v[8:11]
	v_mfma_f32_16x16x32_bf16 v[0:3], v[180:183], v[212:215], v[0:3]
	s_barrier
	s_setprio 0
	s_add_i32 s77, 0, 0x18000
	s_add_i32 s78, 0, 0x1c000
	v_add_u32_e32 v164, s77, v147
	v_add_u32_e32 v180, s78, v147
	ds_read_b128 v[152:155], v164
	ds_read_b128 v[156:159], v164 offset:1024
	ds_read_b128 v[160:163], v164 offset:2048
	ds_read_b128 v[164:167], v164 offset:3072
	ds_read_b128 v[168:171], v180
	ds_read_b128 v[172:175], v180 offset:1024
	ds_read_b128 v[176:179], v180 offset:2048
	ds_read_b128 v[180:183], v180 offset:3072
	s_add_u32 s34, s34, 0x80000
	s_addc_u32 s35, s35, 0
	s_mov_b32 m0, s39
	v_lshl_add_u64 v[222:223], s[34:35], 0, v[134:135]
	ds_read_b128 v[184:187], v150 offset:32768
	ds_read_b128 v[188:191], v150 offset:33792
	ds_read_b128 v[192:195], v150 offset:34816
	ds_read_b128 v[196:199], v150 offset:35840
	ds_read_b128 v[200:203], v150 offset:36864
	ds_read_b128 v[204:207], v150 offset:37888
	ds_read_b128 v[208:211], v150 offset:38912
	ds_read_b128 v[212:215], v150 offset:39936
	global_load_lds_dwordx4 v[222:223], off
	v_lshl_add_u64 v[222:223], s[34:35], 0, v[130:131]
	s_mov_b32 m0, s48
	s_nop 0
	global_load_lds_dwordx4 v[222:223], off
	s_setprio 1
	s_waitcnt vmcnt(8) lgkmcnt(0)
	s_barrier
	v_mfma_f32_16x16x32_bf16 v[124:127], v[152:155], v[184:187], v[124:127]
	v_mfma_f32_16x16x32_bf16 v[116:119], v[160:163], v[184:187], v[116:119]
	v_mfma_f32_16x16x32_bf16 v[108:111], v[152:155], v[192:195], v[108:111]
	v_mfma_f32_16x16x32_bf16 v[100:103], v[160:163], v[192:195], v[100:103]
	v_mfma_f32_16x16x32_bf16 v[92:95], v[152:155], v[200:203], v[92:95]
	v_mfma_f32_16x16x32_bf16 v[84:87], v[160:163], v[200:203], v[84:87]
	v_mfma_f32_16x16x32_bf16 v[76:79], v[152:155], v[208:211], v[76:79]
	v_mfma_f32_16x16x32_bf16 v[68:71], v[160:163], v[208:211], v[68:71]
	v_mfma_f32_16x16x32_bf16 v[124:127], v[156:159], v[188:191], v[124:127]
	v_mfma_f32_16x16x32_bf16 v[116:119], v[164:167], v[188:191], v[116:119]
	v_mfma_f32_16x16x32_bf16 v[108:111], v[156:159], v[196:199], v[108:111]
	v_mfma_f32_16x16x32_bf16 v[100:103], v[164:167], v[196:199], v[100:103]
	v_mfma_f32_16x16x32_bf16 v[92:95], v[156:159], v[204:207], v[92:95]
	v_mfma_f32_16x16x32_bf16 v[84:87], v[164:167], v[204:207], v[84:87]
	v_mfma_f32_16x16x32_bf16 v[76:79], v[156:159], v[212:215], v[76:79]
	v_mfma_f32_16x16x32_bf16 v[68:71], v[164:167], v[212:215], v[68:71]
	v_mfma_f32_16x16x32_bf16 v[120:123], v[168:171], v[184:187], v[120:123]
	v_mfma_f32_16x16x32_bf16 v[112:115], v[176:179], v[184:187], v[112:115]
	v_mfma_f32_16x16x32_bf16 v[104:107], v[168:171], v[192:195], v[104:107]
	v_mfma_f32_16x16x32_bf16 v[96:99], v[176:179], v[192:195], v[96:99]
	v_mfma_f32_16x16x32_bf16 v[88:91], v[168:171], v[200:203], v[88:91]
	v_mfma_f32_16x16x32_bf16 v[80:83], v[176:179], v[200:203], v[80:83]
	v_mfma_f32_16x16x32_bf16 v[72:75], v[168:171], v[208:211], v[72:75]
	v_mfma_f32_16x16x32_bf16 v[64:67], v[176:179], v[208:211], v[64:67]
	v_mfma_f32_16x16x32_bf16 v[120:123], v[172:175], v[188:191], v[120:123]
	v_mfma_f32_16x16x32_bf16 v[112:115], v[180:183], v[188:191], v[112:115]
	v_mfma_f32_16x16x32_bf16 v[104:107], v[172:175], v[196:199], v[104:107]
	v_mfma_f32_16x16x32_bf16 v[96:99], v[180:183], v[196:199], v[96:99]
	v_mfma_f32_16x16x32_bf16 v[88:91], v[172:175], v[204:207], v[88:91]
	v_mfma_f32_16x16x32_bf16 v[80:83], v[180:183], v[204:207], v[80:83]
	v_mfma_f32_16x16x32_bf16 v[72:75], v[172:175], v[212:215], v[72:75]
	v_mfma_f32_16x16x32_bf16 v[64:67], v[180:183], v[212:215], v[64:67]
	s_barrier
; #define PG8_STAGE(bufoff, gbase, voff) do { _Pragma("unroll") for (int _i = 0; _i < 2; ++_i) \
;         __builtin_amdgcn_global_load_lds((const unsigned*)((const char*)(gbase) + (voff)[_i]), (LAS unsigned*)(lds + (bufoff) + ldsw + _i * 8192), 16, 0, 0); } while (0)
; #define PG8_LDA(dst, b, h) do { _Pragma("unroll") for (int m = 0; m < 4; ++m) _Pragma("unroll") for (int k = 0; k < 2; ++k) dst[m][k] = *(const LAS bf16x8*)(lds + PG8_SA(b, h) + aoff + m * 2048 + k * KOFF); } while (0)
; #define PG8_WAIT_V(n) asm volatile("s_waitcnt vmcnt(" #n ")" ::: "memory")
; #define PG8_WAIT_L(n) asm volatile("s_waitcnt lgkmcnt(" #n ")" ::: "memory")
; #define PG8_BAR __builtin_amdgcn_s_barrier()
; #define PG8_SCHED __builtin_amdgcn_sched_barrier(0)
; template <class Epi, bool ALIGN_EPI = true, bool FP8 = false>
; __device__ __forceinline__ void gemm_phase(LAS unsigned char* lds, const Gemm g, const StaticOrder& S, const Epi& E, const int wid) {
;     ...
;             PG8_LDA(At, 1, 1); PG8_STAGE(PG8_SB(1, 0), b3, voffB); PG8_STAGE(PG8_SB(1, 1), b3 + hstep, voffB); PG8_STAGE(PG8_SA(1, 0), a3, voffA);
;             PG8_WAIT_V(8); PG8_WAIT_L(0); PG8_BAR; PG8_MMA(1, 0, At, B0); PG8_MMA(1, 1, At, B1); PG8_BAR; PG8_SCHED;
;         }
	s_setprio 0
	s_add_i32 s34, s77, s38
	v_lshl_add_u64 v[144:145], v[144:145], 0, s[14:15]
	s_mov_b32 m0, s34
	ds_read_b128 v[184:187], v150 offset:49152
	ds_read_b128 v[188:191], v150 offset:50176
	ds_read_b128 v[192:195], v150 offset:51200
	ds_read_b128 v[196:199], v150 offset:52224
	ds_read_b128 v[200:203], v150 offset:53248
	ds_read_b128 v[204:207], v150 offset:54272
	ds_read_b128 v[208:211], v150 offset:55296
	ds_read_b128 v[212:215], v150 offset:56320
	global_load_lds_dwordx4 v[144:145], off
	s_add_i32 m0, s34, 0x2000
	s_add_u32 s30, s30, 0x80080
	v_lshl_add_u64 v[144:145], v[216:217], 0, s[14:15]
	s_addc_u32 s31, s31, 0
	s_add_i32 s34, s78, s38
	global_load_lds_dwordx4 v[144:145], off
	v_lshl_add_u64 v[144:145], s[30:31], 0, v[132:133]
	s_mov_b32 m0, s34
	s_nop 0
	global_load_lds_dwordx4 v[144:145], off
	v_lshl_add_u64 v[144:145], s[30:31], 0, v[128:129]
	s_add_i32 m0, s34, 0x2000
	s_nop 0
	global_load_lds_dwordx4 v[144:145], off
	v_lshl_add_u64 v[144:145], v[218:219], 0, s[14:15]
	s_mov_b32 m0, s53
	s_nop 0
	global_load_lds_dwordx4 v[144:145], off
	v_lshl_add_u64 v[144:145], v[220:221], 0, s[14:15]
	s_mov_b32 m0, s55
	s_nop 0
	global_load_lds_dwordx4 v[144:145], off
	s_setprio 1
	s_waitcnt vmcnt(8) lgkmcnt(0)
	s_barrier
	v_mfma_f32_16x16x32_bf16 v[60:63], v[152:155], v[184:187], v[60:63]
	v_mfma_f32_16x16x32_bf16 v[52:55], v[160:163], v[184:187], v[52:55]
	v_mfma_f32_16x16x32_bf16 v[44:47], v[152:155], v[192:195], v[44:47]
	v_mfma_f32_16x16x32_bf16 v[36:39], v[160:163], v[192:195], v[36:39]
	v_mfma_f32_16x16x32_bf16 v[28:31], v[152:155], v[200:203], v[28:31]
	v_mfma_f32_16x16x32_bf16 v[20:23], v[160:163], v[200:203], v[20:23]
	v_mfma_f32_16x16x32_bf16 v[12:15], v[152:155], v[208:211], v[12:15]
	v_mfma_f32_16x16x32_bf16 v[4:7], v[160:163], v[208:211], v[4:7]
	v_mfma_f32_16x16x32_bf16 v[60:63], v[156:159], v[188:191], v[60:63]
	v_mfma_f32_16x16x32_bf16 v[52:55], v[164:167], v[188:191], v[52:55]
	v_mfma_f32_16x16x32_bf16 v[44:47], v[156:159], v[196:199], v[44:47]
	v_mfma_f32_16x16x32_bf16 v[36:39], v[164:167], v[196:199], v[36:39]
	v_mfma_f32_16x16x32_bf16 v[28:31], v[156:159], v[204:207], v[28:31]
	v_mfma_f32_16x16x32_bf16 v[20:23], v[164:167], v[204:207], v[20:23]
	v_mfma_f32_16x16x32_bf16 v[12:15], v[156:159], v[212:215], v[12:15]
	v_mfma_f32_16x16x32_bf16 v[4:7], v[164:167], v[212:215], v[4:7]
	v_mfma_f32_16x16x32_bf16 v[56:59], v[168:171], v[184:187], v[56:59]
	v_mfma_f32_16x16x32_bf16 v[48:51], v[176:179], v[184:187], v[48:51]
	v_mfma_f32_16x16x32_bf16 v[40:43], v[168:171], v[192:195], v[40:43]
	v_mfma_f32_16x16x32_bf16 v[32:35], v[176:179], v[192:195], v[32:35]
	v_mfma_f32_16x16x32_bf16 v[24:27], v[168:171], v[200:203], v[24:27]
	v_mfma_f32_16x16x32_bf16 v[16:19], v[176:179], v[200:203], v[16:19]
	v_mfma_f32_16x16x32_bf16 v[8:11], v[168:171], v[208:211], v[8:11]
	v_mfma_f32_16x16x32_bf16 v[0:3], v[176:179], v[208:211], v[0:3]
	v_mfma_f32_16x16x32_bf16 v[56:59], v[172:175], v[188:191], v[56:59]
	v_mfma_f32_16x16x32_bf16 v[48:51], v[180:183], v[188:191], v[48:51]
	v_mfma_f32_16x16x32_bf16 v[40:43], v[172:175], v[196:199], v[40:43]
	v_mfma_f32_16x16x32_bf16 v[32:35], v[180:183], v[196:199], v[32:35]
	v_mfma_f32_16x16x32_bf16 v[24:27], v[172:175], v[204:207], v[24:27]
	v_mfma_f32_16x16x32_bf16 v[16:19], v[180:183], v[204:207], v[16:19]
	v_mfma_f32_16x16x32_bf16 v[8:11], v[172:175], v[212:215], v[8:11]
	v_mfma_f32_16x16x32_bf16 v[0:3], v[180:183], v[212:215], v[0:3]
	s_barrier
	s_setprio 0
	s_add_u32 s28, s28, 0x100
	s_addc_u32 s29, s29, 0
	s_add_u32 s52, s52, 0x100
	s_addc_u32 s75, s75, 0
	s_cmp_ge_u32 s76, s54
	s_mov_b32 s30, s76
	s_cbranch_scc0 .LBB0_2452
	s_and_b64 vcc, exec, s[12:13]
	s_cbranch_vccz .LBB0_2455

; __device__ __forceinline__ unsigned cvt_pk4_fp8(float a, float b, float c, float d) { int w = __builtin_amdgcn_cvt_pk_fp8_f32(fp8_clamp(a), fp8_clamp(b), 0, false); w = __builtin_amdgcn_cvt_pk_fp8_f32(fp8_clamp(c), fp8_clamp(d), w, true); return (unsigned)w; }
; __device__ __forceinline__ float sigmoid_f(float v) { return __builtin_amdgcn_rcpf(1.0f + __builtin_amdgcn_exp2f(-1.4426950408889634f * v)); }
;     __device__ __forceinline__ void operator()(const Acc& acc, const Unit& u, int wr, int wc, int fr, int fq) const {
;         unsigned char* base = (unsigned char*)act + (size_t)(u.pm * 256 + wr * 64 + fr) * DFF + u.pn * 128 + wc * 32 + 8 * fq;
; #pragma unroll
;         for (int ai = 0; ai < 2; ++ai)
; #pragma unroll
;             for (int m = 0; m < 4; ++m) {
;                 const f32x4 g0 = acc[ai][0][m][0], g1 = acc[ai][0][m][1], u0 = acc[ai][1][m][0], u1 = acc[ai][1][m][1];
;                 float a[8];
; #pragma unroll
;                 for (int e = 0; e < 4; ++e) { a[e] = g0[e] * sigmoid_f(g0[e]) * u0[e]; a[4 + e] = g1[e] * sigmoid_f(g1[e]) * u1[e]; }
;                 u32x2 w; w.x = cvt_pk4_fp8(a[0], a[1], a[2], a[3]); w.y = cvt_pk4_fp8(a[4], a[5], a[6], a[7]);
;                 *(u32x2*)(base + (size_t)(ai * HALF + m * 16) * DFF) = w;
;             }
;     }
.LBB0_2455:
	v_lshl_add_u32 v152, s26, 8, v146
	v_mov_b64_e32 v[144:145], s[62:63]
	v_mad_i64_i32 v[144:145], s[28:29], v152, s67, v[144:145]
	v_mul_f32_e32 v152, 0xbfb8aa3b, v124
	v_exp_f32_e32 v152, v152
	v_mul_f32_e32 v153, 0xbfb8aa3b, v116
	v_exp_f32_e32 v153, v153
	s_lshl_b32 s28, s24, 7
	v_add_f32_e32 v152, 1.0, v152
	v_rcp_f32_e32 v152, v152
	v_add_f32_e32 v153, 1.0, v153
	v_rcp_f32_e32 v153, v153
	s_ashr_i32 s29, s28, 31
	v_mul_f32_e32 v124, v124, v152
	v_mul_f32_e32 v120, v120, v124
	v_mul_f32_e32 v124, 0xbfb8aa3b, v125
	v_exp_f32_e32 v124, v124
	v_mul_f32_e32 v152, 0xbfb8aa3b, v117
	v_exp_f32_e32 v152, v152
	v_mul_f32_e32 v116, v116, v153
	v_mul_f32_e32 v116, v112, v116
	v_add_f32_e32 v112, 1.0, v124
	v_rcp_f32_e32 v112, v112
	v_add_f32_e32 v124, 1.0, v152
	v_mul_f32_e32 v152, 0xbfb8aa3b, v126
	v_exp_f32_e32 v152, v152
	v_rcp_f32_e32 v124, v124
	v_mul_f32_e32 v112, v125, v112
	v_mul_f32_e32 v112, v121, v112
	v_add_f32_e32 v121, 1.0, v152
	v_mul_f32_e32 v117, v117, v124
	v_rcp_f32_e32 v121, v121
	v_mul_f32_e32 v124, 0xbfb8aa3b, v118
	v_exp_f32_e32 v124, v124
	v_mul_f32_e32 v113, v113, v117
	v_mul_f32_e32 v117, v126, v121
	v_mul_f32_e32 v117, v122, v117
	v_add_f32_e32 v121, 1.0, v124
	v_mul_f32_e32 v122, 0xbfb8aa3b, v127
	v_rcp_f32_e32 v121, v121
	v_exp_f32_e32 v122, v122
	v_mul_f32_e32 v124, 0xbfb8aa3b, v119
	v_exp_f32_e32 v124, v124
	v_mul_f32_e32 v118, v118, v121
	v_add_f32_e32 v121, 1.0, v122
	v_rcp_f32_e32 v121, v121
	v_mul_f32_e32 v114, v114, v118
	v_med3_f32 v120, v120, s68, v151
	v_add_f32_e32 v122, 1.0, v124
	v_mul_f32_e32 v118, v127, v121
	v_med3_f32 v121, v112, s68, v151
	v_mov_b32_e32 v112, 0
	v_cvt_pk_fp8_f32 v112, v120, v121
	v_mul_f32_e32 v118, v123, v118
	v_rcp_f32_e32 v122, v122
	v_med3_f32 v117, v117, s68, v151
	v_med3_f32 v118, v118, s68, v151
	v_cvt_pk_fp8_f32 v112, v117, v118 op_sel:[0,0,1]
	v_med3_f32 v116, v116, s68, v151
	v_med3_f32 v117, v113, s68, v151
	v_mov_b32_e32 v113, 0
	v_cvt_pk_fp8_f32 v113, v116, v117
	v_mul_f32_e32 v116, 0xbfb8aa3b, v108
	v_exp_f32_e32 v116, v116
	v_mul_f32_e32 v119, v119, v122
	v_mul_f32_e32 v115, v115, v119
	v_med3_f32 v114, v114, s68, v151
	v_med3_f32 v115, v115, s68, v151
	v_mul_f32_e32 v117, 0xbfb8aa3b, v100
	v_cvt_pk_fp8_f32 v113, v114, v115 op_sel:[0,0,1]
	v_add_f32_e32 v114, 1.0, v116
	v_exp_f32_e32 v117, v117
	v_rcp_f32_e32 v114, v114
	v_lshl_add_u64 v[144:145], v[144:145], 0, s[28:29]
	v_lshl_add_u64 v[144:145], v[144:145], 0, s[10:11]
	v_add_f32_e32 v115, 1.0, v117
	v_mul_f32_e32 v108, v108, v114
	v_lshl_add_u64 v[144:145], v[144:145], 0, v[136:137]
	v_rcp_f32_e32 v115, v115
	v_mul_f32_e32 v104, v104, v108
	v_mul_f32_e32 v108, 0xbfb8aa3b, v109
	global_store_dwordx2 v[144:145], v[112:113], off
	v_exp_f32_e32 v108, v108
	v_mul_f32_e32 v112, 0xbfb8aa3b, v101
	v_exp_f32_e32 v112, v112
	v_mul_f32_e32 v100, v100, v115
	v_mul_f32_e32 v100, v96, v100
	v_add_f32_e32 v96, 1.0, v108
	v_rcp_f32_e32 v96, v96
	v_add_f32_e32 v108, 1.0, v112
	v_mul_f32_e32 v112, 0xbfb8aa3b, v110
	v_exp_f32_e32 v112, v112
	v_rcp_f32_e32 v108, v108
	v_mul_f32_e32 v96, v109, v96
	v_mul_f32_e32 v96, v105, v96
	v_add_f32_e32 v105, 1.0, v112
	v_mul_f32_e32 v101, v101, v108
	v_rcp_f32_e32 v105, v105
	v_mul_f32_e32 v108, 0xbfb8aa3b, v102
	v_exp_f32_e32 v108, v108
	v_mul_f32_e32 v97, v97, v101
	v_mul_f32_e32 v101, v110, v105
	v_mul_f32_e32 v101, v106, v101
	v_add_f32_e32 v105, 1.0, v108
	v_mul_f32_e32 v106, 0xbfb8aa3b, v111
	v_mul_f32_e32 v108, 0xbfb8aa3b, v103
	v_rcp_f32_e32 v105, v105
	v_exp_f32_e32 v106, v106
	v_exp_f32_e32 v108, v108
	v_med3_f32 v100, v100, s68, v151
	v_mul_f32_e32 v102, v102, v105
	v_add_f32_e32 v105, 1.0, v106
	v_add_f32_e32 v106, 1.0, v108
	v_rcp_f32_e32 v106, v106
	v_mul_f32_e32 v98, v98, v102
	v_rcp_f32_e32 v105, v105
	v_med3_f32 v98, v98, s68, v151
	v_mul_f32_e32 v103, v103, v106
	v_mul_f32_e32 v99, v99, v103
	v_med3_f32 v103, v104, s68, v151
	v_med3_f32 v104, v96, s68, v151
	v_mov_b32_e32 v96, 0
	v_cvt_pk_fp8_f32 v96, v103, v104
	v_med3_f32 v103, v97, s68, v151
	v_mov_b32_e32 v97, 0
	v_cvt_pk_fp8_f32 v97, v100, v103
	v_med3_f32 v99, v99, s68, v151
	v_mul_f32_e32 v102, v111, v105
	v_mul_f32_e32 v102, v107, v102
	v_cvt_pk_fp8_f32 v97, v98, v99 op_sel:[0,0,1]
	v_mul_f32_e32 v98, 0xbfb8aa3b, v92
	v_exp_f32_e32 v100, v98
	v_med3_f32 v101, v101, s68, v151
	v_med3_f32 v102, v102, s68, v151
	v_mul_f32_e32 v98, 0xbfb8aa3b, v84
	v_add_f32_e32 v100, 1.0, v100
	v_cvt_pk_fp8_f32 v96, v101, v102 op_sel:[0,0,1]
	v_exp_f32_e32 v101, v98
	v_rcp_f32_e32 v100, v100
	v_add_co_u32_e32 v98, vcc, s49, v144
	v_add_f32_e32 v101, 1.0, v101
	v_mul_f32_e32 v92, v92, v100
	v_addc_co_u32_e32 v99, vcc, 0, v145, vcc
	v_rcp_f32_e32 v101, v101
	v_mul_f32_e32 v88, v88, v92
	v_mul_f32_e32 v92, 0xbfb8aa3b, v93
	global_store_dwordx2 v[98:99], v[96:97], off
	v_exp_f32_e32 v92, v92
	v_mul_f32_e32 v96, 0xbfb8aa3b, v85
	v_exp_f32_e32 v96, v96
	v_mul_f32_e32 v84, v84, v101
	v_mul_f32_e32 v84, v80, v84
	v_add_f32_e32 v80, 1.0, v92
	v_rcp_f32_e32 v80, v80
	v_add_f32_e32 v92, 1.0, v96
	v_mul_f32_e32 v96, 0xbfb8aa3b, v94
	v_exp_f32_e32 v96, v96
	v_rcp_f32_e32 v92, v92
	v_mul_f32_e32 v80, v93, v80
	v_mul_f32_e32 v80, v89, v80
	v_add_f32_e32 v89, 1.0, v96
	v_mul_f32_e32 v85, v85, v92
	v_rcp_f32_e32 v89, v89
	v_mul_f32_e32 v92, 0xbfb8aa3b, v86
	v_exp_f32_e32 v92, v92
	v_mul_f32_e32 v81, v81, v85
	v_mul_f32_e32 v85, v94, v89
	v_mul_f32_e32 v85, v90, v85
	v_add_f32_e32 v89, 1.0, v92
	v_mul_f32_e32 v90, 0xbfb8aa3b, v95
	v_mul_f32_e32 v92, 0xbfb8aa3b, v87
	v_rcp_f32_e32 v89, v89
	v_exp_f32_e32 v90, v90
	v_exp_f32_e32 v92, v92
	v_med3_f32 v84, v84, s68, v151
	v_mul_f32_e32 v86, v86, v89
	v_add_f32_e32 v89, 1.0, v90
	v_add_f32_e32 v90, 1.0, v92
; __device__ __forceinline__ unsigned cvt_pk4_fp8(float a, float b, float c, float d) { int w = __builtin_amdgcn_cvt_pk_fp8_f32(fp8_clamp(a), fp8_clamp(b), 0, false); w = __builtin_amdgcn_cvt_pk_fp8_f32(fp8_clamp(c), fp8_clamp(d), w, true); return (unsigned)w; }
; __device__ __forceinline__ float sigmoid_f(float v) { return __builtin_amdgcn_rcpf(1.0f + __builtin_amdgcn_exp2f(-1.4426950408889634f * v)); }
;     __device__ __forceinline__ void operator()(const Acc& acc, const Unit& u, int wr, int wc, int fr, int fq) const {
;         unsigned char* base = (unsigned char*)act + (size_t)(u.pm * 256 + wr * 64 + fr) * DFF + u.pn * 128 + wc * 32 + 8 * fq;
; #pragma unroll
;         for (int ai = 0; ai < 2; ++ai)
; #pragma unroll
;             for (int m = 0; m < 4; ++m) {
;                 const f32x4 g0 = acc[ai][0][m][0], g1 = acc[ai][0][m][1], u0 = acc[ai][1][m][0], u1 = acc[ai][1][m][1];
;                 float a[8];
; #pragma unroll
;                 for (int e = 0; e < 4; ++e) { a[e] = g0[e] * sigmoid_f(g0[e]) * u0[e]; a[4 + e] = g1[e] * sigmoid_f(g1[e]) * u1[e]; }
;                 u32x2 w; w.x = cvt_pk4_fp8(a[0], a[1], a[2], a[3]); w.y = cvt_pk4_fp8(a[4], a[5], a[6], a[7]);
;                 *(u32x2*)(base + (size_t)(ai * HALF + m * 16) * DFF) = w;
;             }
;     }
	v_rcp_f32_e32 v90, v90
	v_mul_f32_e32 v82, v82, v86
	v_rcp_f32_e32 v89, v89
	v_med3_f32 v82, v82, s68, v151
	v_mul_f32_e32 v87, v87, v90
	v_mul_f32_e32 v83, v83, v87
	v_med3_f32 v87, v88, s68, v151
	v_med3_f32 v88, v80, s68, v151
	v_mov_b32_e32 v80, 0
	v_cvt_pk_fp8_f32 v80, v87, v88
	v_med3_f32 v87, v81, s68, v151
	v_mov_b32_e32 v81, 0
	v_cvt_pk_fp8_f32 v81, v84, v87
	v_med3_f32 v83, v83, s68, v151
	v_mul_f32_e32 v86, v95, v89
	v_mul_f32_e32 v86, v91, v86
	v_cvt_pk_fp8_f32 v81, v82, v83 op_sel:[0,0,1]
	v_mul_f32_e32 v82, 0xbfb8aa3b, v76
	v_exp_f32_e32 v84, v82
	v_med3_f32 v85, v85, s68, v151
	v_med3_f32 v86, v86, s68, v151
	v_mul_f32_e32 v82, 0xbfb8aa3b, v68
	v_add_f32_e32 v84, 1.0, v84
	v_cvt_pk_fp8_f32 v80, v85, v86 op_sel:[0,0,1]
	v_exp_f32_e32 v85, v82
	v_rcp_f32_e32 v84, v84
	v_add_co_u32_e32 v82, vcc, s69, v144
	v_add_f32_e32 v85, 1.0, v85
	v_mul_f32_e32 v76, v76, v84
	v_addc_co_u32_e32 v83, vcc, 0, v145, vcc
	v_rcp_f32_e32 v85, v85
	v_mul_f32_e32 v72, v72, v76
	v_mul_f32_e32 v76, 0xbfb8aa3b, v77
	global_store_dwordx2 v[82:83], v[80:81], off
	v_exp_f32_e32 v76, v76
	v_mul_f32_e32 v80, 0xbfb8aa3b, v69
	v_exp_f32_e32 v80, v80
	v_mul_f32_e32 v68, v68, v85
	v_mul_f32_e32 v68, v64, v68
	v_add_f32_e32 v64, 1.0, v76
	v_rcp_f32_e32 v64, v64
	v_add_f32_e32 v76, 1.0, v80
	v_mul_f32_e32 v80, 0xbfb8aa3b, v78
	v_exp_f32_e32 v80, v80
	v_rcp_f32_e32 v76, v76
	v_mul_f32_e32 v64, v77, v64
	v_mul_f32_e32 v64, v73, v64
	v_add_f32_e32 v73, 1.0, v80
	v_mul_f32_e32 v69, v69, v76
	v_rcp_f32_e32 v73, v73
	v_mul_f32_e32 v76, 0xbfb8aa3b, v70
	v_exp_f32_e32 v76, v76
	v_mul_f32_e32 v65, v65, v69
	v_mul_f32_e32 v69, v78, v73
	v_mul_f32_e32 v69, v74, v69
	v_add_f32_e32 v73, 1.0, v76
	v_mul_f32_e32 v74, 0xbfb8aa3b, v79
	v_mul_f32_e32 v76, 0xbfb8aa3b, v71
	v_rcp_f32_e32 v73, v73
	v_exp_f32_e32 v74, v74
	v_exp_f32_e32 v76, v76
	v_med3_f32 v68, v68, s68, v151
	v_mul_f32_e32 v70, v70, v73
	v_add_f32_e32 v73, 1.0, v74
	v_add_f32_e32 v74, 1.0, v76
	v_rcp_f32_e32 v74, v74
	v_mul_f32_e32 v66, v66, v70
	v_rcp_f32_e32 v73, v73
	v_med3_f32 v66, v66, s68, v151
	v_mul_f32_e32 v71, v71, v74
	v_mul_f32_e32 v67, v67, v71
	v_med3_f32 v71, v72, s68, v151
	v_med3_f32 v72, v64, s68, v151
	v_mov_b32_e32 v64, 0
	v_cvt_pk_fp8_f32 v64, v71, v72
	v_med3_f32 v71, v65, s68, v151
	v_mov_b32_e32 v65, 0
	v_cvt_pk_fp8_f32 v65, v68, v71
	v_med3_f32 v67, v67, s68, v151
	v_mul_f32_e32 v70, v79, v73
	v_mul_f32_e32 v70, v75, v70
	v_cvt_pk_fp8_f32 v65, v66, v67 op_sel:[0,0,1]
	v_mul_f32_e32 v66, 0xbfb8aa3b, v60
	v_exp_f32_e32 v68, v66
	v_med3_f32 v69, v69, s68, v151
	v_med3_f32 v70, v70, s68, v151
	v_mul_f32_e32 v66, 0xbfb8aa3b, v52
	v_add_f32_e32 v68, 1.0, v68
	v_cvt_pk_fp8_f32 v64, v69, v70 op_sel:[0,0,1]
	v_exp_f32_e32 v69, v66
	v_rcp_f32_e32 v68, v68
	v_add_co_u32_e32 v66, vcc, s70, v144
	v_add_f32_e32 v69, 1.0, v69
	v_mul_f32_e32 v60, v60, v68
	v_addc_co_u32_e32 v67, vcc, 0, v145, vcc
	v_rcp_f32_e32 v69, v69
	v_mul_f32_e32 v56, v56, v60
	v_mul_f32_e32 v60, 0xbfb8aa3b, v61
	global_store_dwordx2 v[66:67], v[64:65], off
	v_exp_f32_e32 v60, v60
	v_mul_f32_e32 v64, 0xbfb8aa3b, v53
	v_exp_f32_e32 v64, v64
	v_mul_f32_e32 v52, v52, v69
	v_mul_f32_e32 v52, v48, v52
	v_add_f32_e32 v48, 1.0, v60
	v_rcp_f32_e32 v48, v48
	v_add_f32_e32 v60, 1.0, v64
	v_mul_f32_e32 v64, 0xbfb8aa3b, v62
	v_exp_f32_e32 v64, v64
	v_rcp_f32_e32 v60, v60
	v_mul_f32_e32 v48, v61, v48
	v_mul_f32_e32 v48, v57, v48
	v_add_f32_e32 v57, 1.0, v64
	v_mul_f32_e32 v53, v53, v60
	v_rcp_f32_e32 v57, v57
	v_mul_f32_e32 v60, 0xbfb8aa3b, v54
	v_exp_f32_e32 v60, v60
	v_mul_f32_e32 v49, v49, v53
	v_mul_f32_e32 v53, v62, v57
	v_mul_f32_e32 v53, v58, v53
	v_add_f32_e32 v57, 1.0, v60
	v_mul_f32_e32 v58, 0xbfb8aa3b, v63
	v_mul_f32_e32 v60, 0xbfb8aa3b, v55
	v_rcp_f32_e32 v57, v57
	v_exp_f32_e32 v58, v58
	v_exp_f32_e32 v60, v60
	v_med3_f32 v52, v52, s68, v151
	v_mul_f32_e32 v54, v54, v57
	v_add_f32_e32 v57, 1.0, v58
	v_add_f32_e32 v58, 1.0, v60
	v_rcp_f32_e32 v58, v58
	v_mul_f32_e32 v50, v50, v54
	v_rcp_f32_e32 v57, v57
	v_med3_f32 v50, v50, s68, v151
	v_mul_f32_e32 v55, v55, v58
	v_mul_f32_e32 v51, v51, v55
	v_med3_f32 v55, v56, s68, v151
	v_med3_f32 v56, v48, s68, v151
	v_mov_b32_e32 v48, 0
	v_cvt_pk_fp8_f32 v48, v55, v56
	v_med3_f32 v55, v49, s68, v151
	v_mov_b32_e32 v49, 0
	v_cvt_pk_fp8_f32 v49, v52, v55
	v_med3_f32 v51, v51, s68, v151
	v_mul_f32_e32 v54, v63, v57
	v_mul_f32_e32 v54, v59, v54
	v_cvt_pk_fp8_f32 v49, v50, v51 op_sel:[0,0,1]
	v_mul_f32_e32 v50, 0xbfb8aa3b, v44
	v_exp_f32_e32 v52, v50
	v_med3_f32 v53, v53, s68, v151
	v_med3_f32 v54, v54, s68, v151
	v_mul_f32_e32 v50, 0xbfb8aa3b, v36
	v_add_f32_e32 v52, 1.0, v52
	v_cvt_pk_fp8_f32 v48, v53, v54 op_sel:[0,0,1]
	v_exp_f32_e32 v53, v50
	v_rcp_f32_e32 v52, v52
	v_add_co_u32_e32 v50, vcc, s71, v144
	v_add_f32_e32 v53, 1.0, v53
	v_mul_f32_e32 v44, v44, v52
	v_addc_co_u32_e32 v51, vcc, 0, v145, vcc
	v_rcp_f32_e32 v53, v53
	v_mul_f32_e32 v40, v40, v44
	v_mul_f32_e32 v44, 0xbfb8aa3b, v45
	global_store_dwordx2 v[50:51], v[48:49], off
	v_exp_f32_e32 v44, v44
	v_mul_f32_e32 v48, 0xbfb8aa3b, v37
	v_exp_f32_e32 v48, v48
	v_mul_f32_e32 v36, v36, v53
	v_mul_f32_e32 v36, v32, v36
	v_add_f32_e32 v32, 1.0, v44
	v_rcp_f32_e32 v32, v32
	v_add_f32_e32 v44, 1.0, v48
	v_mul_f32_e32 v48, 0xbfb8aa3b, v46
	v_exp_f32_e32 v48, v48
	v_rcp_f32_e32 v44, v44
	v_mul_f32_e32 v32, v45, v32
; __device__ __forceinline__ unsigned cvt_pk4_fp8(float a, float b, float c, float d) { int w = __builtin_amdgcn_cvt_pk_fp8_f32(fp8_clamp(a), fp8_clamp(b), 0, false); w = __builtin_amdgcn_cvt_pk_fp8_f32(fp8_clamp(c), fp8_clamp(d), w, true); return (unsigned)w; }
; __device__ __forceinline__ float sigmoid_f(float v) { return __builtin_amdgcn_rcpf(1.0f + __builtin_amdgcn_exp2f(-1.4426950408889634f * v)); }
; #define PG8_BAR __builtin_amdgcn_s_barrier()
;     __device__ __forceinline__ void operator()(const Acc& acc, const Unit& u, int wr, int wc, int fr, int fq) const {
;         unsigned char* base = (unsigned char*)act + (size_t)(u.pm * 256 + wr * 64 + fr) * DFF + u.pn * 128 + wc * 32 + 8 * fq;
; #pragma unroll
;         for (int ai = 0; ai < 2; ++ai)
; #pragma unroll
;             for (int m = 0; m < 4; ++m) {
;                 const f32x4 g0 = acc[ai][0][m][0], g1 = acc[ai][0][m][1], u0 = acc[ai][1][m][0], u1 = acc[ai][1][m][1];
;                 float a[8];
; #pragma unroll
;                 for (int e = 0; e < 4; ++e) { a[e] = g0[e] * sigmoid_f(g0[e]) * u0[e]; a[4 + e] = g1[e] * sigmoid_f(g1[e]) * u1[e]; }
;                 u32x2 w; w.x = cvt_pk4_fp8(a[0], a[1], a[2], a[3]); w.y = cvt_pk4_fp8(a[4], a[5], a[6], a[7]);
;                 *(u32x2*)(base + (size_t)(ai * HALF + m * 16) * DFF) = w;
;             }
;     }
; template <class Epi, bool ALIGN_EPI = true, bool FP8 = false>
; __device__ __forceinline__ void gemm_phase(LAS unsigned char* lds, const Gemm g, const StaticOrder& S, const Epi& E, const int wid) {
;     ...
;         if (!has_next) break;
; #pragma unroll
;         for (int a = 0; a < 2; ++a)
; #pragma unroll
;             for (int b = 0; b < 2; ++b)
; #pragma unroll
;                 for (int m = 0; m < 4; ++m) {
;                     if (!keep) { acc[a][b][m][0] = (f32x4){0.f, 0.f, 0.f, 0.f}; acc[a][b][m][1] = (f32x4){0.f, 0.f, 0.f, 0.f}; }
;                     if constexpr (FP8) acc8[a][b][m] = __builtin_shufflevector(acc[a][b][m][0], acc[a][b][m][1], 0, 1, 2, 3, 4, 5, 6, 7); }
;         cur = nxt; cA = nA; cB = nB; ++ui;
;         if constexpr (ALIGN_EPI) { if (wr == 1) PG8_BAR; }
	v_mul_f32_e32 v32, v41, v32
	v_add_f32_e32 v41, 1.0, v48
	v_mul_f32_e32 v37, v37, v44
	v_rcp_f32_e32 v41, v41
	v_mul_f32_e32 v44, 0xbfb8aa3b, v38
	v_exp_f32_e32 v44, v44
	v_mul_f32_e32 v33, v33, v37
	v_mul_f32_e32 v37, v46, v41
	v_mul_f32_e32 v37, v42, v37
	v_add_f32_e32 v41, 1.0, v44
	v_mul_f32_e32 v42, 0xbfb8aa3b, v47
	v_mul_f32_e32 v44, 0xbfb8aa3b, v39
	v_rcp_f32_e32 v41, v41
	v_exp_f32_e32 v42, v42
	v_exp_f32_e32 v44, v44
	v_med3_f32 v36, v36, s68, v151
	v_mul_f32_e32 v38, v38, v41
	v_add_f32_e32 v41, 1.0, v42
	v_add_f32_e32 v42, 1.0, v44
	v_rcp_f32_e32 v42, v42
	v_mul_f32_e32 v34, v34, v38
	v_rcp_f32_e32 v41, v41
	v_med3_f32 v34, v34, s68, v151
	v_mul_f32_e32 v39, v39, v42
	v_mul_f32_e32 v35, v35, v39
	v_med3_f32 v39, v40, s68, v151
	v_med3_f32 v40, v32, s68, v151
	v_mov_b32_e32 v32, 0
	v_cvt_pk_fp8_f32 v32, v39, v40
	v_med3_f32 v39, v33, s68, v151
	v_mov_b32_e32 v33, 0
	v_cvt_pk_fp8_f32 v33, v36, v39
	v_med3_f32 v35, v35, s68, v151
	v_mul_f32_e32 v38, v47, v41
	v_mul_f32_e32 v38, v43, v38
	v_cvt_pk_fp8_f32 v33, v34, v35 op_sel:[0,0,1]
	v_mul_f32_e32 v34, 0xbfb8aa3b, v28
	v_exp_f32_e32 v36, v34
	v_med3_f32 v37, v37, s68, v151
	v_med3_f32 v38, v38, s68, v151
	v_mul_f32_e32 v34, 0xbfb8aa3b, v20
	v_add_f32_e32 v36, 1.0, v36
	v_cvt_pk_fp8_f32 v32, v37, v38 op_sel:[0,0,1]
	v_exp_f32_e32 v37, v34
	v_rcp_f32_e32 v36, v36
	v_add_co_u32_e32 v34, vcc, s72, v144
	v_add_f32_e32 v37, 1.0, v37
	v_mul_f32_e32 v28, v28, v36
	v_addc_co_u32_e32 v35, vcc, 0, v145, vcc
	v_rcp_f32_e32 v37, v37
	v_mul_f32_e32 v24, v24, v28
	v_mul_f32_e32 v28, 0xbfb8aa3b, v29
	global_store_dwordx2 v[34:35], v[32:33], off
	v_exp_f32_e32 v28, v28
	v_mul_f32_e32 v32, 0xbfb8aa3b, v21
	v_exp_f32_e32 v32, v32
	v_mul_f32_e32 v20, v20, v37
	v_mul_f32_e32 v20, v16, v20
	v_add_f32_e32 v16, 1.0, v28
	v_rcp_f32_e32 v16, v16
	v_add_f32_e32 v28, 1.0, v32
	v_mul_f32_e32 v32, 0xbfb8aa3b, v30
	v_exp_f32_e32 v32, v32
	v_rcp_f32_e32 v28, v28
	v_mul_f32_e32 v16, v29, v16
	v_mul_f32_e32 v16, v25, v16
	v_add_f32_e32 v25, 1.0, v32
	v_mul_f32_e32 v21, v21, v28
	v_rcp_f32_e32 v25, v25
	v_mul_f32_e32 v28, 0xbfb8aa3b, v22
	v_exp_f32_e32 v28, v28
	v_mul_f32_e32 v17, v17, v21
	v_mul_f32_e32 v21, v30, v25
	v_mul_f32_e32 v21, v26, v21
	v_add_f32_e32 v25, 1.0, v28
	v_mul_f32_e32 v26, 0xbfb8aa3b, v31
	v_mul_f32_e32 v28, 0xbfb8aa3b, v23
	v_rcp_f32_e32 v25, v25
	v_exp_f32_e32 v26, v26
	v_exp_f32_e32 v28, v28
	v_med3_f32 v20, v20, s68, v151
	v_mul_f32_e32 v22, v22, v25
	v_add_f32_e32 v25, 1.0, v26
	v_add_f32_e32 v26, 1.0, v28
	v_rcp_f32_e32 v26, v26
	v_mul_f32_e32 v18, v18, v22
	v_rcp_f32_e32 v25, v25
	v_med3_f32 v18, v18, s68, v151
	v_mul_f32_e32 v23, v23, v26
	v_mul_f32_e32 v19, v19, v23
	v_med3_f32 v23, v24, s68, v151
	v_med3_f32 v24, v16, s68, v151
	v_mov_b32_e32 v16, 0
	v_cvt_pk_fp8_f32 v16, v23, v24
	v_med3_f32 v23, v17, s68, v151
	v_mov_b32_e32 v17, 0
	v_cvt_pk_fp8_f32 v17, v20, v23
	v_med3_f32 v19, v19, s68, v151
	v_mul_f32_e32 v22, v31, v25
	v_mul_f32_e32 v22, v27, v22
	v_cvt_pk_fp8_f32 v17, v18, v19 op_sel:[0,0,1]
	v_mul_f32_e32 v18, 0xbfb8aa3b, v12
	v_exp_f32_e32 v20, v18
	v_med3_f32 v21, v21, s68, v151
	v_med3_f32 v22, v22, s68, v151
	v_mul_f32_e32 v18, 0xbfb8aa3b, v4
	v_add_f32_e32 v20, 1.0, v20
	v_cvt_pk_fp8_f32 v16, v21, v22 op_sel:[0,0,1]
	v_exp_f32_e32 v21, v18
	v_rcp_f32_e32 v20, v20
	v_add_co_u32_e32 v18, vcc, s73, v144
	v_add_f32_e32 v21, 1.0, v21
	v_mul_f32_e32 v12, v12, v20
	v_addc_co_u32_e32 v19, vcc, 0, v145, vcc
	v_rcp_f32_e32 v21, v21
	v_mul_f32_e32 v8, v8, v12
	v_mul_f32_e32 v12, 0xbfb8aa3b, v13
	global_store_dwordx2 v[18:19], v[16:17], off
	v_exp_f32_e32 v12, v12
	v_mul_f32_e32 v16, 0xbfb8aa3b, v5
	v_exp_f32_e32 v16, v16
	v_mul_f32_e32 v4, v4, v21
	v_mul_f32_e32 v4, v0, v4
	v_add_f32_e32 v0, 1.0, v12
	v_rcp_f32_e32 v0, v0
	v_add_f32_e32 v12, 1.0, v16
	v_mul_f32_e32 v16, 0xbfb8aa3b, v14
	v_exp_f32_e32 v16, v16
	v_rcp_f32_e32 v12, v12
	v_mul_f32_e32 v0, v13, v0
	v_mul_f32_e32 v0, v9, v0
	v_add_f32_e32 v9, 1.0, v16
	v_mul_f32_e32 v5, v5, v12
	v_rcp_f32_e32 v9, v9
	v_mul_f32_e32 v12, 0xbfb8aa3b, v6
	v_exp_f32_e32 v12, v12
	v_mul_f32_e32 v1, v1, v5
	v_mul_f32_e32 v5, v14, v9
	v_mul_f32_e32 v5, v10, v5
	v_add_f32_e32 v9, 1.0, v12
	v_mul_f32_e32 v10, 0xbfb8aa3b, v15
	v_mul_f32_e32 v12, 0xbfb8aa3b, v7
	v_rcp_f32_e32 v9, v9
	v_exp_f32_e32 v10, v10
	v_exp_f32_e32 v12, v12
	v_med3_f32 v4, v4, s68, v151
	v_mul_f32_e32 v6, v6, v9
	v_add_f32_e32 v9, 1.0, v10
	v_add_f32_e32 v10, 1.0, v12
	v_rcp_f32_e32 v10, v10
	v_rcp_f32_e32 v9, v9
	v_mul_f32_e32 v2, v2, v6
	v_med3_f32 v5, v5, s68, v151
	v_mul_f32_e32 v7, v7, v10
	v_mul_f32_e32 v3, v3, v7
	v_med3_f32 v7, v8, s68, v151
	v_med3_f32 v8, v0, s68, v151
	v_mov_b32_e32 v0, 0
	v_cvt_pk_fp8_f32 v0, v7, v8
	v_med3_f32 v7, v1, s68, v151
	v_mov_b32_e32 v1, 0
	v_cvt_pk_fp8_f32 v1, v4, v7
	v_mul_f32_e32 v6, v15, v9
	v_mul_f32_e32 v6, v11, v6
	v_med3_f32 v6, v6, s68, v151
	v_med3_f32 v2, v2, s68, v151
	v_med3_f32 v3, v3, s68, v151
	v_cvt_pk_fp8_f32 v0, v5, v6 op_sel:[0,0,1]
	v_cvt_pk_fp8_f32 v1, v2, v3 op_sel:[0,0,1]
	v_add_co_u32_e32 v2, vcc, 0xf2000, v144
	s_nop 1
	v_addc_co_u32_e32 v3, vcc, 0, v145, vcc
	s_andn2_b64 vcc, exec, s[4:5]
	s_mov_b64 s[4:5], -1
	global_store_dwordx2 v[2:3], v[0:1], off
	s_cbranch_vccnz .LBB0_2449
	s_andn2_b64 vcc, exec, s[8:9]
	s_cbranch_vccnz .LBB0_2448
	s_mov_b32 s100, 1
	s_branch .LBB0_2448

; #define PG8_STAGE(bufoff, gbase, voff) do { _Pragma("unroll") for (int _i = 0; _i < 2; ++_i) \
;         __builtin_amdgcn_global_load_lds((const unsigned*)((const char*)(gbase) + (voff)[_i]), (LAS unsigned*)(lds + (bufoff) + ldsw + _i * 8192), 16, 0, 0); } while (0)
; #define PG8_LDA(dst, b, h) do { _Pragma("unroll") for (int m = 0; m < 4; ++m) _Pragma("unroll") for (int k = 0; k < 2; ++k) dst[m][k] = *(const LAS bf16x8*)(lds + PG8_SA(b, h) + aoff + m * 2048 + k * KOFF); } while (0)
; #define PG8_LDB(dst, b, h) do { _Pragma("unroll") for (int n = 0; n < 2; ++n) _Pragma("unroll") for (int k = 0; k < 2; ++k) dst[n][k] = *(const LAS bf16x8*)(lds + PG8_SB(b, h) + boff + n * 2048 + k * KOFF); } while (0)
; #define PG8_WAIT_V(n) asm volatile("s_waitcnt vmcnt(" #n ")" ::: "memory")
; #define PG8_WAIT_L(n) asm volatile("s_waitcnt lgkmcnt(" #n ")" ::: "memory")
; #define PG8_BAR __builtin_amdgcn_s_barrier()
; #define PG8_SCHED __builtin_amdgcn_sched_barrier(0)
; template <class Epi, bool ALIGN_EPI = true, bool FP8 = false>
; __device__ __forceinline__ void gemm_phase(LAS unsigned char* lds, const Gemm g, const StaticOrder& S, const Epi& E, const int wid) {
;     ...
;             const char* a1 = cA + (size_t)(t + 1) * kstep;
;             const char* a2 = last ? nA : cA + (size_t)(t + 2) * kstep; const char* b2 = last ? nB : cB + (size_t)(t + 2) * kstep;
;             const char* a3 = a2 + kstep; const char* b3 = b2 + kstep;
;             PG8_LDB(B0, 0, 0); PG8_LDB(B1, 0, 1); PG8_SCHED; PG8_LDA(At, 0, 0); PG8_STAGE(PG8_SA(1, 1), a1 + hstep, voffA);
;             PG8_WAIT_V(8); PG8_WAIT_L(0); PG8_BAR; PG8_MMA(0, 0, At, B0); PG8_MMA(0, 1, At, B1); PG8_BAR; PG8_SCHED;
;     ...
; #pragma unroll
;         for (int a = 0; a < 2; ++a)
; #pragma unroll
;             for (int b = 0; b < 2; ++b)
; #pragma unroll
;                 for (int m = 0; m < 4; ++m) {
;                     if (!keep) { acc[a][b][m][0] = (f32x4){0.f, 0.f, 0.f, 0.f}; acc[a][b][m][1] = (f32x4){0.f, 0.f, 0.f, 0.f}; }
;                     if constexpr (FP8) acc8[a][b][m] = __builtin_shufflevector(acc[a][b][m][0], acc[a][b][m][1], 0, 1, 2, 3, 4, 5, 6, 7); }
;         cur = nxt; cA = nA; cB = nB; ++ui;
;         if constexpr (ALIGN_EPI) { if (wr == 1) PG8_BAR; }
.LBB0_2535:
	s_add_i32 s81, s80, -2
	s_add_u32 s24, s24, 0xb0080
	s_addc_u32 s25, s25, 0
	s_add_u32 s82, s26, 0x100
	v_mov_b32_e32 v0, 0
	s_addc_u32 s83, s27, 0
	s_mov_b32 s26, 0
	v_mov_b32_e32 v1, v0
	v_mov_b32_e32 v2, v0
	v_mov_b32_e32 v3, v0
	v_mov_b32_e32 v4, v0
	v_mov_b32_e32 v5, v0
	v_mov_b32_e32 v6, v0
	v_mov_b32_e32 v7, v0
	v_mov_b32_e32 v8, v0
	v_mov_b32_e32 v9, v0
	v_mov_b32_e32 v10, v0
	v_mov_b32_e32 v11, v0
	v_mov_b32_e32 v12, v0
	v_mov_b32_e32 v13, v0
	v_mov_b32_e32 v14, v0
	v_mov_b32_e32 v15, v0
	v_mov_b32_e32 v24, v0
	v_mov_b32_e32 v25, v0
	v_mov_b32_e32 v26, v0
	v_mov_b32_e32 v27, v0
	v_mov_b32_e32 v28, v0
	v_mov_b32_e32 v29, v0
	v_mov_b32_e32 v30, v0
	v_mov_b32_e32 v31, v0
	v_mov_b32_e32 v40, v0
	v_mov_b32_e32 v41, v0
	v_mov_b32_e32 v42, v0
	v_mov_b32_e32 v43, v0
	v_mov_b32_e32 v44, v0
	v_mov_b32_e32 v45, v0
	v_mov_b32_e32 v46, v0
	v_mov_b32_e32 v47, v0
	v_mov_b32_e32 v16, v0
	v_mov_b32_e32 v17, v0
	v_mov_b32_e32 v18, v0
	v_mov_b32_e32 v19, v0
	v_mov_b32_e32 v20, v0
	v_mov_b32_e32 v21, v0
	v_mov_b32_e32 v22, v0
	v_mov_b32_e32 v23, v0
	v_mov_b32_e32 v32, v0
	s_waitcnt lgkmcnt(0)
	v_mov_b32_e32 v33, v0
	v_mov_b32_e32 v34, v0
	v_mov_b32_e32 v35, v0
	v_mov_b32_e32 v36, v0
	v_mov_b32_e32 v37, v0
	v_mov_b32_e32 v38, v0
	v_mov_b32_e32 v39, v0
	v_mov_b32_e32 v48, v0
	v_mov_b32_e32 v49, v0
	v_mov_b32_e32 v50, v0
	v_mov_b32_e32 v51, v0
	v_mov_b32_e32 v52, v0
	v_mov_b32_e32 v53, v0
	v_mov_b32_e32 v54, v0
	v_mov_b32_e32 v55, v0
	v_mov_b32_e32 v56, v0
	v_mov_b32_e32 v57, v0
	v_mov_b32_e32 v58, v0
	v_mov_b32_e32 v59, v0
	v_mov_b32_e32 v60, v0
	v_mov_b32_e32 v61, v0
	v_mov_b32_e32 v62, v0
	v_mov_b32_e32 v63, v0
	v_mov_b32_e32 v64, v0
	v_mov_b32_e32 v65, v0
	v_mov_b32_e32 v66, v0
	v_mov_b32_e32 v67, v0
	v_mov_b32_e32 v68, v0
	v_mov_b32_e32 v69, v0
	v_mov_b32_e32 v70, v0
	v_mov_b32_e32 v71, v0
	v_mov_b32_e32 v72, v0
	v_mov_b32_e32 v73, v0
	v_mov_b32_e32 v74, v0
	v_mov_b32_e32 v75, v0
	v_mov_b32_e32 v76, v0
	v_mov_b32_e32 v77, v0
	v_mov_b32_e32 v78, v0
	v_mov_b32_e32 v79, v0
	v_mov_b32_e32 v88, v0
	v_mov_b32_e32 v89, v0
	v_mov_b32_e32 v90, v0
	v_mov_b32_e32 v91, v0
	v_mov_b32_e32 v92, v0
	v_mov_b32_e32 v93, v0
	v_mov_b32_e32 v94, v0
	v_mov_b32_e32 v95, v0
	v_mov_b32_e32 v104, v0
	v_mov_b32_e32 v105, v0
	v_mov_b32_e32 v106, v0
	v_mov_b32_e32 v107, v0
	v_mov_b32_e32 v108, v0
	v_mov_b32_e32 v109, v0
	v_mov_b32_e32 v110, v0
	v_mov_b32_e32 v111, v0
	v_mov_b32_e32 v80, v0
	v_mov_b32_e32 v81, v0
	v_mov_b32_e32 v82, v0
	v_mov_b32_e32 v83, v0
	v_mov_b32_e32 v84, v0
	v_mov_b32_e32 v85, v0
	v_mov_b32_e32 v86, v0
	v_mov_b32_e32 v87, v0
	v_mov_b32_e32 v96, v0
	v_mov_b32_e32 v97, v0
	v_mov_b32_e32 v98, v0
	v_mov_b32_e32 v99, v0
	v_mov_b32_e32 v100, v0
	v_mov_b32_e32 v101, v0
	v_mov_b32_e32 v102, v0
	v_mov_b32_e32 v103, v0
	v_mov_b32_e32 v112, v0
	v_mov_b32_e32 v113, v0
	v_mov_b32_e32 v114, v0
	v_mov_b32_e32 v115, v0
	v_mov_b32_e32 v116, v0
	v_mov_b32_e32 v117, v0
	v_mov_b32_e32 v118, v0
	v_mov_b32_e32 v119, v0
	v_mov_b32_e32 v120, v0
	v_mov_b32_e32 v121, v0
	v_mov_b32_e32 v122, v0
	v_mov_b32_e32 v123, v0
	v_mov_b32_e32 v124, v0
	v_mov_b32_e32 v125, v0
	v_mov_b32_e32 v126, v0
	v_mov_b32_e32 v127, v0
	s_cmp_eq_u32 s100, 0
	s_cbranch_scc1 .Ldefbar_skip_9
	s_mov_b32 s100, 0
	s_barrier
.Ldefbar_skip_9:
.LBB0_2536:
	ds_read_b128 v[152:155], v188
	ds_read_b128 v[156:159], v188 offset:1024
	ds_read_b128 v[144:147], v188 offset:2048
	ds_read_b128 v[148:151], v188 offset:3072
	ds_read_b128 v[136:139], v189
	ds_read_b128 v[140:143], v189 offset:1024
	ds_read_b128 v[128:131], v189 offset:2048
	ds_read_b128 v[132:135], v189 offset:3072
	s_add_i32 s42, s26, 2
	s_add_u32 s27, s24, 0xfff50080
	s_addc_u32 s28, s25, -1
	s_cmp_eq_u32 s81, s26
	s_cselect_b32 s26, s20, s82
	s_cselect_b32 s29, s7, s28
	s_cselect_b32 s28, s6, s27
	s_cselect_b32 s27, s21, s83
	v_lshl_add_u64 v[216:217], s[24:25], 0, v[172:173]
	s_add_i32 m0, s34, 0xc000
	ds_read_b128 v[178:181], v190
	ds_read_b128 v[182:185], v190 offset:1024
	ds_read_b128 v[192:195], v190 offset:2048
	ds_read_b128 v[196:199], v190 offset:3072
	ds_read_b128 v[200:203], v190 offset:4096
	ds_read_b128 v[204:207], v190 offset:5120
	ds_read_b128 v[208:211], v190 offset:6144
	ds_read_b128 v[212:215], v190 offset:7168
	global_load_lds_dwordx4 v[216:217], off
	v_lshl_add_u64 v[216:217], s[24:25], 0, v[174:175]
	s_add_i32 m0, s34, 0xe000
	s_nop 0
	global_load_lds_dwordx4 v[216:217], off
	s_setprio 1
	s_waitcnt vmcnt(8) lgkmcnt(0)
	s_barrier
	v_mfma_f32_16x16x128_f8f6f4 v[120:123], v[152:159], v[178:185], v[120:123]
	v_mfma_f32_16x16x128_f8f6f4 v[124:127], v[144:151], v[178:185], v[124:127]
	v_mfma_f32_16x16x128_f8f6f4 v[112:115], v[152:159], v[192:199], v[112:115]
	v_mfma_f32_16x16x128_f8f6f4 v[116:119], v[144:151], v[192:199], v[116:119]
	v_mfma_f32_16x16x128_f8f6f4 v[96:99], v[152:159], v[200:207], v[96:99]
	v_mfma_f32_16x16x128_f8f6f4 v[100:103], v[144:151], v[200:207], v[100:103]
	v_mfma_f32_16x16x128_f8f6f4 v[80:83], v[152:159], v[208:215], v[80:83]
	v_mfma_f32_16x16x128_f8f6f4 v[84:87], v[144:151], v[208:215], v[84:87]
	v_mfma_f32_16x16x128_f8f6f4 v[104:107], v[136:143], v[178:185], v[104:107]
	v_mfma_f32_16x16x128_f8f6f4 v[108:111], v[128:135], v[178:185], v[108:111]
	v_mfma_f32_16x16x128_f8f6f4 v[88:91], v[136:143], v[192:199], v[88:91]
	v_mfma_f32_16x16x128_f8f6f4 v[92:95], v[128:135], v[192:199], v[92:95]
	v_mfma_f32_16x16x128_f8f6f4 v[72:75], v[136:143], v[200:207], v[72:75]
	v_mfma_f32_16x16x128_f8f6f4 v[76:79], v[128:135], v[200:207], v[76:79]
	v_mfma_f32_16x16x128_f8f6f4 v[64:67], v[136:143], v[208:215], v[64:67]
	v_mfma_f32_16x16x128_f8f6f4 v[68:71], v[128:135], v[208:215], v[68:71]
	s_barrier
; #define PG8_STAGE(bufoff, gbase, voff) do { _Pragma("unroll") for (int _i = 0; _i < 2; ++_i) \
;         __builtin_amdgcn_global_load_lds((const unsigned*)((const char*)(gbase) + (voff)[_i]), (LAS unsigned*)(lds + (bufoff) + ldsw + _i * 8192), 16, 0, 0); } while (0)
; #define PG8_LDA(dst, b, h) do { _Pragma("unroll") for (int m = 0; m < 4; ++m) _Pragma("unroll") for (int k = 0; k < 2; ++k) dst[m][k] = *(const LAS bf16x8*)(lds + PG8_SA(b, h) + aoff + m * 2048 + k * KOFF); } while (0)
; #define PG8_LDB(dst, b, h) do { _Pragma("unroll") for (int n = 0; n < 2; ++n) _Pragma("unroll") for (int k = 0; k < 2; ++k) dst[n][k] = *(const LAS bf16x8*)(lds + PG8_SB(b, h) + boff + n * 2048 + k * KOFF); } while (0)
; #define PG8_WAIT_V(n) asm volatile("s_waitcnt vmcnt(" #n ")" ::: "memory")
; #define PG8_WAIT_L(n) asm volatile("s_waitcnt lgkmcnt(" #n ")" ::: "memory")
; #define PG8_BAR __builtin_amdgcn_s_barrier()
; #define PG8_SCHED __builtin_amdgcn_sched_barrier(0)
; template <class Epi, bool ALIGN_EPI = true, bool FP8 = false>
; __device__ __forceinline__ void gemm_phase(LAS unsigned char* lds, const Gemm g, const StaticOrder& S, const Epi& E, const int wid) {
;     ...
;             PG8_WAIT_V(8); PG8_WAIT_L(0); PG8_BAR; PG8_MMA(0, 0, At, B0); PG8_MMA(0, 1, At, B1); PG8_BAR; PG8_SCHED;
;             PG8_LDA(At, 0, 1); PG8_STAGE(PG8_SB(0, 0), b2, voffB); PG8_STAGE(PG8_SB(0, 1), b2 + hstep, voffB); PG8_STAGE(PG8_SA(0, 0), a2, voffA);
;             PG8_WAIT_V(8); PG8_WAIT_L(0); PG8_BAR; PG8_MMA(1, 0, At, B0); PG8_MMA(1, 1, At, B1); PG8_BAR; PG8_SCHED;
;             PG8_LDB(B0, 1, 0); PG8_LDB(B1, 1, 1); PG8_SCHED; PG8_LDA(At, 1, 0); PG8_STAGE(PG8_SA(0, 1), a2 + hstep, voffA);
;             PG8_WAIT_V(8); PG8_WAIT_L(0); PG8_BAR; PG8_MMA(0, 0, At, B0); PG8_MMA(0, 1, At, B1); PG8_BAR; PG8_SCHED;
	s_setprio 0
	s_add_i32 s43, s64, s31
	v_lshl_add_u64 v[178:179], s[26:27], 0, v[162:163]
	s_mov_b32 m0, s43
	ds_read_b128 v[192:195], v190 offset:16384
	ds_read_b128 v[196:199], v190 offset:17408
	ds_read_b128 v[200:203], v190 offset:18432
	ds_read_b128 v[204:207], v190 offset:19456
	ds_read_b128 v[208:211], v190 offset:20480
	ds_read_b128 v[212:215], v190 offset:21504
	ds_read_b128 v[216:219], v190 offset:22528
	ds_read_b128 v[220:223], v190 offset:23552
	global_load_lds_dwordx4 v[178:179], off
	s_add_i32 m0, s43, 0x2000
	s_add_u32 s84, s26, 0xb0000
	v_lshl_add_u64 v[180:181], s[26:27], 0, v[166:167]
	s_addc_u32 s85, s27, 0
	s_add_i32 s43, s65, s31
	global_load_lds_dwordx4 v[180:181], off
	v_lshl_add_u64 v[182:183], s[84:85], 0, v[162:163]
	s_mov_b32 m0, s43
	v_lshl_add_u64 v[184:185], s[28:29], 0, v[164:165]
	global_load_lds_dwordx4 v[182:183], off
	v_lshl_add_u64 v[182:183], s[84:85], 0, v[166:167]
	s_add_i32 m0, s43, 0x2000
	s_nop 0
	global_load_lds_dwordx4 v[182:183], off
	v_lshl_add_u64 v[182:183], s[28:29], 0, v[160:161]
	s_mov_b32 m0, s34
	s_nop 0
	global_load_lds_dwordx4 v[182:183], off
	s_mov_b32 m0, s35
	s_nop 0
	global_load_lds_dwordx4 v[184:185], off
	s_setprio 1
	s_waitcnt vmcnt(8) lgkmcnt(0)
	s_barrier
	v_mfma_f32_16x16x128_f8f6f4 v[56:59], v[152:159], v[192:199], v[56:59]
	v_mfma_f32_16x16x128_f8f6f4 v[60:63], v[144:151], v[192:199], v[60:63]
	v_mfma_f32_16x16x128_f8f6f4 v[48:51], v[152:159], v[200:207], v[48:51]
	v_mfma_f32_16x16x128_f8f6f4 v[52:55], v[144:151], v[200:207], v[52:55]
	v_mfma_f32_16x16x128_f8f6f4 v[32:35], v[152:159], v[208:215], v[32:35]
	v_mfma_f32_16x16x128_f8f6f4 v[224:227], v[144:151], v[208:215], v[36:39]
	v_mfma_f32_16x16x128_f8f6f4 v[228:231], v[152:159], v[216:223], v[16:19]
	v_mfma_f32_16x16x128_f8f6f4 v[232:235], v[144:151], v[216:223], v[20:23]
	v_mfma_f32_16x16x128_f8f6f4 v[44:47], v[128:135], v[192:199], v[44:47]
	v_mfma_f32_16x16x128_f8f6f4 v[236:239], v[136:143], v[192:199], v[40:43]
	v_mfma_f32_16x16x128_f8f6f4 v[240:243], v[136:143], v[200:207], v[24:27]
	v_mfma_f32_16x16x128_f8f6f4 v[200:203], v[128:135], v[200:207], v[28:31]
	v_mfma_f32_16x16x128_f8f6f4 v[204:207], v[136:143], v[208:215], v[8:11]
	v_mfma_f32_16x16x128_f8f6f4 v[208:211], v[128:135], v[208:215], v[12:15]
	v_mfma_f32_16x16x128_f8f6f4 v[212:215], v[136:143], v[216:223], v[0:3]
	v_mfma_f32_16x16x128_f8f6f4 v[216:219], v[128:135], v[216:223], v[4:7]
	s_barrier
	s_setprio 0
	s_add_i32 s43, 0, 0x18000
	s_add_i32 s54, 0, 0x1c000
	s_nop 0
	v_add_u32_e32 v12, s43, v187
	v_add_u32_e32 v16, s54, v187
	ds_read_b128 v[0:3], v12
	ds_read_b128 v[4:7], v12 offset:1024
	ds_read_b128 v[8:11], v12 offset:2048
	ds_read_b128 v[12:15], v12 offset:3072
	ds_read_b128 v[128:131], v16
	ds_read_b128 v[132:135], v16 offset:1024
	ds_read_b128 v[136:139], v16 offset:2048
	ds_read_b128 v[140:143], v16 offset:3072
	s_add_u32 s28, s28, 0xb0000
	s_addc_u32 s29, s29, 0
	s_mov_b32 m0, s36
	v_lshl_add_u64 v[152:153], s[28:29], 0, v[160:161]
	ds_read_b128 v[16:19], v190 offset:32768
	ds_read_b128 v[20:23], v190 offset:33792
	ds_read_b128 v[24:27], v190 offset:34816
	ds_read_b128 v[28:31], v190 offset:35840
	ds_read_b128 v[36:39], v190 offset:36864
	ds_read_b128 v[40:43], v190 offset:37888
	ds_read_b128 v[144:147], v190 offset:38912
	ds_read_b128 v[148:151], v190 offset:39936
	global_load_lds_dwordx4 v[152:153], off
	v_lshl_add_u64 v[152:153], s[28:29], 0, v[164:165]
	s_mov_b32 m0, s37
	s_nop 0
	global_load_lds_dwordx4 v[152:153], off
	s_setprio 1
	s_waitcnt vmcnt(8) lgkmcnt(0)
	s_barrier
; #define PG8_STAGE(bufoff, gbase, voff) do { _Pragma("unroll") for (int _i = 0; _i < 2; ++_i) \
;         __builtin_amdgcn_global_load_lds((const unsigned*)((const char*)(gbase) + (voff)[_i]), (LAS unsigned*)(lds + (bufoff) + ldsw + _i * 8192), 16, 0, 0); } while (0)
; #define PG8_LDA(dst, b, h) do { _Pragma("unroll") for (int m = 0; m < 4; ++m) _Pragma("unroll") for (int k = 0; k < 2; ++k) dst[m][k] = *(const LAS bf16x8*)(lds + PG8_SA(b, h) + aoff + m * 2048 + k * KOFF); } while (0)
; #define PG8_LDB(dst, b, h) do { _Pragma("unroll") for (int n = 0; n < 2; ++n) _Pragma("unroll") for (int k = 0; k < 2; ++k) dst[n][k] = *(const LAS bf16x8*)(lds + PG8_SB(b, h) + boff + n * 2048 + k * KOFF); } while (0)
; #define PG8_WAIT_V(n) asm volatile("s_waitcnt vmcnt(" #n ")" ::: "memory")
; #define PG8_WAIT_L(n) asm volatile("s_waitcnt lgkmcnt(" #n ")" ::: "memory")
; #define PG8_BAR __builtin_amdgcn_s_barrier()
; #define PG8_SCHED __builtin_amdgcn_sched_barrier(0)
; template <class Epi, bool ALIGN_EPI = true, bool FP8 = false>
; __device__ __forceinline__ void gemm_phase(LAS unsigned char* lds, const Gemm g, const StaticOrder& S, const Epi& E, const int wid) {
;     ...
;             PG8_LDB(B0, 0, 0); PG8_LDB(B1, 0, 1); PG8_SCHED; PG8_LDA(At, 0, 0); PG8_STAGE(PG8_SA(1, 1), a1 + hstep, voffA);
;             PG8_WAIT_V(8); PG8_WAIT_L(0); PG8_BAR; PG8_MMA(0, 0, At, B0); PG8_MMA(0, 1, At, B1); PG8_BAR; PG8_SCHED;
;             PG8_LDA(At, 0, 1); PG8_STAGE(PG8_SB(0, 0), b2, voffB); PG8_STAGE(PG8_SB(0, 1), b2 + hstep, voffB); PG8_STAGE(PG8_SA(0, 0), a2, voffA);
;             PG8_WAIT_V(8); PG8_WAIT_L(0); PG8_BAR; PG8_MMA(1, 0, At, B0); PG8_MMA(1, 1, At, B1); PG8_BAR; PG8_SCHED;
;             PG8_LDB(B0, 1, 0); PG8_LDB(B1, 1, 1); PG8_SCHED; PG8_LDA(At, 1, 0); PG8_STAGE(PG8_SA(0, 1), a2 + hstep, voffA);
;             PG8_WAIT_V(8); PG8_WAIT_L(0); PG8_BAR; PG8_MMA(0, 0, At, B0); PG8_MMA(0, 1, At, B1); PG8_BAR; PG8_SCHED;
;             PG8_LDA(At, 1, 1); PG8_STAGE(PG8_SB(1, 0), b3, voffB); PG8_STAGE(PG8_SB(1, 1), b3 + hstep, voffB); PG8_STAGE(PG8_SA(1, 0), a3, voffA);
;             PG8_WAIT_V(8); PG8_WAIT_L(0); PG8_BAR; PG8_MMA(1, 0, At, B0); PG8_MMA(1, 1, At, B1); PG8_BAR; PG8_SCHED;
;         }
;         if constexpr (ALIGN_EPI) { if (wr == 0) PG8_BAR; }
	v_mfma_f32_16x16x128_f8f6f4 v[120:123], v[0:7], v[16:23], v[120:123]
	v_mfma_f32_16x16x128_f8f6f4 v[124:127], v[8:15], v[16:23], v[124:127]
	v_mfma_f32_16x16x128_f8f6f4 v[112:115], v[0:7], v[24:31], v[112:115]
	v_mfma_f32_16x16x128_f8f6f4 v[116:119], v[8:15], v[24:31], v[116:119]
	v_mfma_f32_16x16x128_f8f6f4 v[96:99], v[0:7], v[36:43], v[96:99]
	v_mfma_f32_16x16x128_f8f6f4 v[100:103], v[8:15], v[36:43], v[100:103]
	v_mfma_f32_16x16x128_f8f6f4 v[80:83], v[0:7], v[144:151], v[80:83]
	v_mfma_f32_16x16x128_f8f6f4 v[84:87], v[8:15], v[144:151], v[84:87]
	v_mfma_f32_16x16x128_f8f6f4 v[104:107], v[128:135], v[16:23], v[104:107]
	v_mfma_f32_16x16x128_f8f6f4 v[108:111], v[136:143], v[16:23], v[108:111]
	v_mfma_f32_16x16x128_f8f6f4 v[88:91], v[128:135], v[24:31], v[88:91]
	v_mfma_f32_16x16x128_f8f6f4 v[92:95], v[136:143], v[24:31], v[92:95]
	v_mfma_f32_16x16x128_f8f6f4 v[72:75], v[128:135], v[36:43], v[72:75]
	v_mfma_f32_16x16x128_f8f6f4 v[76:79], v[136:143], v[36:43], v[76:79]
	v_mfma_f32_16x16x128_f8f6f4 v[64:67], v[128:135], v[144:151], v[64:67]
	v_mfma_f32_16x16x128_f8f6f4 v[68:71], v[136:143], v[144:151], v[68:71]
	s_barrier
	s_setprio 0
	s_add_i32 s28, s43, s31
	v_lshl_add_u64 v[16:17], v[178:179], 0, s[14:15]
	s_mov_b32 m0, s28
	ds_read_b128 v[24:27], v190 offset:49152
	ds_read_b128 v[28:31], v190 offset:50176
	ds_read_b128 v[144:147], v190 offset:51200
	ds_read_b128 v[148:151], v190 offset:52224
	ds_read_b128 v[152:155], v190 offset:53248
	ds_read_b128 v[156:159], v190 offset:54272
	ds_read_b128 v[192:195], v190 offset:55296
	ds_read_b128 v[196:199], v190 offset:56320
	global_load_lds_dwordx4 v[16:17], off
	s_add_i32 m0, s28, 0x2000
	s_add_u32 s26, s26, 0xb0080
	v_lshl_add_u64 v[16:17], v[180:181], 0, s[14:15]
	s_addc_u32 s27, s27, 0
	s_add_i32 s28, s54, s31
	global_load_lds_dwordx4 v[16:17], off
	v_lshl_add_u64 v[16:17], s[26:27], 0, v[162:163]
	s_mov_b32 m0, s28
	s_nop 0
	global_load_lds_dwordx4 v[16:17], off
	v_lshl_add_u64 v[16:17], s[26:27], 0, v[166:167]
	s_add_i32 m0, s28, 0x2000
	s_nop 0
	global_load_lds_dwordx4 v[16:17], off
	v_lshl_add_u64 v[16:17], v[182:183], 0, s[14:15]
	s_mov_b32 m0, s52
	s_nop 0
	global_load_lds_dwordx4 v[16:17], off
	v_lshl_add_u64 v[16:17], v[184:185], 0, s[14:15]
	s_mov_b32 m0, s53
	s_nop 0
	global_load_lds_dwordx4 v[16:17], off
	s_setprio 1
	s_waitcnt vmcnt(8) lgkmcnt(0)
	s_barrier
	v_mfma_f32_16x16x128_f8f6f4 v[56:59], v[0:7], v[24:31], v[56:59]
	v_mfma_f32_16x16x128_f8f6f4 v[60:63], v[8:15], v[24:31], v[60:63]
	v_mfma_f32_16x16x128_f8f6f4 v[48:51], v[0:7], v[144:151], v[48:51]
	v_mfma_f32_16x16x128_f8f6f4 v[52:55], v[8:15], v[144:151], v[52:55]
	v_mfma_f32_16x16x128_f8f6f4 v[32:35], v[0:7], v[152:159], v[32:35]
	v_mfma_f32_16x16x128_f8f6f4 v[36:39], v[8:15], v[152:159], v[224:227]
	v_mfma_f32_16x16x128_f8f6f4 v[16:19], v[0:7], v[192:199], v[228:231]
	v_mfma_f32_16x16x128_f8f6f4 v[20:23], v[8:15], v[192:199], v[232:235]
	v_mfma_f32_16x16x128_f8f6f4 v[40:43], v[128:135], v[24:31], v[236:239]
	v_mfma_f32_16x16x128_f8f6f4 v[44:47], v[136:143], v[24:31], v[44:47]
	v_mfma_f32_16x16x128_f8f6f4 v[24:27], v[128:135], v[144:151], v[240:243]
	v_mfma_f32_16x16x128_f8f6f4 v[28:31], v[136:143], v[144:151], v[200:203]
	v_mfma_f32_16x16x128_f8f6f4 v[8:11], v[128:135], v[152:159], v[204:207]
	v_mfma_f32_16x16x128_f8f6f4 v[12:15], v[136:143], v[152:159], v[208:211]
	v_mfma_f32_16x16x128_f8f6f4 v[0:3], v[128:135], v[192:199], v[212:215]
	v_mfma_f32_16x16x128_f8f6f4 v[4:7], v[136:143], v[192:199], v[216:219]
	s_barrier
	s_setprio 0
	s_add_u32 s24, s24, 0x100
	s_addc_u32 s25, s25, 0
	s_add_u32 s82, s82, 0x100
	s_addc_u32 s83, s83, 0
	s_cmp_ge_u32 s42, s80
	s_mov_b32 s26, s42
	s_cbranch_scc0 .LBB0_2536
	s_and_b64 vcc, exec, s[16:17]
	s_cbranch_vccz .LBB0_2539
	s_barrier

; #define PG8_BAR __builtin_amdgcn_s_barrier()
; template <class Epi, bool ALIGN_EPI = true, bool FP8 = false>
; __device__ __forceinline__ void gemm_phase(LAS unsigned char* lds, const Gemm g, const StaticOrder& S, const Epi& E, const int wid) {
;     ...
;         if (!has_next) break;
; #pragma unroll
;         for (int a = 0; a < 2; ++a)
; #pragma unroll
;             for (int b = 0; b < 2; ++b)
; #pragma unroll
;                 for (int m = 0; m < 4; ++m) {
;                     if (!keep) { acc[a][b][m][0] = (f32x4){0.f, 0.f, 0.f, 0.f}; acc[a][b][m][1] = (f32x4){0.f, 0.f, 0.f, 0.f}; }
;                     if constexpr (FP8) acc8[a][b][m] = __builtin_shufflevector(acc[a][b][m][0], acc[a][b][m][1], 0, 1, 2, 3, 4, 5, 6, 7); }
;         cur = nxt; cA = nA; cB = nB; ++ui;
;         if constexpr (ALIGN_EPI) { if (wr == 1) PG8_BAR; }
.LBB0_2542:
	s_and_b64 vcc, exec, s[4:5]
	s_mov_b64 s[4:5], -1
	s_cbranch_vccnz .LBB0_2526
	s_andn2_b64 vcc, exec, s[12:13]
	s_cbranch_vccnz .LBB0_2525
	s_mov_b32 s100, 1
	s_branch .LBB0_2525

; __global__ void __launch_bounds__(NTHREADS, 2) fwd_kernel(Args args) {
	.amdhsa_kernel _Z10fwd_kernel4Args
		.amdhsa_group_segment_fixed_size 0
		.amdhsa_private_segment_fixed_size 0
		.amdhsa_kernarg_size 464
		.amdhsa_user_sgpr_count 2
		.amdhsa_user_sgpr_dispatch_ptr 0
		.amdhsa_user_sgpr_queue_ptr 0
		.amdhsa_user_sgpr_kernarg_segment_ptr 1
		.amdhsa_user_sgpr_dispatch_id 0
		.amdhsa_user_sgpr_kernarg_preload_length 0
		.amdhsa_user_sgpr_kernarg_preload_offset 0
		.amdhsa_user_sgpr_private_segment_size 0
		.amdhsa_uses_dynamic_stack 0
		.amdhsa_enable_private_segment 0
		.amdhsa_system_sgpr_workgroup_id_x 1
		.amdhsa_system_sgpr_workgroup_id_y 0
		.amdhsa_system_sgpr_workgroup_id_z 0
		.amdhsa_system_sgpr_workgroup_info 0
		.amdhsa_system_vgpr_workitem_id 0
		.amdhsa_next_free_vgpr 256
		.amdhsa_next_free_sgpr 101
		.amdhsa_accum_offset 256
		.amdhsa_reserve_vcc 1
		.amdhsa_float_round_mode_32 0
		.amdhsa_float_round_mode_16_64 0
		.amdhsa_float_denorm_mode_32 3
		.amdhsa_float_denorm_mode_16_64 3
		.amdhsa_dx10_clamp 1
		.amdhsa_ieee_mode 1
		.amdhsa_fp16_overflow 0
		.amdhsa_tg_split 0
		.amdhsa_exception_fp_ieee_invalid_op 0
		.amdhsa_exception_fp_denorm_src 0
		.amdhsa_exception_fp_ieee_div_zero 0
		.amdhsa_exception_fp_ieee_overflow 0
		.amdhsa_exception_fp_ieee_underflow 0
		.amdhsa_exception_fp_ieee_inexact 0
		.amdhsa_exception_int_div_zero 0
	.end_amdhsa_kernel

; __global__ void __launch_bounds__(NTHREADS, 2) fwd_kernel(Args args) {
amdhsa.kernels:
  - .agpr_count:     0
    .args:
      - .offset:         0
        .size:           208
        .value_kind:     by_value
      - .offset:         208
        .size:           4
        .value_kind:     hidden_block_count_x
      - .offset:         212
        .size:           4
        .value_kind:     hidden_block_count_y
      - .offset:         216
        .size:           4
        .value_kind:     hidden_block_count_z
      - .offset:         220
        .size:           2
        .value_kind:     hidden_group_size_x
      - .offset:         222
        .size:           2
        .value_kind:     hidden_group_size_y
      - .offset:         224
        .size:           2
        .value_kind:     hidden_group_size_z
      - .offset:         226
        .size:           2
        .value_kind:     hidden_remainder_x
      - .offset:         228
        .size:           2
        .value_kind:     hidden_remainder_y
      - .offset:         230
        .size:           2
        .value_kind:     hidden_remainder_z
      - .offset:         248
        .size:           8
        .value_kind:     hidden_global_offset_x
      - .offset:         256
        .size:           8
        .value_kind:     hidden_global_offset_y
      - .offset:         264
        .size:           8
        .value_kind:     hidden_global_offset_z
      - .offset:         272
        .size:           2
        .value_kind:     hidden_grid_dims
      - .offset:         328
        .size:           4
        .value_kind:     hidden_dynamic_lds_size
    .group_segment_fixed_size: 0
    .kernarg_segment_align: 8
    .kernarg_segment_size: 464
    .language:       OpenCL C
    .language_version:
      - 2
      - 0
    .max_flat_workgroup_size: 512
    .name:           _Z10fwd_kernel4Args
    .private_segment_fixed_size: 0
    .sgpr_count:     107
    .sgpr_spill_count: 25
    .symbol:         _Z10fwd_kernel4Args.kd
    .uniform_work_group_size: 1
    .uses_dynamic_stack: false
    .vgpr_count:     256
    .vgpr_spill_count: 0
    .wavefront_size: 64
